# K-loop MFMA issue order: the two k-half MFMAs of each accumulator tile issued back to back (accumulator forwarding)
# speedup vs baseline: 1.0106x; 1.0106x over previous
.LBB0_140:
	s_ashr_i32 s37, s36, 31
	s_lshl_b64 s[42:43], s[36:37], 19
	s_add_u32 s42, s62, s42
	s_addc_u32 s43, s63, s43
	s_and_b64 s[44:45], s[0:1], exec
	s_cselect_b32 s37, s43, s49
	s_cselect_b32 s77, s42, s48
	s_ashr_i32 s39, s38, 31
	s_lshl_b64 s[44:45], s[38:39], 19
	s_add_u32 s44, s54, s44
	s_addc_u32 s45, s55, s45
	s_and_b64 s[52:53], s[0:1], exec
	s_cselect_b32 s39, s45, s51
	s_cselect_b32 s78, s44, s50
	s_add_u32 s48, s48, 0x40080
	s_addc_u32 s49, s49, 0
	s_add_u32 s79, s50, 0x100
	s_addc_u32 s80, s51, 0
	s_mov_b32 s81, -2
	ds_read_b128 v[150:153], v147
	ds_read_b128 v[154:157], v147 offset:1024
	ds_read_b128 v[158:161], v147 offset:2048
	ds_read_b128 v[162:165], v147 offset:3072
	ds_read_b128 v[166:169], v148
	ds_read_b128 v[170:173], v148 offset:1024
	ds_read_b128 v[174:177], v148 offset:2048
	ds_read_b128 v[178:181], v148 offset:3072
	s_add_u32 s50, s48, 0xfffc0080
	s_addc_u32 s51, s49, -1
	s_cmp_eq_u32 s81, 12
	s_cselect_b32 s53, s37, s51
	s_cselect_b32 s52, s77, s50
	s_cselect_b32 s51, s39, s80
	s_cselect_b32 s50, s78, s79
	v_lshl_add_u64 v[214:215], s[48:49], 0, v[136:137]
	s_add_i32 m0, s47, 0xc000
	ds_read_b128 v[182:185], v149
	ds_read_b128 v[186:189], v149 offset:1024
	ds_read_b128 v[190:193], v149 offset:2048
	ds_read_b128 v[194:197], v149 offset:3072
	ds_read_b128 v[198:201], v149 offset:4096
	ds_read_b128 v[202:205], v149 offset:5120
	ds_read_b128 v[206:209], v149 offset:6144
	ds_read_b128 v[210:213], v149 offset:7168
	global_load_lds_dwordx4 v[214:215], off
	v_lshl_add_u64 v[214:215], s[48:49], 0, v[138:139]
	s_add_i32 m0, s47, 0xe000
	s_nop 0
	global_load_lds_dwordx4 v[214:215], off
	s_waitcnt vmcnt(8)
	s_waitcnt lgkmcnt(0)
	s_setprio 1
	s_barrier
	v_mfma_f32_16x16x32_bf16 v[124:127], v[150:153], v[182:185], 0
	v_mfma_f32_16x16x32_bf16 v[124:127], v[154:157], v[186:189], v[124:127]
	v_mfma_f32_16x16x32_bf16 v[116:119], v[158:161], v[182:185], 0
	v_mfma_f32_16x16x32_bf16 v[116:119], v[162:165], v[186:189], v[116:119]
	v_mfma_f32_16x16x32_bf16 v[108:111], v[150:153], v[190:193], 0
	v_mfma_f32_16x16x32_bf16 v[108:111], v[154:157], v[194:197], v[108:111]
	v_mfma_f32_16x16x32_bf16 v[100:103], v[158:161], v[190:193], 0
	v_mfma_f32_16x16x32_bf16 v[100:103], v[162:165], v[194:197], v[100:103]
	v_mfma_f32_16x16x32_bf16 v[92:95], v[150:153], v[198:201], 0
	v_mfma_f32_16x16x32_bf16 v[92:95], v[154:157], v[202:205], v[92:95]
	v_mfma_f32_16x16x32_bf16 v[84:87], v[158:161], v[198:201], 0
	v_mfma_f32_16x16x32_bf16 v[84:87], v[162:165], v[202:205], v[84:87]
	v_mfma_f32_16x16x32_bf16 v[76:79], v[150:153], v[206:209], 0
	v_mfma_f32_16x16x32_bf16 v[76:79], v[154:157], v[210:213], v[76:79]
	v_mfma_f32_16x16x32_bf16 v[68:71], v[158:161], v[206:209], 0
	v_mfma_f32_16x16x32_bf16 v[68:71], v[162:165], v[210:213], v[68:71]
	v_mfma_f32_16x16x32_bf16 v[120:123], v[166:169], v[182:185], 0
	v_mfma_f32_16x16x32_bf16 v[120:123], v[170:173], v[186:189], v[120:123]
	v_mfma_f32_16x16x32_bf16 v[112:115], v[174:177], v[182:185], 0
	v_mfma_f32_16x16x32_bf16 v[112:115], v[178:181], v[186:189], v[112:115]
	v_mfma_f32_16x16x32_bf16 v[104:107], v[166:169], v[190:193], 0
	v_mfma_f32_16x16x32_bf16 v[104:107], v[170:173], v[194:197], v[104:107]
	v_mfma_f32_16x16x32_bf16 v[96:99], v[174:177], v[190:193], 0
	v_mfma_f32_16x16x32_bf16 v[96:99], v[178:181], v[194:197], v[96:99]
	v_mfma_f32_16x16x32_bf16 v[88:91], v[166:169], v[198:201], 0
	v_mfma_f32_16x16x32_bf16 v[88:91], v[170:173], v[202:205], v[88:91]
	v_mfma_f32_16x16x32_bf16 v[80:83], v[174:177], v[198:201], 0
	v_mfma_f32_16x16x32_bf16 v[80:83], v[178:181], v[202:205], v[80:83]
	v_mfma_f32_16x16x32_bf16 v[72:75], v[166:169], v[206:209], 0
	v_mfma_f32_16x16x32_bf16 v[72:75], v[170:173], v[210:213], v[72:75]
	v_mfma_f32_16x16x32_bf16 v[64:67], v[174:177], v[206:209], 0
	v_mfma_f32_16x16x32_bf16 v[64:67], v[178:181], v[210:213], v[64:67]
	s_barrier
	s_setprio 0
	s_add_i32 s82, s73, s56
	v_lshl_add_u64 v[214:215], s[50:51], 0, v[132:133]
	s_mov_b32 m0, s82
	ds_read_b128 v[182:185], v149 offset:16384
	ds_read_b128 v[186:189], v149 offset:17408
	ds_read_b128 v[190:193], v149 offset:18432
	ds_read_b128 v[194:197], v149 offset:19456
	ds_read_b128 v[198:201], v149 offset:20480
	ds_read_b128 v[202:205], v149 offset:21504
	ds_read_b128 v[206:209], v149 offset:22528
	ds_read_b128 v[210:213], v149 offset:23552
	global_load_lds_dwordx4 v[214:215], off
	s_add_i32 m0, s82, 0x2000
	s_add_u32 s88, s50, 0x40000
	v_lshl_add_u64 v[216:217], s[50:51], 0, v[128:129]
	s_addc_u32 s89, s51, 0
	s_add_i32 s82, s74, s56
	global_load_lds_dwordx4 v[216:217], off
	v_lshl_add_u64 v[218:219], s[88:89], 0, v[132:133]
	s_mov_b32 m0, s82
	v_lshl_add_u64 v[220:221], s[52:53], 0, v[130:131]
	global_load_lds_dwordx4 v[218:219], off
	v_lshl_add_u64 v[218:219], s[88:89], 0, v[128:129]
	s_add_i32 m0, s82, 0x2000
	s_nop 0
	global_load_lds_dwordx4 v[218:219], off
	v_lshl_add_u64 v[218:219], s[52:53], 0, v[134:135]
	s_mov_b32 m0, s47
	s_nop 0
	global_load_lds_dwordx4 v[218:219], off
	s_mov_b32 m0, s59
	s_nop 0
	global_load_lds_dwordx4 v[220:221], off
	s_waitcnt vmcnt(8)
	s_waitcnt lgkmcnt(0)
	s_setprio 1
	s_barrier
	v_mfma_f32_16x16x32_bf16 v[60:63], v[150:153], v[182:185], 0
	v_mfma_f32_16x16x32_bf16 v[60:63], v[154:157], v[186:189], v[60:63]
	v_mfma_f32_16x16x32_bf16 v[52:55], v[158:161], v[182:185], 0
	v_mfma_f32_16x16x32_bf16 v[52:55], v[162:165], v[186:189], v[52:55]
	v_mfma_f32_16x16x32_bf16 v[44:47], v[150:153], v[190:193], 0
	v_mfma_f32_16x16x32_bf16 v[44:47], v[154:157], v[194:197], v[44:47]
	v_mfma_f32_16x16x32_bf16 v[36:39], v[158:161], v[190:193], 0
	v_mfma_f32_16x16x32_bf16 v[36:39], v[162:165], v[194:197], v[36:39]
	v_mfma_f32_16x16x32_bf16 v[28:31], v[150:153], v[198:201], 0
	v_mfma_f32_16x16x32_bf16 v[28:31], v[154:157], v[202:205], v[28:31]
	v_mfma_f32_16x16x32_bf16 v[20:23], v[158:161], v[198:201], 0
	v_mfma_f32_16x16x32_bf16 v[20:23], v[162:165], v[202:205], v[20:23]
	v_mfma_f32_16x16x32_bf16 v[12:15], v[150:153], v[206:209], 0
	v_mfma_f32_16x16x32_bf16 v[12:15], v[154:157], v[210:213], v[12:15]
	v_mfma_f32_16x16x32_bf16 v[4:7], v[158:161], v[206:209], 0
	v_mfma_f32_16x16x32_bf16 v[4:7], v[162:165], v[210:213], v[4:7]
	v_mfma_f32_16x16x32_bf16 v[56:59], v[166:169], v[182:185], 0
	v_mfma_f32_16x16x32_bf16 v[56:59], v[170:173], v[186:189], v[56:59]
	v_mfma_f32_16x16x32_bf16 v[48:51], v[174:177], v[182:185], 0
	v_mfma_f32_16x16x32_bf16 v[48:51], v[178:181], v[186:189], v[48:51]
	v_mfma_f32_16x16x32_bf16 v[40:43], v[166:169], v[190:193], 0
	v_mfma_f32_16x16x32_bf16 v[40:43], v[170:173], v[194:197], v[40:43]
	v_mfma_f32_16x16x32_bf16 v[32:35], v[174:177], v[190:193], 0
	v_mfma_f32_16x16x32_bf16 v[32:35], v[178:181], v[194:197], v[32:35]
	v_mfma_f32_16x16x32_bf16 v[24:27], v[166:169], v[198:201], 0
	v_mfma_f32_16x16x32_bf16 v[24:27], v[170:173], v[202:205], v[24:27]
	v_mfma_f32_16x16x32_bf16 v[16:19], v[174:177], v[198:201], 0
	v_mfma_f32_16x16x32_bf16 v[16:19], v[178:181], v[202:205], v[16:19]
	v_mfma_f32_16x16x32_bf16 v[8:11], v[166:169], v[206:209], 0
	v_mfma_f32_16x16x32_bf16 v[8:11], v[170:173], v[210:213], v[8:11]
	v_mfma_f32_16x16x32_bf16 v[0:3], v[174:177], v[206:209], 0
	v_mfma_f32_16x16x32_bf16 v[0:3], v[178:181], v[210:213], v[0:3]
	s_barrier
	s_setprio 0
	s_add_i32 s82, 0, 0x18000
	s_add_i32 s85, 0, 0x1c000
	v_add_u32_e32 v162, s82, v145
	v_add_u32_e32 v178, s85, v145
	ds_read_b128 v[150:153], v162
	ds_read_b128 v[154:157], v162 offset:1024
	ds_read_b128 v[158:161], v162 offset:2048
	ds_read_b128 v[162:165], v162 offset:3072
	ds_read_b128 v[166:169], v178
	ds_read_b128 v[170:173], v178 offset:1024
	ds_read_b128 v[174:177], v178 offset:2048
	ds_read_b128 v[178:181], v178 offset:3072
	s_add_u32 s52, s52, 0x40000
	s_addc_u32 s53, s53, 0
	s_mov_b32 m0, s66
	v_lshl_add_u64 v[222:223], s[52:53], 0, v[134:135]
	ds_read_b128 v[182:185], v149 offset:32768
	ds_read_b128 v[186:189], v149 offset:33792
	ds_read_b128 v[190:193], v149 offset:34816
	ds_read_b128 v[194:197], v149 offset:35840
	ds_read_b128 v[198:201], v149 offset:36864
	ds_read_b128 v[202:205], v149 offset:37888
	ds_read_b128 v[206:209], v149 offset:38912
	ds_read_b128 v[210:213], v149 offset:39936
	global_load_lds_dwordx4 v[222:223], off
	v_lshl_add_u64 v[222:223], s[52:53], 0, v[130:131]
	s_mov_b32 m0, s67
	s_nop 0
	global_load_lds_dwordx4 v[222:223], off
	s_waitcnt vmcnt(8)
	s_waitcnt lgkmcnt(0)
	s_setprio 1
	s_barrier
	v_mfma_f32_16x16x32_bf16 v[124:127], v[150:153], v[182:185], v[124:127]
	v_mfma_f32_16x16x32_bf16 v[124:127], v[154:157], v[186:189], v[124:127]
	v_mfma_f32_16x16x32_bf16 v[116:119], v[158:161], v[182:185], v[116:119]
	v_mfma_f32_16x16x32_bf16 v[116:119], v[162:165], v[186:189], v[116:119]
	v_mfma_f32_16x16x32_bf16 v[108:111], v[150:153], v[190:193], v[108:111]
	v_mfma_f32_16x16x32_bf16 v[108:111], v[154:157], v[194:197], v[108:111]
	v_mfma_f32_16x16x32_bf16 v[100:103], v[158:161], v[190:193], v[100:103]
	v_mfma_f32_16x16x32_bf16 v[100:103], v[162:165], v[194:197], v[100:103]
	v_mfma_f32_16x16x32_bf16 v[92:95], v[150:153], v[198:201], v[92:95]
	v_mfma_f32_16x16x32_bf16 v[92:95], v[154:157], v[202:205], v[92:95]
	v_mfma_f32_16x16x32_bf16 v[84:87], v[158:161], v[198:201], v[84:87]
	v_mfma_f32_16x16x32_bf16 v[84:87], v[162:165], v[202:205], v[84:87]
	v_mfma_f32_16x16x32_bf16 v[76:79], v[150:153], v[206:209], v[76:79]
	v_mfma_f32_16x16x32_bf16 v[76:79], v[154:157], v[210:213], v[76:79]
	v_mfma_f32_16x16x32_bf16 v[68:71], v[158:161], v[206:209], v[68:71]
	v_mfma_f32_16x16x32_bf16 v[68:71], v[162:165], v[210:213], v[68:71]
	v_mfma_f32_16x16x32_bf16 v[120:123], v[166:169], v[182:185], v[120:123]
	v_mfma_f32_16x16x32_bf16 v[120:123], v[170:173], v[186:189], v[120:123]
	v_mfma_f32_16x16x32_bf16 v[112:115], v[174:177], v[182:185], v[112:115]
	v_mfma_f32_16x16x32_bf16 v[112:115], v[178:181], v[186:189], v[112:115]
	v_mfma_f32_16x16x32_bf16 v[104:107], v[166:169], v[190:193], v[104:107]
	v_mfma_f32_16x16x32_bf16 v[104:107], v[170:173], v[194:197], v[104:107]
	v_mfma_f32_16x16x32_bf16 v[96:99], v[174:177], v[190:193], v[96:99]
	v_mfma_f32_16x16x32_bf16 v[96:99], v[178:181], v[194:197], v[96:99]
	v_mfma_f32_16x16x32_bf16 v[88:91], v[166:169], v[198:201], v[88:91]
	v_mfma_f32_16x16x32_bf16 v[88:91], v[170:173], v[202:205], v[88:91]
	v_mfma_f32_16x16x32_bf16 v[80:83], v[174:177], v[198:201], v[80:83]
	v_mfma_f32_16x16x32_bf16 v[80:83], v[178:181], v[202:205], v[80:83]
	v_mfma_f32_16x16x32_bf16 v[72:75], v[166:169], v[206:209], v[72:75]
	v_mfma_f32_16x16x32_bf16 v[72:75], v[170:173], v[210:213], v[72:75]
	v_mfma_f32_16x16x32_bf16 v[64:67], v[174:177], v[206:209], v[64:67]
	v_mfma_f32_16x16x32_bf16 v[64:67], v[178:181], v[210:213], v[64:67]
	s_barrier
	s_setprio 0
	s_add_i32 s52, s82, s56
	v_lshl_add_u64 v[214:215], v[214:215], 0, s[10:11]
	s_mov_b32 m0, s52
	ds_read_b128 v[182:185], v149 offset:49152
	ds_read_b128 v[186:189], v149 offset:50176
	ds_read_b128 v[190:193], v149 offset:51200
	ds_read_b128 v[194:197], v149 offset:52224
	ds_read_b128 v[198:201], v149 offset:53248
	ds_read_b128 v[202:205], v149 offset:54272
	ds_read_b128 v[206:209], v149 offset:55296
	ds_read_b128 v[210:213], v149 offset:56320
	global_load_lds_dwordx4 v[214:215], off
	s_add_i32 m0, s52, 0x2000
	s_add_u32 s50, s50, 0x40080
	v_lshl_add_u64 v[214:215], v[216:217], 0, s[10:11]
	s_addc_u32 s51, s51, 0
	s_add_i32 s52, s85, s56
	global_load_lds_dwordx4 v[214:215], off
	v_lshl_add_u64 v[214:215], s[50:51], 0, v[132:133]
	s_mov_b32 m0, s52
	s_nop 0
	global_load_lds_dwordx4 v[214:215], off
	v_lshl_add_u64 v[214:215], s[50:51], 0, v[128:129]
	s_add_i32 m0, s52, 0x2000
	s_nop 0
	global_load_lds_dwordx4 v[214:215], off
	v_lshl_add_u64 v[214:215], v[218:219], 0, s[10:11]
	s_mov_b32 m0, s69
	s_nop 0
	global_load_lds_dwordx4 v[214:215], off
	v_lshl_add_u64 v[214:215], v[220:221], 0, s[10:11]
	s_mov_b32 m0, s70
	s_nop 0
	global_load_lds_dwordx4 v[214:215], off
	s_waitcnt vmcnt(8)
	s_waitcnt lgkmcnt(0)
	s_setprio 1
	s_barrier
	v_mfma_f32_16x16x32_bf16 v[60:63], v[150:153], v[182:185], v[60:63]
	v_mfma_f32_16x16x32_bf16 v[60:63], v[154:157], v[186:189], v[60:63]
	v_mfma_f32_16x16x32_bf16 v[52:55], v[158:161], v[182:185], v[52:55]
	v_mfma_f32_16x16x32_bf16 v[52:55], v[162:165], v[186:189], v[52:55]
	v_mfma_f32_16x16x32_bf16 v[44:47], v[150:153], v[190:193], v[44:47]
	v_mfma_f32_16x16x32_bf16 v[44:47], v[154:157], v[194:197], v[44:47]
	v_mfma_f32_16x16x32_bf16 v[36:39], v[158:161], v[190:193], v[36:39]
	v_mfma_f32_16x16x32_bf16 v[36:39], v[162:165], v[194:197], v[36:39]
	v_mfma_f32_16x16x32_bf16 v[28:31], v[150:153], v[198:201], v[28:31]
	v_mfma_f32_16x16x32_bf16 v[28:31], v[154:157], v[202:205], v[28:31]
	v_mfma_f32_16x16x32_bf16 v[20:23], v[158:161], v[198:201], v[20:23]
	v_mfma_f32_16x16x32_bf16 v[20:23], v[162:165], v[202:205], v[20:23]
	v_mfma_f32_16x16x32_bf16 v[12:15], v[150:153], v[206:209], v[12:15]
	v_mfma_f32_16x16x32_bf16 v[12:15], v[154:157], v[210:213], v[12:15]
	v_mfma_f32_16x16x32_bf16 v[4:7], v[158:161], v[206:209], v[4:7]
	v_mfma_f32_16x16x32_bf16 v[4:7], v[162:165], v[210:213], v[4:7]
	v_mfma_f32_16x16x32_bf16 v[56:59], v[166:169], v[182:185], v[56:59]
	v_mfma_f32_16x16x32_bf16 v[56:59], v[170:173], v[186:189], v[56:59]
	v_mfma_f32_16x16x32_bf16 v[48:51], v[174:177], v[182:185], v[48:51]
	v_mfma_f32_16x16x32_bf16 v[48:51], v[178:181], v[186:189], v[48:51]
	v_mfma_f32_16x16x32_bf16 v[40:43], v[166:169], v[190:193], v[40:43]
	v_mfma_f32_16x16x32_bf16 v[40:43], v[170:173], v[194:197], v[40:43]
	v_mfma_f32_16x16x32_bf16 v[32:35], v[174:177], v[190:193], v[32:35]
	v_mfma_f32_16x16x32_bf16 v[32:35], v[178:181], v[194:197], v[32:35]
	v_mfma_f32_16x16x32_bf16 v[24:27], v[166:169], v[198:201], v[24:27]
	v_mfma_f32_16x16x32_bf16 v[24:27], v[170:173], v[202:205], v[24:27]
	v_mfma_f32_16x16x32_bf16 v[16:19], v[174:177], v[198:201], v[16:19]
	v_mfma_f32_16x16x32_bf16 v[16:19], v[178:181], v[202:205], v[16:19]
	v_mfma_f32_16x16x32_bf16 v[8:11], v[166:169], v[206:209], v[8:11]
	v_mfma_f32_16x16x32_bf16 v[8:11], v[170:173], v[210:213], v[8:11]
	v_mfma_f32_16x16x32_bf16 v[0:3], v[174:177], v[206:209], v[0:3]
	v_mfma_f32_16x16x32_bf16 v[0:3], v[178:181], v[210:213], v[0:3]
	s_barrier
	s_setprio 0
	s_add_i32 s81, s81, 2
	s_add_u32 s48, s48, 0x100
	s_addc_u32 s49, s49, 0
	s_add_u32 s79, s79, 0x100
	s_addc_u32 s80, s80, 0
	s_cmp_gt_u32 s81, 13
.LBB0_141:
	ds_read_b128 v[150:153], v147
	ds_read_b128 v[154:157], v147 offset:1024
	ds_read_b128 v[158:161], v147 offset:2048
	ds_read_b128 v[162:165], v147 offset:3072
	ds_read_b128 v[166:169], v148
	ds_read_b128 v[170:173], v148 offset:1024
	ds_read_b128 v[174:177], v148 offset:2048
	ds_read_b128 v[178:181], v148 offset:3072
	s_add_u32 s50, s48, 0xfffc0080
	s_addc_u32 s51, s49, -1
	s_cmp_eq_u32 s81, 12
	s_cselect_b32 s53, s37, s51
	s_cselect_b32 s52, s77, s50
	s_cselect_b32 s51, s39, s80
	s_cselect_b32 s50, s78, s79
	v_lshl_add_u64 v[214:215], s[48:49], 0, v[136:137]
	s_add_i32 m0, s47, 0xc000
	ds_read_b128 v[182:185], v149
	ds_read_b128 v[186:189], v149 offset:1024
	ds_read_b128 v[190:193], v149 offset:2048
	ds_read_b128 v[194:197], v149 offset:3072
	ds_read_b128 v[198:201], v149 offset:4096
	ds_read_b128 v[202:205], v149 offset:5120
	ds_read_b128 v[206:209], v149 offset:6144
	ds_read_b128 v[210:213], v149 offset:7168
	global_load_lds_dwordx4 v[214:215], off
	v_lshl_add_u64 v[214:215], s[48:49], 0, v[138:139]
	s_add_i32 m0, s47, 0xe000
	s_nop 0
	global_load_lds_dwordx4 v[214:215], off
	s_waitcnt vmcnt(8)
	s_waitcnt lgkmcnt(0)
	s_setprio 1
	s_barrier
	v_mfma_f32_16x16x32_bf16 v[124:127], v[150:153], v[182:185], v[124:127]
	v_mfma_f32_16x16x32_bf16 v[124:127], v[154:157], v[186:189], v[124:127]
	v_mfma_f32_16x16x32_bf16 v[116:119], v[158:161], v[182:185], v[116:119]
	v_mfma_f32_16x16x32_bf16 v[116:119], v[162:165], v[186:189], v[116:119]
	v_mfma_f32_16x16x32_bf16 v[108:111], v[150:153], v[190:193], v[108:111]
	v_mfma_f32_16x16x32_bf16 v[108:111], v[154:157], v[194:197], v[108:111]
	v_mfma_f32_16x16x32_bf16 v[100:103], v[158:161], v[190:193], v[100:103]
	v_mfma_f32_16x16x32_bf16 v[100:103], v[162:165], v[194:197], v[100:103]
	v_mfma_f32_16x16x32_bf16 v[92:95], v[150:153], v[198:201], v[92:95]
	v_mfma_f32_16x16x32_bf16 v[92:95], v[154:157], v[202:205], v[92:95]
	v_mfma_f32_16x16x32_bf16 v[84:87], v[158:161], v[198:201], v[84:87]
	v_mfma_f32_16x16x32_bf16 v[84:87], v[162:165], v[202:205], v[84:87]
	v_mfma_f32_16x16x32_bf16 v[76:79], v[150:153], v[206:209], v[76:79]
	v_mfma_f32_16x16x32_bf16 v[76:79], v[154:157], v[210:213], v[76:79]
	v_mfma_f32_16x16x32_bf16 v[68:71], v[158:161], v[206:209], v[68:71]
	v_mfma_f32_16x16x32_bf16 v[68:71], v[162:165], v[210:213], v[68:71]
	v_mfma_f32_16x16x32_bf16 v[120:123], v[166:169], v[182:185], v[120:123]
	v_mfma_f32_16x16x32_bf16 v[120:123], v[170:173], v[186:189], v[120:123]
	v_mfma_f32_16x16x32_bf16 v[112:115], v[174:177], v[182:185], v[112:115]
	v_mfma_f32_16x16x32_bf16 v[112:115], v[178:181], v[186:189], v[112:115]
	v_mfma_f32_16x16x32_bf16 v[104:107], v[166:169], v[190:193], v[104:107]
	v_mfma_f32_16x16x32_bf16 v[104:107], v[170:173], v[194:197], v[104:107]
	v_mfma_f32_16x16x32_bf16 v[96:99], v[174:177], v[190:193], v[96:99]
	v_mfma_f32_16x16x32_bf16 v[96:99], v[178:181], v[194:197], v[96:99]
	v_mfma_f32_16x16x32_bf16 v[88:91], v[166:169], v[198:201], v[88:91]
	v_mfma_f32_16x16x32_bf16 v[88:91], v[170:173], v[202:205], v[88:91]
	v_mfma_f32_16x16x32_bf16 v[80:83], v[174:177], v[198:201], v[80:83]
	v_mfma_f32_16x16x32_bf16 v[80:83], v[178:181], v[202:205], v[80:83]
	v_mfma_f32_16x16x32_bf16 v[72:75], v[166:169], v[206:209], v[72:75]
	v_mfma_f32_16x16x32_bf16 v[72:75], v[170:173], v[210:213], v[72:75]
	v_mfma_f32_16x16x32_bf16 v[64:67], v[174:177], v[206:209], v[64:67]
	v_mfma_f32_16x16x32_bf16 v[64:67], v[178:181], v[210:213], v[64:67]
	s_barrier
	s_setprio 0
	s_add_i32 s82, s73, s56
	v_lshl_add_u64 v[214:215], s[50:51], 0, v[132:133]
	s_mov_b32 m0, s82
	ds_read_b128 v[182:185], v149 offset:16384
	ds_read_b128 v[186:189], v149 offset:17408
	ds_read_b128 v[190:193], v149 offset:18432
	ds_read_b128 v[194:197], v149 offset:19456
	ds_read_b128 v[198:201], v149 offset:20480
	ds_read_b128 v[202:205], v149 offset:21504
	ds_read_b128 v[206:209], v149 offset:22528
	ds_read_b128 v[210:213], v149 offset:23552
	global_load_lds_dwordx4 v[214:215], off
	s_add_i32 m0, s82, 0x2000
	s_add_u32 s88, s50, 0x40000
	v_lshl_add_u64 v[216:217], s[50:51], 0, v[128:129]
	s_addc_u32 s89, s51, 0
	s_add_i32 s82, s74, s56
	global_load_lds_dwordx4 v[216:217], off
	v_lshl_add_u64 v[218:219], s[88:89], 0, v[132:133]
	s_mov_b32 m0, s82
	v_lshl_add_u64 v[220:221], s[52:53], 0, v[130:131]
	global_load_lds_dwordx4 v[218:219], off
	v_lshl_add_u64 v[218:219], s[88:89], 0, v[128:129]
	s_add_i32 m0, s82, 0x2000
	s_nop 0
	global_load_lds_dwordx4 v[218:219], off
	v_lshl_add_u64 v[218:219], s[52:53], 0, v[134:135]
	s_mov_b32 m0, s47
	s_nop 0
	global_load_lds_dwordx4 v[218:219], off
	s_mov_b32 m0, s59
	s_nop 0
	global_load_lds_dwordx4 v[220:221], off
	s_waitcnt vmcnt(8)
	s_waitcnt lgkmcnt(0)
	s_setprio 1
	s_barrier
	v_mfma_f32_16x16x32_bf16 v[60:63], v[150:153], v[182:185], v[60:63]
	v_mfma_f32_16x16x32_bf16 v[60:63], v[154:157], v[186:189], v[60:63]
	v_mfma_f32_16x16x32_bf16 v[52:55], v[158:161], v[182:185], v[52:55]
	v_mfma_f32_16x16x32_bf16 v[52:55], v[162:165], v[186:189], v[52:55]
	v_mfma_f32_16x16x32_bf16 v[44:47], v[150:153], v[190:193], v[44:47]
	v_mfma_f32_16x16x32_bf16 v[44:47], v[154:157], v[194:197], v[44:47]
	v_mfma_f32_16x16x32_bf16 v[36:39], v[158:161], v[190:193], v[36:39]
	v_mfma_f32_16x16x32_bf16 v[36:39], v[162:165], v[194:197], v[36:39]
	v_mfma_f32_16x16x32_bf16 v[28:31], v[150:153], v[198:201], v[28:31]
	v_mfma_f32_16x16x32_bf16 v[28:31], v[154:157], v[202:205], v[28:31]
	v_mfma_f32_16x16x32_bf16 v[20:23], v[158:161], v[198:201], v[20:23]
	v_mfma_f32_16x16x32_bf16 v[20:23], v[162:165], v[202:205], v[20:23]
	v_mfma_f32_16x16x32_bf16 v[12:15], v[150:153], v[206:209], v[12:15]
	v_mfma_f32_16x16x32_bf16 v[12:15], v[154:157], v[210:213], v[12:15]
	v_mfma_f32_16x16x32_bf16 v[4:7], v[158:161], v[206:209], v[4:7]
	v_mfma_f32_16x16x32_bf16 v[4:7], v[162:165], v[210:213], v[4:7]
	v_mfma_f32_16x16x32_bf16 v[56:59], v[166:169], v[182:185], v[56:59]
	v_mfma_f32_16x16x32_bf16 v[56:59], v[170:173], v[186:189], v[56:59]
	v_mfma_f32_16x16x32_bf16 v[48:51], v[174:177], v[182:185], v[48:51]
	v_mfma_f32_16x16x32_bf16 v[48:51], v[178:181], v[186:189], v[48:51]
	v_mfma_f32_16x16x32_bf16 v[40:43], v[166:169], v[190:193], v[40:43]
	v_mfma_f32_16x16x32_bf16 v[40:43], v[170:173], v[194:197], v[40:43]
	v_mfma_f32_16x16x32_bf16 v[32:35], v[174:177], v[190:193], v[32:35]
	v_mfma_f32_16x16x32_bf16 v[32:35], v[178:181], v[194:197], v[32:35]
	v_mfma_f32_16x16x32_bf16 v[24:27], v[166:169], v[198:201], v[24:27]
	v_mfma_f32_16x16x32_bf16 v[24:27], v[170:173], v[202:205], v[24:27]
	v_mfma_f32_16x16x32_bf16 v[16:19], v[174:177], v[198:201], v[16:19]
	v_mfma_f32_16x16x32_bf16 v[16:19], v[178:181], v[202:205], v[16:19]
	v_mfma_f32_16x16x32_bf16 v[8:11], v[166:169], v[206:209], v[8:11]
	v_mfma_f32_16x16x32_bf16 v[8:11], v[170:173], v[210:213], v[8:11]
	v_mfma_f32_16x16x32_bf16 v[0:3], v[174:177], v[206:209], v[0:3]
	v_mfma_f32_16x16x32_bf16 v[0:3], v[178:181], v[210:213], v[0:3]
	s_barrier
	s_setprio 0
	s_add_i32 s82, 0, 0x18000
	s_add_i32 s85, 0, 0x1c000
	v_add_u32_e32 v162, s82, v145
	v_add_u32_e32 v178, s85, v145
	ds_read_b128 v[150:153], v162
	ds_read_b128 v[154:157], v162 offset:1024
	ds_read_b128 v[158:161], v162 offset:2048
	ds_read_b128 v[162:165], v162 offset:3072
	ds_read_b128 v[166:169], v178
	ds_read_b128 v[170:173], v178 offset:1024
	ds_read_b128 v[174:177], v178 offset:2048
	ds_read_b128 v[178:181], v178 offset:3072
	s_add_u32 s52, s52, 0x40000
	s_addc_u32 s53, s53, 0
	s_mov_b32 m0, s66
	v_lshl_add_u64 v[222:223], s[52:53], 0, v[134:135]
	ds_read_b128 v[182:185], v149 offset:32768
	ds_read_b128 v[186:189], v149 offset:33792
	ds_read_b128 v[190:193], v149 offset:34816
	ds_read_b128 v[194:197], v149 offset:35840
	ds_read_b128 v[198:201], v149 offset:36864
	ds_read_b128 v[202:205], v149 offset:37888
	ds_read_b128 v[206:209], v149 offset:38912
	ds_read_b128 v[210:213], v149 offset:39936
	global_load_lds_dwordx4 v[222:223], off
	v_lshl_add_u64 v[222:223], s[52:53], 0, v[130:131]
	s_mov_b32 m0, s67
	s_nop 0
	global_load_lds_dwordx4 v[222:223], off
	s_waitcnt vmcnt(8)
	s_waitcnt lgkmcnt(0)
	s_setprio 1
	s_barrier
	v_mfma_f32_16x16x32_bf16 v[124:127], v[150:153], v[182:185], v[124:127]
	v_mfma_f32_16x16x32_bf16 v[124:127], v[154:157], v[186:189], v[124:127]
	v_mfma_f32_16x16x32_bf16 v[116:119], v[158:161], v[182:185], v[116:119]
	v_mfma_f32_16x16x32_bf16 v[116:119], v[162:165], v[186:189], v[116:119]
	v_mfma_f32_16x16x32_bf16 v[108:111], v[150:153], v[190:193], v[108:111]
	v_mfma_f32_16x16x32_bf16 v[108:111], v[154:157], v[194:197], v[108:111]
	v_mfma_f32_16x16x32_bf16 v[100:103], v[158:161], v[190:193], v[100:103]
	v_mfma_f32_16x16x32_bf16 v[100:103], v[162:165], v[194:197], v[100:103]
	v_mfma_f32_16x16x32_bf16 v[92:95], v[150:153], v[198:201], v[92:95]
	v_mfma_f32_16x16x32_bf16 v[92:95], v[154:157], v[202:205], v[92:95]
	v_mfma_f32_16x16x32_bf16 v[84:87], v[158:161], v[198:201], v[84:87]
	v_mfma_f32_16x16x32_bf16 v[84:87], v[162:165], v[202:205], v[84:87]
	v_mfma_f32_16x16x32_bf16 v[76:79], v[150:153], v[206:209], v[76:79]
	v_mfma_f32_16x16x32_bf16 v[76:79], v[154:157], v[210:213], v[76:79]
	v_mfma_f32_16x16x32_bf16 v[68:71], v[158:161], v[206:209], v[68:71]
	v_mfma_f32_16x16x32_bf16 v[68:71], v[162:165], v[210:213], v[68:71]
	v_mfma_f32_16x16x32_bf16 v[120:123], v[166:169], v[182:185], v[120:123]
	v_mfma_f32_16x16x32_bf16 v[120:123], v[170:173], v[186:189], v[120:123]
	v_mfma_f32_16x16x32_bf16 v[112:115], v[174:177], v[182:185], v[112:115]
	v_mfma_f32_16x16x32_bf16 v[112:115], v[178:181], v[186:189], v[112:115]
	v_mfma_f32_16x16x32_bf16 v[104:107], v[166:169], v[190:193], v[104:107]
	v_mfma_f32_16x16x32_bf16 v[104:107], v[170:173], v[194:197], v[104:107]
	v_mfma_f32_16x16x32_bf16 v[96:99], v[174:177], v[190:193], v[96:99]
	v_mfma_f32_16x16x32_bf16 v[96:99], v[178:181], v[194:197], v[96:99]
	v_mfma_f32_16x16x32_bf16 v[88:91], v[166:169], v[198:201], v[88:91]
	v_mfma_f32_16x16x32_bf16 v[88:91], v[170:173], v[202:205], v[88:91]
	v_mfma_f32_16x16x32_bf16 v[80:83], v[174:177], v[198:201], v[80:83]
	v_mfma_f32_16x16x32_bf16 v[80:83], v[178:181], v[202:205], v[80:83]
	v_mfma_f32_16x16x32_bf16 v[72:75], v[166:169], v[206:209], v[72:75]
	v_mfma_f32_16x16x32_bf16 v[72:75], v[170:173], v[210:213], v[72:75]
	v_mfma_f32_16x16x32_bf16 v[64:67], v[174:177], v[206:209], v[64:67]
	v_mfma_f32_16x16x32_bf16 v[64:67], v[178:181], v[210:213], v[64:67]
	s_barrier
	s_setprio 0
	s_add_i32 s52, s82, s56
	v_lshl_add_u64 v[214:215], v[214:215], 0, s[10:11]
	s_mov_b32 m0, s52
	ds_read_b128 v[182:185], v149 offset:49152
	ds_read_b128 v[186:189], v149 offset:50176
	ds_read_b128 v[190:193], v149 offset:51200
	ds_read_b128 v[194:197], v149 offset:52224
	ds_read_b128 v[198:201], v149 offset:53248
	ds_read_b128 v[202:205], v149 offset:54272
	ds_read_b128 v[206:209], v149 offset:55296
	ds_read_b128 v[210:213], v149 offset:56320
	global_load_lds_dwordx4 v[214:215], off
	s_add_i32 m0, s52, 0x2000
	s_add_u32 s50, s50, 0x40080
	v_lshl_add_u64 v[214:215], v[216:217], 0, s[10:11]
	s_addc_u32 s51, s51, 0
	s_add_i32 s52, s85, s56
	global_load_lds_dwordx4 v[214:215], off
	v_lshl_add_u64 v[214:215], s[50:51], 0, v[132:133]
	s_mov_b32 m0, s52
	s_nop 0
	global_load_lds_dwordx4 v[214:215], off
	v_lshl_add_u64 v[214:215], s[50:51], 0, v[128:129]
	s_add_i32 m0, s52, 0x2000
	s_nop 0
	global_load_lds_dwordx4 v[214:215], off
	v_lshl_add_u64 v[214:215], v[218:219], 0, s[10:11]
	s_mov_b32 m0, s69
	s_nop 0
	global_load_lds_dwordx4 v[214:215], off
	v_lshl_add_u64 v[214:215], v[220:221], 0, s[10:11]
	s_mov_b32 m0, s70
	s_nop 0
	global_load_lds_dwordx4 v[214:215], off
	s_waitcnt vmcnt(8)
	s_waitcnt lgkmcnt(0)
	s_setprio 1
	s_barrier
	v_mfma_f32_16x16x32_bf16 v[60:63], v[150:153], v[182:185], v[60:63]
	v_mfma_f32_16x16x32_bf16 v[60:63], v[154:157], v[186:189], v[60:63]
	v_mfma_f32_16x16x32_bf16 v[52:55], v[158:161], v[182:185], v[52:55]
	v_mfma_f32_16x16x32_bf16 v[52:55], v[162:165], v[186:189], v[52:55]
	v_mfma_f32_16x16x32_bf16 v[44:47], v[150:153], v[190:193], v[44:47]
	v_mfma_f32_16x16x32_bf16 v[44:47], v[154:157], v[194:197], v[44:47]
	v_mfma_f32_16x16x32_bf16 v[36:39], v[158:161], v[190:193], v[36:39]
	v_mfma_f32_16x16x32_bf16 v[36:39], v[162:165], v[194:197], v[36:39]
	v_mfma_f32_16x16x32_bf16 v[28:31], v[150:153], v[198:201], v[28:31]
	v_mfma_f32_16x16x32_bf16 v[28:31], v[154:157], v[202:205], v[28:31]
	v_mfma_f32_16x16x32_bf16 v[20:23], v[158:161], v[198:201], v[20:23]
	v_mfma_f32_16x16x32_bf16 v[20:23], v[162:165], v[202:205], v[20:23]
	v_mfma_f32_16x16x32_bf16 v[12:15], v[150:153], v[206:209], v[12:15]
	v_mfma_f32_16x16x32_bf16 v[12:15], v[154:157], v[210:213], v[12:15]
	v_mfma_f32_16x16x32_bf16 v[4:7], v[158:161], v[206:209], v[4:7]
	v_mfma_f32_16x16x32_bf16 v[4:7], v[162:165], v[210:213], v[4:7]
	v_mfma_f32_16x16x32_bf16 v[56:59], v[166:169], v[182:185], v[56:59]
	v_mfma_f32_16x16x32_bf16 v[56:59], v[170:173], v[186:189], v[56:59]
	v_mfma_f32_16x16x32_bf16 v[48:51], v[174:177], v[182:185], v[48:51]
	v_mfma_f32_16x16x32_bf16 v[48:51], v[178:181], v[186:189], v[48:51]
	v_mfma_f32_16x16x32_bf16 v[40:43], v[166:169], v[190:193], v[40:43]
	v_mfma_f32_16x16x32_bf16 v[40:43], v[170:173], v[194:197], v[40:43]
	v_mfma_f32_16x16x32_bf16 v[32:35], v[174:177], v[190:193], v[32:35]
	v_mfma_f32_16x16x32_bf16 v[32:35], v[178:181], v[194:197], v[32:35]
	v_mfma_f32_16x16x32_bf16 v[24:27], v[166:169], v[198:201], v[24:27]
	v_mfma_f32_16x16x32_bf16 v[24:27], v[170:173], v[202:205], v[24:27]
	v_mfma_f32_16x16x32_bf16 v[16:19], v[174:177], v[198:201], v[16:19]
	v_mfma_f32_16x16x32_bf16 v[16:19], v[178:181], v[202:205], v[16:19]
	v_mfma_f32_16x16x32_bf16 v[8:11], v[166:169], v[206:209], v[8:11]
	v_mfma_f32_16x16x32_bf16 v[8:11], v[170:173], v[210:213], v[8:11]
	v_mfma_f32_16x16x32_bf16 v[0:3], v[174:177], v[206:209], v[0:3]
	v_mfma_f32_16x16x32_bf16 v[0:3], v[178:181], v[210:213], v[0:3]
	s_barrier
	s_setprio 0
	s_add_i32 s81, s81, 2
	s_add_u32 s48, s48, 0x100
	s_addc_u32 s49, s49, 0
	s_add_u32 s79, s79, 0x100
	s_addc_u32 s80, s80, 0
	s_cmp_gt_u32 s81, 13
	s_cbranch_scc0 .LBB0_141
	s_and_b64 vcc, exec, s[26:27]
	s_cbranch_vccz .LBB0_144
	s_barrier

.LBB0_220:
	s_add_u32 s95, s52, 0x100
	s_addc_u32 s96, s53, 0
	s_mov_b32 s97, -2
	ds_read_b128 v[88:91], v233
	ds_read_b128 v[92:95], v233 offset:1024
	ds_read_b128 v[112:115], v233 offset:2048
	ds_read_b128 v[116:119], v233 offset:3072
	ds_read_b128 v[132:135], v234
	ds_read_b128 v[136:139], v234 offset:1024
	ds_read_b128 v[152:155], v234 offset:2048
	ds_read_b128 v[156:159], v234 offset:3072
	s_add_u32 s52, s50, 0x100
	s_addc_u32 s53, s51, 0
	s_cmp_eq_u32 s97, 40
	s_cselect_b32 s57, s9, s53
	s_cselect_b32 s56, s8, s52
	s_cselect_b32 s55, s41, s96
	s_cselect_b32 s54, s40, s95
	v_lshl_add_u64 v[216:217], s[50:51], 0, v[196:197]
	s_add_i32 m0, s67, 0xc000
	ds_read_b128 v[160:163], v235
	ds_read_b128 v[164:167], v235 offset:1024
	ds_read_b128 v[168:171], v235 offset:2048
	ds_read_b128 v[172:175], v235 offset:3072
	ds_read_b128 v[176:179], v235 offset:4096
	ds_read_b128 v[180:183], v235 offset:5120
	ds_read_b128 v[208:211], v235 offset:6144
	ds_read_b128 v[212:215], v235 offset:7168
	global_load_lds_dwordx4 v[216:217], off
	v_lshl_add_u64 v[216:217], s[50:51], 0, v[198:199]
	s_add_i32 m0, s67, 0xe000
	s_nop 0
	global_load_lds_dwordx4 v[216:217], off
	s_waitcnt vmcnt(8)
	s_waitcnt lgkmcnt(0)
	s_setprio 1
	s_barrier
	v_mfma_f32_16x16x32_bf16 v[148:151], v[88:91], v[160:163], 0
	v_mfma_f32_16x16x32_bf16 v[148:151], v[92:95], v[164:167], v[148:151]
	v_mfma_f32_16x16x32_bf16 v[144:147], v[112:115], v[160:163], 0
	v_mfma_f32_16x16x32_bf16 v[144:147], v[116:119], v[164:167], v[144:147]
	v_mfma_f32_16x16x32_bf16 v[124:127], v[88:91], v[168:171], 0
	v_mfma_f32_16x16x32_bf16 v[124:127], v[92:95], v[172:175], v[124:127]
	v_mfma_f32_16x16x32_bf16 v[120:123], v[112:115], v[168:171], 0
	v_mfma_f32_16x16x32_bf16 v[120:123], v[116:119], v[172:175], v[120:123]
	v_mfma_f32_16x16x32_bf16 v[100:103], v[88:91], v[176:179], 0
	v_mfma_f32_16x16x32_bf16 v[100:103], v[92:95], v[180:183], v[100:103]
	v_mfma_f32_16x16x32_bf16 v[96:99], v[112:115], v[176:179], 0
	v_mfma_f32_16x16x32_bf16 v[96:99], v[116:119], v[180:183], v[96:99]
	v_mfma_f32_16x16x32_bf16 v[76:79], v[88:91], v[208:211], 0
	v_mfma_f32_16x16x32_bf16 v[76:79], v[92:95], v[212:215], v[76:79]
	v_mfma_f32_16x16x32_bf16 v[72:75], v[112:115], v[208:211], 0
	v_mfma_f32_16x16x32_bf16 v[72:75], v[116:119], v[212:215], v[72:75]
	v_mfma_f32_16x16x32_bf16 v[140:143], v[132:135], v[160:163], 0
	v_mfma_f32_16x16x32_bf16 v[140:143], v[136:139], v[164:167], v[140:143]
	v_mfma_f32_16x16x32_bf16 v[128:131], v[152:155], v[160:163], 0
	v_mfma_f32_16x16x32_bf16 v[128:131], v[156:159], v[164:167], v[128:131]
	v_mfma_f32_16x16x32_bf16 v[108:111], v[132:135], v[168:171], 0
	v_mfma_f32_16x16x32_bf16 v[108:111], v[136:139], v[172:175], v[108:111]
	v_mfma_f32_16x16x32_bf16 v[104:107], v[152:155], v[168:171], 0
	v_mfma_f32_16x16x32_bf16 v[104:107], v[156:159], v[172:175], v[104:107]
	v_mfma_f32_16x16x32_bf16 v[84:87], v[132:135], v[176:179], 0
	v_mfma_f32_16x16x32_bf16 v[84:87], v[136:139], v[180:183], v[84:87]
	v_mfma_f32_16x16x32_bf16 v[80:83], v[152:155], v[176:179], 0
	v_mfma_f32_16x16x32_bf16 v[80:83], v[156:159], v[180:183], v[80:83]
	v_mfma_f32_16x16x32_bf16 v[68:71], v[132:135], v[208:211], 0
	v_mfma_f32_16x16x32_bf16 v[68:71], v[136:139], v[212:215], v[68:71]
	v_mfma_f32_16x16x32_bf16 v[64:67], v[152:155], v[208:211], 0
	v_mfma_f32_16x16x32_bf16 v[64:67], v[156:159], v[212:215], v[64:67]
	s_barrier
	s_setprio 0
	s_add_i32 s50, s82, s66
	v_lshl_add_u64 v[216:217], s[54:55], 0, v[186:187]
	s_mov_b32 m0, s50
	ds_read_b128 v[160:163], v235 offset:16384
	ds_read_b128 v[164:167], v235 offset:17408
	ds_read_b128 v[168:171], v235 offset:18432
	ds_read_b128 v[172:175], v235 offset:19456
	ds_read_b128 v[176:179], v235 offset:20480
	ds_read_b128 v[180:183], v235 offset:21504
	ds_read_b128 v[208:211], v235 offset:22528
	ds_read_b128 v[212:215], v235 offset:23552
	global_load_lds_dwordx4 v[216:217], off
	s_add_i32 m0, s50, 0x2000
	s_add_u32 s50, s54, 0xb0000
	v_lshl_add_u64 v[218:219], s[54:55], 0, v[190:191]
	s_addc_u32 s51, s55, 0
	s_add_i32 vcc_lo, s85, s66
	global_load_lds_dwordx4 v[218:219], off
	v_lshl_add_u64 v[220:221], s[50:51], 0, v[186:187]
	s_mov_b32 m0, vcc_lo
	v_lshl_add_u64 v[222:223], s[56:57], 0, v[188:189]
	global_load_lds_dwordx4 v[220:221], off
	v_lshl_add_u64 v[220:221], s[50:51], 0, v[190:191]
	s_add_i32 m0, vcc_lo, 0x2000
	s_nop 0
	global_load_lds_dwordx4 v[220:221], off
	v_lshl_add_u64 v[220:221], s[56:57], 0, v[184:185]
	s_mov_b32 m0, s67
	s_nop 0
	global_load_lds_dwordx4 v[220:221], off
	s_mov_b32 m0, s68
	s_nop 0
	global_load_lds_dwordx4 v[222:223], off
	s_waitcnt vmcnt(8)
	s_waitcnt lgkmcnt(0)
	s_setprio 1
	s_barrier
	v_mfma_f32_16x16x32_bf16 v[60:63], v[88:91], v[160:163], 0
	v_mfma_f32_16x16x32_bf16 v[60:63], v[92:95], v[164:167], v[60:63]
	v_mfma_f32_16x16x32_bf16 v[56:59], v[112:115], v[160:163], 0
	v_mfma_f32_16x16x32_bf16 v[56:59], v[116:119], v[164:167], v[56:59]
	v_mfma_f32_16x16x32_bf16 v[44:47], v[88:91], v[168:171], 0
	v_mfma_f32_16x16x32_bf16 v[44:47], v[92:95], v[172:175], v[44:47]
	v_mfma_f32_16x16x32_bf16 v[40:43], v[112:115], v[168:171], 0
	v_mfma_f32_16x16x32_bf16 v[40:43], v[116:119], v[172:175], v[40:43]
	v_mfma_f32_16x16x32_bf16 v[28:31], v[88:91], v[176:179], 0
	v_mfma_f32_16x16x32_bf16 v[28:31], v[92:95], v[180:183], v[28:31]
	v_mfma_f32_16x16x32_bf16 v[24:27], v[112:115], v[176:179], 0
	v_mfma_f32_16x16x32_bf16 v[24:27], v[116:119], v[180:183], v[24:27]
	v_mfma_f32_16x16x32_bf16 v[12:15], v[88:91], v[208:211], 0
	v_mfma_f32_16x16x32_bf16 v[12:15], v[92:95], v[212:215], v[12:15]
	v_mfma_f32_16x16x32_bf16 v[8:11], v[112:115], v[208:211], 0
	v_mfma_f32_16x16x32_bf16 v[8:11], v[116:119], v[212:215], v[8:11]
	v_mfma_f32_16x16x32_bf16 v[52:55], v[132:135], v[160:163], 0
	v_mfma_f32_16x16x32_bf16 v[52:55], v[136:139], v[164:167], v[52:55]
	v_mfma_f32_16x16x32_bf16 v[48:51], v[152:155], v[160:163], 0
	v_mfma_f32_16x16x32_bf16 v[48:51], v[156:159], v[164:167], v[48:51]
	v_mfma_f32_16x16x32_bf16 v[36:39], v[132:135], v[168:171], 0
	v_mfma_f32_16x16x32_bf16 v[36:39], v[136:139], v[172:175], v[36:39]
	v_mfma_f32_16x16x32_bf16 v[32:35], v[152:155], v[168:171], 0
	v_mfma_f32_16x16x32_bf16 v[32:35], v[156:159], v[172:175], v[32:35]
	v_mfma_f32_16x16x32_bf16 v[20:23], v[132:135], v[176:179], 0
	v_mfma_f32_16x16x32_bf16 v[20:23], v[136:139], v[180:183], v[20:23]
	v_mfma_f32_16x16x32_bf16 v[16:19], v[152:155], v[176:179], 0
	v_mfma_f32_16x16x32_bf16 v[16:19], v[156:159], v[180:183], v[16:19]
	v_mfma_f32_16x16x32_bf16 v[4:7], v[132:135], v[208:211], 0
	v_mfma_f32_16x16x32_bf16 v[4:7], v[136:139], v[212:215], v[4:7]
	v_mfma_f32_16x16x32_bf16 v[0:3], v[152:155], v[208:211], 0
	v_mfma_f32_16x16x32_bf16 v[0:3], v[156:159], v[212:215], v[0:3]
	s_barrier
	s_setprio 0
	s_add_i32 vcc_lo, 0, 0x18000
	s_add_i32 vcc_hi, 0, 0x1c000
	v_add_u32_e32 v116, vcc_lo, v230
	v_add_u32_e32 v156, vcc_hi, v230
	ds_read_b128 v[88:91], v116
	ds_read_b128 v[92:95], v116 offset:1024
	ds_read_b128 v[112:115], v116 offset:2048
	ds_read_b128 v[116:119], v116 offset:3072
	ds_read_b128 v[132:135], v156
	ds_read_b128 v[136:139], v156 offset:1024
	ds_read_b128 v[152:155], v156 offset:2048
	ds_read_b128 v[156:159], v156 offset:3072
	s_add_u32 s50, s56, 0xb0000
	s_addc_u32 s51, s57, 0
	s_mov_b32 m0, s69
	v_lshl_add_u64 v[224:225], s[50:51], 0, v[184:185]
	ds_read_b128 v[160:163], v235 offset:32768
	ds_read_b128 v[164:167], v235 offset:33792
	ds_read_b128 v[168:171], v235 offset:34816
	ds_read_b128 v[172:175], v235 offset:35840
	ds_read_b128 v[176:179], v235 offset:36864
	ds_read_b128 v[180:183], v235 offset:37888
	ds_read_b128 v[208:211], v235 offset:38912
	ds_read_b128 v[212:215], v235 offset:39936
	global_load_lds_dwordx4 v[224:225], off
	v_lshl_add_u64 v[224:225], s[50:51], 0, v[188:189]
	s_mov_b32 m0, s70
	s_nop 0
	global_load_lds_dwordx4 v[224:225], off
	s_waitcnt vmcnt(8)
	s_waitcnt lgkmcnt(0)
	s_setprio 1
	s_barrier
	v_mfma_f32_16x16x32_bf16 v[148:151], v[88:91], v[160:163], v[148:151]
	v_mfma_f32_16x16x32_bf16 v[148:151], v[92:95], v[164:167], v[148:151]
	v_mfma_f32_16x16x32_bf16 v[144:147], v[112:115], v[160:163], v[144:147]
	v_mfma_f32_16x16x32_bf16 v[144:147], v[116:119], v[164:167], v[144:147]
	v_mfma_f32_16x16x32_bf16 v[124:127], v[88:91], v[168:171], v[124:127]
	v_mfma_f32_16x16x32_bf16 v[124:127], v[92:95], v[172:175], v[124:127]
	v_mfma_f32_16x16x32_bf16 v[120:123], v[112:115], v[168:171], v[120:123]
	v_mfma_f32_16x16x32_bf16 v[120:123], v[116:119], v[172:175], v[120:123]
	v_mfma_f32_16x16x32_bf16 v[100:103], v[88:91], v[176:179], v[100:103]
	v_mfma_f32_16x16x32_bf16 v[100:103], v[92:95], v[180:183], v[100:103]
	v_mfma_f32_16x16x32_bf16 v[96:99], v[112:115], v[176:179], v[96:99]
	v_mfma_f32_16x16x32_bf16 v[96:99], v[116:119], v[180:183], v[96:99]
	v_mfma_f32_16x16x32_bf16 v[76:79], v[88:91], v[208:211], v[76:79]
	v_mfma_f32_16x16x32_bf16 v[76:79], v[92:95], v[212:215], v[76:79]
	v_mfma_f32_16x16x32_bf16 v[72:75], v[112:115], v[208:211], v[72:75]
	v_mfma_f32_16x16x32_bf16 v[72:75], v[116:119], v[212:215], v[72:75]
	v_mfma_f32_16x16x32_bf16 v[140:143], v[132:135], v[160:163], v[140:143]
	v_mfma_f32_16x16x32_bf16 v[140:143], v[136:139], v[164:167], v[140:143]
	v_mfma_f32_16x16x32_bf16 v[128:131], v[152:155], v[160:163], v[128:131]
	v_mfma_f32_16x16x32_bf16 v[128:131], v[156:159], v[164:167], v[128:131]
	v_mfma_f32_16x16x32_bf16 v[108:111], v[132:135], v[168:171], v[108:111]
	v_mfma_f32_16x16x32_bf16 v[108:111], v[136:139], v[172:175], v[108:111]
	v_mfma_f32_16x16x32_bf16 v[104:107], v[152:155], v[168:171], v[104:107]
	v_mfma_f32_16x16x32_bf16 v[104:107], v[156:159], v[172:175], v[104:107]
	v_mfma_f32_16x16x32_bf16 v[84:87], v[132:135], v[176:179], v[84:87]
	v_mfma_f32_16x16x32_bf16 v[84:87], v[136:139], v[180:183], v[84:87]
	v_mfma_f32_16x16x32_bf16 v[80:83], v[152:155], v[176:179], v[80:83]
	v_mfma_f32_16x16x32_bf16 v[80:83], v[156:159], v[180:183], v[80:83]
	v_mfma_f32_16x16x32_bf16 v[68:71], v[132:135], v[208:211], v[68:71]
	v_mfma_f32_16x16x32_bf16 v[68:71], v[136:139], v[212:215], v[68:71]
	v_mfma_f32_16x16x32_bf16 v[64:67], v[152:155], v[208:211], v[64:67]
	v_mfma_f32_16x16x32_bf16 v[64:67], v[156:159], v[212:215], v[64:67]
	s_barrier
	s_setprio 0
	s_add_i32 s50, vcc_lo, s66
	v_lshl_add_u64 v[216:217], v[216:217], 0, s[46:47]
	s_mov_b32 m0, s50
	ds_read_b128 v[160:163], v235 offset:49152
	ds_read_b128 v[164:167], v235 offset:50176
	ds_read_b128 v[168:171], v235 offset:51200
	ds_read_b128 v[172:175], v235 offset:52224
	ds_read_b128 v[176:179], v235 offset:53248
	ds_read_b128 v[180:183], v235 offset:54272
	ds_read_b128 v[208:211], v235 offset:55296
	ds_read_b128 v[212:215], v235 offset:56320
	global_load_lds_dwordx4 v[216:217], off
	s_add_i32 m0, s50, 0x2000
	s_add_u32 s50, s54, 0xb0080
	v_lshl_add_u64 v[216:217], v[218:219], 0, s[46:47]
	s_addc_u32 s51, s55, 0
	s_add_i32 s54, vcc_hi, s66
	global_load_lds_dwordx4 v[216:217], off
	v_lshl_add_u64 v[216:217], s[50:51], 0, v[186:187]
	s_mov_b32 m0, s54
	s_nop 0
	global_load_lds_dwordx4 v[216:217], off
	v_lshl_add_u64 v[216:217], s[50:51], 0, v[190:191]
	s_add_i32 m0, s54, 0x2000
	s_nop 0
	global_load_lds_dwordx4 v[216:217], off
	v_lshl_add_u64 v[216:217], v[220:221], 0, s[46:47]
	s_mov_b32 m0, s74
	s_nop 0
	global_load_lds_dwordx4 v[216:217], off
	v_lshl_add_u64 v[216:217], v[222:223], 0, s[46:47]
	s_mov_b32 m0, s75
	s_nop 0
	global_load_lds_dwordx4 v[216:217], off
	s_waitcnt vmcnt(8)
	s_waitcnt lgkmcnt(0)
	s_setprio 1
	s_barrier
	v_mfma_f32_16x16x32_bf16 v[60:63], v[88:91], v[160:163], v[60:63]
	v_mfma_f32_16x16x32_bf16 v[60:63], v[92:95], v[164:167], v[60:63]
	v_mfma_f32_16x16x32_bf16 v[56:59], v[112:115], v[160:163], v[56:59]
	v_mfma_f32_16x16x32_bf16 v[56:59], v[116:119], v[164:167], v[56:59]
	v_mfma_f32_16x16x32_bf16 v[44:47], v[88:91], v[168:171], v[44:47]
	v_mfma_f32_16x16x32_bf16 v[44:47], v[92:95], v[172:175], v[44:47]
	v_mfma_f32_16x16x32_bf16 v[40:43], v[112:115], v[168:171], v[40:43]
	v_mfma_f32_16x16x32_bf16 v[40:43], v[116:119], v[172:175], v[40:43]
	v_mfma_f32_16x16x32_bf16 v[28:31], v[88:91], v[176:179], v[28:31]
	v_mfma_f32_16x16x32_bf16 v[28:31], v[92:95], v[180:183], v[28:31]
	v_mfma_f32_16x16x32_bf16 v[24:27], v[112:115], v[176:179], v[24:27]
	v_mfma_f32_16x16x32_bf16 v[24:27], v[116:119], v[180:183], v[24:27]
	v_mfma_f32_16x16x32_bf16 v[12:15], v[88:91], v[208:211], v[12:15]
	v_mfma_f32_16x16x32_bf16 v[12:15], v[92:95], v[212:215], v[12:15]
	v_mfma_f32_16x16x32_bf16 v[8:11], v[112:115], v[208:211], v[8:11]
	v_mfma_f32_16x16x32_bf16 v[8:11], v[116:119], v[212:215], v[8:11]
	v_mfma_f32_16x16x32_bf16 v[52:55], v[132:135], v[160:163], v[52:55]
	v_mfma_f32_16x16x32_bf16 v[52:55], v[136:139], v[164:167], v[52:55]
	v_mfma_f32_16x16x32_bf16 v[48:51], v[152:155], v[160:163], v[48:51]
	v_mfma_f32_16x16x32_bf16 v[48:51], v[156:159], v[164:167], v[48:51]
	v_mfma_f32_16x16x32_bf16 v[36:39], v[132:135], v[168:171], v[36:39]
	v_mfma_f32_16x16x32_bf16 v[36:39], v[136:139], v[172:175], v[36:39]
	v_mfma_f32_16x16x32_bf16 v[32:35], v[152:155], v[168:171], v[32:35]
	v_mfma_f32_16x16x32_bf16 v[32:35], v[156:159], v[172:175], v[32:35]
	v_mfma_f32_16x16x32_bf16 v[20:23], v[132:135], v[176:179], v[20:23]
	v_mfma_f32_16x16x32_bf16 v[20:23], v[136:139], v[180:183], v[20:23]
	v_mfma_f32_16x16x32_bf16 v[16:19], v[152:155], v[176:179], v[16:19]
	v_mfma_f32_16x16x32_bf16 v[16:19], v[156:159], v[180:183], v[16:19]
	v_mfma_f32_16x16x32_bf16 v[4:7], v[132:135], v[208:211], v[4:7]
	v_mfma_f32_16x16x32_bf16 v[4:7], v[136:139], v[212:215], v[4:7]
	v_mfma_f32_16x16x32_bf16 v[0:3], v[152:155], v[208:211], v[0:3]
	v_mfma_f32_16x16x32_bf16 v[0:3], v[156:159], v[212:215], v[0:3]
	s_barrier
	s_setprio 0
	s_add_i32 s97, s97, 2
	s_add_u32 s95, s95, 0x100
	s_addc_u32 s96, s96, 0
	s_cmp_gt_u32 s97, 41
	s_mov_b64 s[50:51], s[52:53]
.LBB0_221:
	ds_read_b128 v[88:91], v233
	ds_read_b128 v[92:95], v233 offset:1024
	ds_read_b128 v[112:115], v233 offset:2048
	ds_read_b128 v[116:119], v233 offset:3072
	ds_read_b128 v[132:135], v234
	ds_read_b128 v[136:139], v234 offset:1024
	ds_read_b128 v[152:155], v234 offset:2048
	ds_read_b128 v[156:159], v234 offset:3072
	s_add_u32 s52, s50, 0x100
	s_addc_u32 s53, s51, 0
	s_cmp_eq_u32 s97, 40
	s_cselect_b32 s57, s9, s53
	s_cselect_b32 s56, s8, s52
	s_cselect_b32 s55, s41, s96
	s_cselect_b32 s54, s40, s95
	v_lshl_add_u64 v[216:217], s[50:51], 0, v[196:197]
	s_add_i32 m0, s67, 0xc000
	ds_read_b128 v[160:163], v235
	ds_read_b128 v[164:167], v235 offset:1024
	ds_read_b128 v[168:171], v235 offset:2048
	ds_read_b128 v[172:175], v235 offset:3072
	ds_read_b128 v[176:179], v235 offset:4096
	ds_read_b128 v[180:183], v235 offset:5120
	ds_read_b128 v[208:211], v235 offset:6144
	ds_read_b128 v[212:215], v235 offset:7168
	global_load_lds_dwordx4 v[216:217], off
	v_lshl_add_u64 v[216:217], s[50:51], 0, v[198:199]
	s_add_i32 m0, s67, 0xe000
	s_nop 0
	global_load_lds_dwordx4 v[216:217], off
	s_waitcnt vmcnt(8)
	s_waitcnt lgkmcnt(0)
	s_setprio 1
	s_barrier
	v_mfma_f32_16x16x32_bf16 v[148:151], v[88:91], v[160:163], v[148:151]
	v_mfma_f32_16x16x32_bf16 v[148:151], v[92:95], v[164:167], v[148:151]
	v_mfma_f32_16x16x32_bf16 v[144:147], v[112:115], v[160:163], v[144:147]
	v_mfma_f32_16x16x32_bf16 v[144:147], v[116:119], v[164:167], v[144:147]
	v_mfma_f32_16x16x32_bf16 v[124:127], v[88:91], v[168:171], v[124:127]
	v_mfma_f32_16x16x32_bf16 v[124:127], v[92:95], v[172:175], v[124:127]
	v_mfma_f32_16x16x32_bf16 v[120:123], v[112:115], v[168:171], v[120:123]
	v_mfma_f32_16x16x32_bf16 v[120:123], v[116:119], v[172:175], v[120:123]
	v_mfma_f32_16x16x32_bf16 v[100:103], v[88:91], v[176:179], v[100:103]
	v_mfma_f32_16x16x32_bf16 v[100:103], v[92:95], v[180:183], v[100:103]
	v_mfma_f32_16x16x32_bf16 v[96:99], v[112:115], v[176:179], v[96:99]
	v_mfma_f32_16x16x32_bf16 v[96:99], v[116:119], v[180:183], v[96:99]
	v_mfma_f32_16x16x32_bf16 v[76:79], v[88:91], v[208:211], v[76:79]
	v_mfma_f32_16x16x32_bf16 v[76:79], v[92:95], v[212:215], v[76:79]
	v_mfma_f32_16x16x32_bf16 v[72:75], v[112:115], v[208:211], v[72:75]
	v_mfma_f32_16x16x32_bf16 v[72:75], v[116:119], v[212:215], v[72:75]
	v_mfma_f32_16x16x32_bf16 v[140:143], v[132:135], v[160:163], v[140:143]
	v_mfma_f32_16x16x32_bf16 v[140:143], v[136:139], v[164:167], v[140:143]
	v_mfma_f32_16x16x32_bf16 v[128:131], v[152:155], v[160:163], v[128:131]
	v_mfma_f32_16x16x32_bf16 v[128:131], v[156:159], v[164:167], v[128:131]
	v_mfma_f32_16x16x32_bf16 v[108:111], v[132:135], v[168:171], v[108:111]
	v_mfma_f32_16x16x32_bf16 v[108:111], v[136:139], v[172:175], v[108:111]
	v_mfma_f32_16x16x32_bf16 v[104:107], v[152:155], v[168:171], v[104:107]
	v_mfma_f32_16x16x32_bf16 v[104:107], v[156:159], v[172:175], v[104:107]
	v_mfma_f32_16x16x32_bf16 v[84:87], v[132:135], v[176:179], v[84:87]
	v_mfma_f32_16x16x32_bf16 v[84:87], v[136:139], v[180:183], v[84:87]
	v_mfma_f32_16x16x32_bf16 v[80:83], v[152:155], v[176:179], v[80:83]
	v_mfma_f32_16x16x32_bf16 v[80:83], v[156:159], v[180:183], v[80:83]
	v_mfma_f32_16x16x32_bf16 v[68:71], v[132:135], v[208:211], v[68:71]
	v_mfma_f32_16x16x32_bf16 v[68:71], v[136:139], v[212:215], v[68:71]
	v_mfma_f32_16x16x32_bf16 v[64:67], v[152:155], v[208:211], v[64:67]
	v_mfma_f32_16x16x32_bf16 v[64:67], v[156:159], v[212:215], v[64:67]
	s_barrier
	s_setprio 0
	s_add_i32 s50, s82, s66
	v_lshl_add_u64 v[216:217], s[54:55], 0, v[186:187]
	s_mov_b32 m0, s50
	ds_read_b128 v[160:163], v235 offset:16384
	ds_read_b128 v[164:167], v235 offset:17408
	ds_read_b128 v[168:171], v235 offset:18432
	ds_read_b128 v[172:175], v235 offset:19456
	ds_read_b128 v[176:179], v235 offset:20480
	ds_read_b128 v[180:183], v235 offset:21504
	ds_read_b128 v[208:211], v235 offset:22528
	ds_read_b128 v[212:215], v235 offset:23552
	global_load_lds_dwordx4 v[216:217], off
	s_add_i32 m0, s50, 0x2000
	s_add_u32 s50, s54, 0xb0000
	v_lshl_add_u64 v[218:219], s[54:55], 0, v[190:191]
	s_addc_u32 s51, s55, 0
	s_add_i32 vcc_lo, s85, s66
	global_load_lds_dwordx4 v[218:219], off
	v_lshl_add_u64 v[220:221], s[50:51], 0, v[186:187]
	s_mov_b32 m0, vcc_lo
	v_lshl_add_u64 v[222:223], s[56:57], 0, v[188:189]
	global_load_lds_dwordx4 v[220:221], off
	v_lshl_add_u64 v[220:221], s[50:51], 0, v[190:191]
	s_add_i32 m0, vcc_lo, 0x2000
	s_nop 0
	global_load_lds_dwordx4 v[220:221], off
	v_lshl_add_u64 v[220:221], s[56:57], 0, v[184:185]
	s_mov_b32 m0, s67
	s_nop 0
	global_load_lds_dwordx4 v[220:221], off
	s_mov_b32 m0, s68
	s_nop 0
	global_load_lds_dwordx4 v[222:223], off
	s_waitcnt vmcnt(8)
	s_waitcnt lgkmcnt(0)
	s_setprio 1
	s_barrier
	v_mfma_f32_16x16x32_bf16 v[60:63], v[88:91], v[160:163], v[60:63]
	v_mfma_f32_16x16x32_bf16 v[60:63], v[92:95], v[164:167], v[60:63]
	v_mfma_f32_16x16x32_bf16 v[56:59], v[112:115], v[160:163], v[56:59]
	v_mfma_f32_16x16x32_bf16 v[56:59], v[116:119], v[164:167], v[56:59]
	v_mfma_f32_16x16x32_bf16 v[44:47], v[88:91], v[168:171], v[44:47]
	v_mfma_f32_16x16x32_bf16 v[44:47], v[92:95], v[172:175], v[44:47]
	v_mfma_f32_16x16x32_bf16 v[40:43], v[112:115], v[168:171], v[40:43]
	v_mfma_f32_16x16x32_bf16 v[40:43], v[116:119], v[172:175], v[40:43]
	v_mfma_f32_16x16x32_bf16 v[28:31], v[88:91], v[176:179], v[28:31]
	v_mfma_f32_16x16x32_bf16 v[28:31], v[92:95], v[180:183], v[28:31]
	v_mfma_f32_16x16x32_bf16 v[24:27], v[112:115], v[176:179], v[24:27]
	v_mfma_f32_16x16x32_bf16 v[24:27], v[116:119], v[180:183], v[24:27]
	v_mfma_f32_16x16x32_bf16 v[12:15], v[88:91], v[208:211], v[12:15]
	v_mfma_f32_16x16x32_bf16 v[12:15], v[92:95], v[212:215], v[12:15]
	v_mfma_f32_16x16x32_bf16 v[8:11], v[112:115], v[208:211], v[8:11]
	v_mfma_f32_16x16x32_bf16 v[8:11], v[116:119], v[212:215], v[8:11]
	v_mfma_f32_16x16x32_bf16 v[52:55], v[132:135], v[160:163], v[52:55]
	v_mfma_f32_16x16x32_bf16 v[52:55], v[136:139], v[164:167], v[52:55]
	v_mfma_f32_16x16x32_bf16 v[48:51], v[152:155], v[160:163], v[48:51]
	v_mfma_f32_16x16x32_bf16 v[48:51], v[156:159], v[164:167], v[48:51]
	v_mfma_f32_16x16x32_bf16 v[36:39], v[132:135], v[168:171], v[36:39]
	v_mfma_f32_16x16x32_bf16 v[36:39], v[136:139], v[172:175], v[36:39]
	v_mfma_f32_16x16x32_bf16 v[32:35], v[152:155], v[168:171], v[32:35]
	v_mfma_f32_16x16x32_bf16 v[32:35], v[156:159], v[172:175], v[32:35]
	v_mfma_f32_16x16x32_bf16 v[20:23], v[132:135], v[176:179], v[20:23]
	v_mfma_f32_16x16x32_bf16 v[20:23], v[136:139], v[180:183], v[20:23]
	v_mfma_f32_16x16x32_bf16 v[16:19], v[152:155], v[176:179], v[16:19]
	v_mfma_f32_16x16x32_bf16 v[16:19], v[156:159], v[180:183], v[16:19]
	v_mfma_f32_16x16x32_bf16 v[4:7], v[132:135], v[208:211], v[4:7]
	v_mfma_f32_16x16x32_bf16 v[4:7], v[136:139], v[212:215], v[4:7]
	v_mfma_f32_16x16x32_bf16 v[0:3], v[152:155], v[208:211], v[0:3]
	v_mfma_f32_16x16x32_bf16 v[0:3], v[156:159], v[212:215], v[0:3]
	s_barrier
	s_setprio 0
	s_add_i32 vcc_lo, 0, 0x18000
	s_add_i32 vcc_hi, 0, 0x1c000
	v_add_u32_e32 v116, vcc_lo, v230
	v_add_u32_e32 v156, vcc_hi, v230
	ds_read_b128 v[88:91], v116
	ds_read_b128 v[92:95], v116 offset:1024
	ds_read_b128 v[112:115], v116 offset:2048
	ds_read_b128 v[116:119], v116 offset:3072
	ds_read_b128 v[132:135], v156
	ds_read_b128 v[136:139], v156 offset:1024
	ds_read_b128 v[152:155], v156 offset:2048
	ds_read_b128 v[156:159], v156 offset:3072
	s_add_u32 s50, s56, 0xb0000
	s_addc_u32 s51, s57, 0
	s_mov_b32 m0, s69
	v_lshl_add_u64 v[224:225], s[50:51], 0, v[184:185]
	ds_read_b128 v[160:163], v235 offset:32768
	ds_read_b128 v[164:167], v235 offset:33792
	ds_read_b128 v[168:171], v235 offset:34816
	ds_read_b128 v[172:175], v235 offset:35840
	ds_read_b128 v[176:179], v235 offset:36864
	ds_read_b128 v[180:183], v235 offset:37888
	ds_read_b128 v[208:211], v235 offset:38912
	ds_read_b128 v[212:215], v235 offset:39936
	global_load_lds_dwordx4 v[224:225], off
	v_lshl_add_u64 v[224:225], s[50:51], 0, v[188:189]
	s_mov_b32 m0, s70
	s_nop 0
	global_load_lds_dwordx4 v[224:225], off
	s_waitcnt vmcnt(8)
	s_waitcnt lgkmcnt(0)
	s_setprio 1
	s_barrier
	v_mfma_f32_16x16x32_bf16 v[148:151], v[88:91], v[160:163], v[148:151]
	v_mfma_f32_16x16x32_bf16 v[148:151], v[92:95], v[164:167], v[148:151]
	v_mfma_f32_16x16x32_bf16 v[144:147], v[112:115], v[160:163], v[144:147]
	v_mfma_f32_16x16x32_bf16 v[144:147], v[116:119], v[164:167], v[144:147]
	v_mfma_f32_16x16x32_bf16 v[124:127], v[88:91], v[168:171], v[124:127]
	v_mfma_f32_16x16x32_bf16 v[124:127], v[92:95], v[172:175], v[124:127]
	v_mfma_f32_16x16x32_bf16 v[120:123], v[112:115], v[168:171], v[120:123]
	v_mfma_f32_16x16x32_bf16 v[120:123], v[116:119], v[172:175], v[120:123]
	v_mfma_f32_16x16x32_bf16 v[100:103], v[88:91], v[176:179], v[100:103]
	v_mfma_f32_16x16x32_bf16 v[100:103], v[92:95], v[180:183], v[100:103]
	v_mfma_f32_16x16x32_bf16 v[96:99], v[112:115], v[176:179], v[96:99]
	v_mfma_f32_16x16x32_bf16 v[96:99], v[116:119], v[180:183], v[96:99]
	v_mfma_f32_16x16x32_bf16 v[76:79], v[88:91], v[208:211], v[76:79]
	v_mfma_f32_16x16x32_bf16 v[76:79], v[92:95], v[212:215], v[76:79]
	v_mfma_f32_16x16x32_bf16 v[72:75], v[112:115], v[208:211], v[72:75]
	v_mfma_f32_16x16x32_bf16 v[72:75], v[116:119], v[212:215], v[72:75]
	v_mfma_f32_16x16x32_bf16 v[140:143], v[132:135], v[160:163], v[140:143]
	v_mfma_f32_16x16x32_bf16 v[140:143], v[136:139], v[164:167], v[140:143]
	v_mfma_f32_16x16x32_bf16 v[128:131], v[152:155], v[160:163], v[128:131]
	v_mfma_f32_16x16x32_bf16 v[128:131], v[156:159], v[164:167], v[128:131]
	v_mfma_f32_16x16x32_bf16 v[108:111], v[132:135], v[168:171], v[108:111]
	v_mfma_f32_16x16x32_bf16 v[108:111], v[136:139], v[172:175], v[108:111]
	v_mfma_f32_16x16x32_bf16 v[104:107], v[152:155], v[168:171], v[104:107]
	v_mfma_f32_16x16x32_bf16 v[104:107], v[156:159], v[172:175], v[104:107]
	v_mfma_f32_16x16x32_bf16 v[84:87], v[132:135], v[176:179], v[84:87]
	v_mfma_f32_16x16x32_bf16 v[84:87], v[136:139], v[180:183], v[84:87]
	v_mfma_f32_16x16x32_bf16 v[80:83], v[152:155], v[176:179], v[80:83]
	v_mfma_f32_16x16x32_bf16 v[80:83], v[156:159], v[180:183], v[80:83]
	v_mfma_f32_16x16x32_bf16 v[68:71], v[132:135], v[208:211], v[68:71]
	v_mfma_f32_16x16x32_bf16 v[68:71], v[136:139], v[212:215], v[68:71]
	v_mfma_f32_16x16x32_bf16 v[64:67], v[152:155], v[208:211], v[64:67]
	v_mfma_f32_16x16x32_bf16 v[64:67], v[156:159], v[212:215], v[64:67]
	s_barrier
	s_setprio 0
	s_add_i32 s50, vcc_lo, s66
	v_lshl_add_u64 v[216:217], v[216:217], 0, s[46:47]
	s_mov_b32 m0, s50
	ds_read_b128 v[160:163], v235 offset:49152
	ds_read_b128 v[164:167], v235 offset:50176
	ds_read_b128 v[168:171], v235 offset:51200
	ds_read_b128 v[172:175], v235 offset:52224
	ds_read_b128 v[176:179], v235 offset:53248
	ds_read_b128 v[180:183], v235 offset:54272
	ds_read_b128 v[208:211], v235 offset:55296
	ds_read_b128 v[212:215], v235 offset:56320
	global_load_lds_dwordx4 v[216:217], off
	s_add_i32 m0, s50, 0x2000
	s_add_u32 s50, s54, 0xb0080
	v_lshl_add_u64 v[216:217], v[218:219], 0, s[46:47]
	s_addc_u32 s51, s55, 0
	s_add_i32 s54, vcc_hi, s66
	global_load_lds_dwordx4 v[216:217], off
	v_lshl_add_u64 v[216:217], s[50:51], 0, v[186:187]
	s_mov_b32 m0, s54
	s_nop 0
	global_load_lds_dwordx4 v[216:217], off
	v_lshl_add_u64 v[216:217], s[50:51], 0, v[190:191]
	s_add_i32 m0, s54, 0x2000
	s_nop 0
	global_load_lds_dwordx4 v[216:217], off
	v_lshl_add_u64 v[216:217], v[220:221], 0, s[46:47]
	s_mov_b32 m0, s74
	s_nop 0
	global_load_lds_dwordx4 v[216:217], off
	v_lshl_add_u64 v[216:217], v[222:223], 0, s[46:47]
	s_mov_b32 m0, s75
	s_nop 0
	global_load_lds_dwordx4 v[216:217], off
	s_waitcnt vmcnt(8)
	s_waitcnt lgkmcnt(0)
	s_setprio 1
	s_barrier
	v_mfma_f32_16x16x32_bf16 v[60:63], v[88:91], v[160:163], v[60:63]
	v_mfma_f32_16x16x32_bf16 v[60:63], v[92:95], v[164:167], v[60:63]
	v_mfma_f32_16x16x32_bf16 v[56:59], v[112:115], v[160:163], v[56:59]
	v_mfma_f32_16x16x32_bf16 v[56:59], v[116:119], v[164:167], v[56:59]
	v_mfma_f32_16x16x32_bf16 v[44:47], v[88:91], v[168:171], v[44:47]
	v_mfma_f32_16x16x32_bf16 v[44:47], v[92:95], v[172:175], v[44:47]
	v_mfma_f32_16x16x32_bf16 v[40:43], v[112:115], v[168:171], v[40:43]
	v_mfma_f32_16x16x32_bf16 v[40:43], v[116:119], v[172:175], v[40:43]
	v_mfma_f32_16x16x32_bf16 v[28:31], v[88:91], v[176:179], v[28:31]
	v_mfma_f32_16x16x32_bf16 v[28:31], v[92:95], v[180:183], v[28:31]
	v_mfma_f32_16x16x32_bf16 v[24:27], v[112:115], v[176:179], v[24:27]
	v_mfma_f32_16x16x32_bf16 v[24:27], v[116:119], v[180:183], v[24:27]
	v_mfma_f32_16x16x32_bf16 v[12:15], v[88:91], v[208:211], v[12:15]
	v_mfma_f32_16x16x32_bf16 v[12:15], v[92:95], v[212:215], v[12:15]
	v_mfma_f32_16x16x32_bf16 v[8:11], v[112:115], v[208:211], v[8:11]
	v_mfma_f32_16x16x32_bf16 v[8:11], v[116:119], v[212:215], v[8:11]
	v_mfma_f32_16x16x32_bf16 v[52:55], v[132:135], v[160:163], v[52:55]
	v_mfma_f32_16x16x32_bf16 v[52:55], v[136:139], v[164:167], v[52:55]
	v_mfma_f32_16x16x32_bf16 v[48:51], v[152:155], v[160:163], v[48:51]
	v_mfma_f32_16x16x32_bf16 v[48:51], v[156:159], v[164:167], v[48:51]
	v_mfma_f32_16x16x32_bf16 v[36:39], v[132:135], v[168:171], v[36:39]
	v_mfma_f32_16x16x32_bf16 v[36:39], v[136:139], v[172:175], v[36:39]
	v_mfma_f32_16x16x32_bf16 v[32:35], v[152:155], v[168:171], v[32:35]
	v_mfma_f32_16x16x32_bf16 v[32:35], v[156:159], v[172:175], v[32:35]
	v_mfma_f32_16x16x32_bf16 v[20:23], v[132:135], v[176:179], v[20:23]
	v_mfma_f32_16x16x32_bf16 v[20:23], v[136:139], v[180:183], v[20:23]
	v_mfma_f32_16x16x32_bf16 v[16:19], v[152:155], v[176:179], v[16:19]
	v_mfma_f32_16x16x32_bf16 v[16:19], v[156:159], v[180:183], v[16:19]
	v_mfma_f32_16x16x32_bf16 v[4:7], v[132:135], v[208:211], v[4:7]
	v_mfma_f32_16x16x32_bf16 v[4:7], v[136:139], v[212:215], v[4:7]
	v_mfma_f32_16x16x32_bf16 v[0:3], v[152:155], v[208:211], v[0:3]
	v_mfma_f32_16x16x32_bf16 v[0:3], v[156:159], v[212:215], v[0:3]
	s_barrier
	s_setprio 0
	s_add_i32 s97, s97, 2
	s_add_u32 s95, s95, 0x100
	s_addc_u32 s96, s96, 0
	s_cmp_gt_u32 s97, 41
	s_mov_b64 s[50:51], s[52:53]
	s_cbranch_scc0 .LBB0_221
	s_and_b64 vcc, exec, s[48:49]
	s_cbranch_vccz .LBB0_224
	s_barrier

.LBB0_312:
	s_ashr_i32 s43, s42, 31
	s_lshl_b64 s[46:47], s[42:43], 19
	s_add_u32 s46, s62, s46
	s_addc_u32 s47, s63, s47
	s_and_b64 s[48:49], s[4:5], exec
	s_cselect_b32 s10, s47, s53
	s_cselect_b32 s43, s46, s52
	s_ashr_i32 s45, s44, 31
	s_lshl_b64 s[48:49], s[44:45], 19
	s_add_u32 s48, s70, s48
	s_addc_u32 s49, s71, s49
	s_and_b64 s[56:57], s[4:5], exec
	s_cselect_b32 s45, s49, s55
	s_cselect_b32 s51, s48, s54
	s_add_u32 s52, s52, 0x40080
	s_addc_u32 s53, s53, 0
	s_add_u32 s67, s54, 0x100
	s_addc_u32 s68, s55, 0
	s_mov_b32 s69, -2
	ds_read_b128 v[128:131], v179
	ds_read_b128 v[132:135], v179 offset:1024
	ds_read_b128 v[136:139], v179 offset:2048
	ds_read_b128 v[140:143], v179 offset:3072
	ds_read_b128 v[188:191], v181
	ds_read_b128 v[192:195], v181 offset:1024
	ds_read_b128 v[196:199], v181 offset:2048
	ds_read_b128 v[200:203], v181 offset:3072
	s_add_u32 s54, s52, 0xfffc0080
	s_addc_u32 s55, s53, -1
	s_cmp_eq_u32 s69, 12
	s_cselect_b32 s57, s10, s55
	s_cselect_b32 s56, s43, s54
	s_cselect_b32 s55, s45, s68
	s_cselect_b32 s54, s51, s67
	v_lshl_add_u64 v[238:239], s[52:53], 0, v[162:163]
	s_add_i32 m0, s75, 0xc000
	ds_read_b128 v[204:207], v183
	ds_read_b128 v[208:211], v183 offset:1024
	ds_read_b128 v[212:215], v183 offset:2048
	ds_read_b128 v[216:219], v183 offset:3072
	ds_read_b128 v[220:223], v183 offset:4096
	ds_read_b128 v[224:227], v183 offset:5120
	ds_read_b128 v[230:233], v183 offset:6144
	ds_read_b128 v[234:237], v183 offset:7168
	global_load_lds_dwordx4 v[238:239], off
	v_lshl_add_u64 v[238:239], s[52:53], 0, v[164:165]
	s_add_i32 m0, s75, 0xe000
	s_nop 0
	global_load_lds_dwordx4 v[238:239], off
	s_waitcnt vmcnt(8)
	s_waitcnt lgkmcnt(0)
	s_setprio 1
	s_barrier
	v_mfma_f32_16x16x32_bf16 v[124:127], v[128:131], v[204:207], 0
	v_mfma_f32_16x16x32_bf16 v[124:127], v[132:135], v[208:211], v[124:127]
	v_mfma_f32_16x16x32_bf16 v[120:123], v[136:139], v[204:207], 0
	v_mfma_f32_16x16x32_bf16 v[120:123], v[140:143], v[208:211], v[120:123]
	v_mfma_f32_16x16x32_bf16 v[108:111], v[128:131], v[212:215], 0
	v_mfma_f32_16x16x32_bf16 v[108:111], v[132:135], v[216:219], v[108:111]
	v_mfma_f32_16x16x32_bf16 v[104:107], v[136:139], v[212:215], 0
	v_mfma_f32_16x16x32_bf16 v[104:107], v[140:143], v[216:219], v[104:107]
	v_mfma_f32_16x16x32_bf16 v[92:95], v[128:131], v[220:223], 0
	v_mfma_f32_16x16x32_bf16 v[92:95], v[132:135], v[224:227], v[92:95]
	v_mfma_f32_16x16x32_bf16 v[88:91], v[136:139], v[220:223], 0
	v_mfma_f32_16x16x32_bf16 v[88:91], v[140:143], v[224:227], v[88:91]
	v_mfma_f32_16x16x32_bf16 v[76:79], v[128:131], v[230:233], 0
	v_mfma_f32_16x16x32_bf16 v[76:79], v[132:135], v[234:237], v[76:79]
	v_mfma_f32_16x16x32_bf16 v[72:75], v[136:139], v[230:233], 0
	v_mfma_f32_16x16x32_bf16 v[72:75], v[140:143], v[234:237], v[72:75]
	v_mfma_f32_16x16x32_bf16 v[116:119], v[188:191], v[204:207], 0
	v_mfma_f32_16x16x32_bf16 v[116:119], v[192:195], v[208:211], v[116:119]
	v_mfma_f32_16x16x32_bf16 v[112:115], v[196:199], v[204:207], 0
	v_mfma_f32_16x16x32_bf16 v[112:115], v[200:203], v[208:211], v[112:115]
	v_mfma_f32_16x16x32_bf16 v[100:103], v[188:191], v[212:215], 0
	v_mfma_f32_16x16x32_bf16 v[100:103], v[192:195], v[216:219], v[100:103]
	v_mfma_f32_16x16x32_bf16 v[96:99], v[196:199], v[212:215], 0
	v_mfma_f32_16x16x32_bf16 v[96:99], v[200:203], v[216:219], v[96:99]
	v_mfma_f32_16x16x32_bf16 v[84:87], v[188:191], v[220:223], 0
	v_mfma_f32_16x16x32_bf16 v[84:87], v[192:195], v[224:227], v[84:87]
	v_mfma_f32_16x16x32_bf16 v[80:83], v[196:199], v[220:223], 0
	v_mfma_f32_16x16x32_bf16 v[80:83], v[200:203], v[224:227], v[80:83]
	v_mfma_f32_16x16x32_bf16 v[68:71], v[188:191], v[230:233], 0
	v_mfma_f32_16x16x32_bf16 v[68:71], v[192:195], v[234:237], v[68:71]
	v_mfma_f32_16x16x32_bf16 v[64:67], v[196:199], v[230:233], 0
	v_mfma_f32_16x16x32_bf16 v[64:67], v[200:203], v[234:237], v[64:67]
	s_barrier
	s_setprio 0
	s_add_i32 vcc_lo, s92, s72
	v_lshl_add_u64 v[238:239], s[54:55], 0, v[148:149]
	s_mov_b32 m0, vcc_lo
	ds_read_b128 v[204:207], v183 offset:16384
	ds_read_b128 v[208:211], v183 offset:17408
	ds_read_b128 v[212:215], v183 offset:18432
	ds_read_b128 v[216:219], v183 offset:19456
	ds_read_b128 v[220:223], v183 offset:20480
	ds_read_b128 v[224:227], v183 offset:21504
	ds_read_b128 v[230:233], v183 offset:22528
	ds_read_b128 v[234:237], v183 offset:23552
	global_load_lds_dwordx4 v[238:239], off
	s_add_i32 m0, vcc_lo, 0x2000
	s_add_u32 vcc_lo, s54, 0x40000
	v_lshl_add_u64 v[240:241], s[54:55], 0, v[144:145]
	s_addc_u32 vcc_hi, s55, 0
	s_add_i32 s83, s93, s72
	global_load_lds_dwordx4 v[240:241], off
	v_lshl_add_u64 v[242:243], vcc, 0, v[148:149]
	s_mov_b32 m0, s83
	v_lshl_add_u64 v[244:245], s[56:57], 0, v[146:147]
	global_load_lds_dwordx4 v[242:243], off
	v_lshl_add_u64 v[242:243], vcc, 0, v[144:145]
	s_add_i32 m0, s83, 0x2000
	s_nop 0
	global_load_lds_dwordx4 v[242:243], off
	v_lshl_add_u64 v[242:243], s[56:57], 0, v[150:151]
	s_mov_b32 m0, s75
	s_nop 0
	global_load_lds_dwordx4 v[242:243], off
	s_mov_b32 m0, s76
	s_nop 0
	global_load_lds_dwordx4 v[244:245], off
	s_waitcnt vmcnt(8)
	s_waitcnt lgkmcnt(0)
	s_setprio 1
	s_barrier
	v_mfma_f32_16x16x32_bf16 v[60:63], v[128:131], v[204:207], 0
	v_mfma_f32_16x16x32_bf16 v[60:63], v[132:135], v[208:211], v[60:63]
	v_mfma_f32_16x16x32_bf16 v[56:59], v[136:139], v[204:207], 0
	v_mfma_f32_16x16x32_bf16 v[56:59], v[140:143], v[208:211], v[56:59]
	v_mfma_f32_16x16x32_bf16 v[44:47], v[128:131], v[212:215], 0
	v_mfma_f32_16x16x32_bf16 v[44:47], v[132:135], v[216:219], v[44:47]
	v_mfma_f32_16x16x32_bf16 v[40:43], v[136:139], v[212:215], 0
	v_mfma_f32_16x16x32_bf16 v[40:43], v[140:143], v[216:219], v[40:43]
	v_mfma_f32_16x16x32_bf16 v[28:31], v[128:131], v[220:223], 0
	v_mfma_f32_16x16x32_bf16 v[28:31], v[132:135], v[224:227], v[28:31]
	v_mfma_f32_16x16x32_bf16 v[24:27], v[136:139], v[220:223], 0
	v_mfma_f32_16x16x32_bf16 v[24:27], v[140:143], v[224:227], v[24:27]
	v_mfma_f32_16x16x32_bf16 v[12:15], v[128:131], v[230:233], 0
	v_mfma_f32_16x16x32_bf16 v[12:15], v[132:135], v[234:237], v[12:15]
	v_mfma_f32_16x16x32_bf16 v[8:11], v[136:139], v[230:233], 0
	v_mfma_f32_16x16x32_bf16 v[8:11], v[140:143], v[234:237], v[8:11]
	v_mfma_f32_16x16x32_bf16 v[52:55], v[188:191], v[204:207], 0
	v_mfma_f32_16x16x32_bf16 v[52:55], v[192:195], v[208:211], v[52:55]
	v_mfma_f32_16x16x32_bf16 v[48:51], v[196:199], v[204:207], 0
	v_mfma_f32_16x16x32_bf16 v[48:51], v[200:203], v[208:211], v[48:51]
	v_mfma_f32_16x16x32_bf16 v[36:39], v[188:191], v[212:215], 0
	v_mfma_f32_16x16x32_bf16 v[36:39], v[192:195], v[216:219], v[36:39]
	v_mfma_f32_16x16x32_bf16 v[32:35], v[196:199], v[212:215], 0
	v_mfma_f32_16x16x32_bf16 v[32:35], v[200:203], v[216:219], v[32:35]
	v_mfma_f32_16x16x32_bf16 v[20:23], v[188:191], v[220:223], 0
	v_mfma_f32_16x16x32_bf16 v[20:23], v[192:195], v[224:227], v[20:23]
	v_mfma_f32_16x16x32_bf16 v[16:19], v[196:199], v[220:223], 0
	v_mfma_f32_16x16x32_bf16 v[16:19], v[200:203], v[224:227], v[16:19]
	v_mfma_f32_16x16x32_bf16 v[4:7], v[188:191], v[230:233], 0
	v_mfma_f32_16x16x32_bf16 v[4:7], v[192:195], v[234:237], v[4:7]
	v_mfma_f32_16x16x32_bf16 v[0:3], v[196:199], v[230:233], 0
	v_mfma_f32_16x16x32_bf16 v[0:3], v[200:203], v[234:237], v[0:3]
	s_barrier
	s_setprio 0
	s_add_i32 s83, 0, 0x18000
	s_add_i32 vcc_lo, 0, 0x1c000
	v_add_u32_e32 v140, s83, v157
	v_add_u32_e32 v171, vcc_lo, v157
	ds_read_b128 v[128:131], v140
	ds_read_b128 v[132:135], v140 offset:1024
	ds_read_b128 v[136:139], v140 offset:2048
	ds_read_b128 v[140:143], v140 offset:3072
	ds_read_b128 v[188:191], v171
	ds_read_b128 v[192:195], v171 offset:1024
	ds_read_b128 v[196:199], v171 offset:2048
	ds_read_b128 v[200:203], v171 offset:3072
	s_add_u32 s56, s56, 0x40000
	s_addc_u32 s57, s57, 0
	s_mov_b32 m0, s77
	v_lshl_add_u64 v[246:247], s[56:57], 0, v[150:151]
	ds_read_b128 v[204:207], v183 offset:32768
	ds_read_b128 v[208:211], v183 offset:33792
	ds_read_b128 v[212:215], v183 offset:34816
	ds_read_b128 v[216:219], v183 offset:35840
	ds_read_b128 v[220:223], v183 offset:36864
	ds_read_b128 v[224:227], v183 offset:37888
	ds_read_b128 v[230:233], v183 offset:38912
	ds_read_b128 v[234:237], v183 offset:39936
	global_load_lds_dwordx4 v[246:247], off
	v_lshl_add_u64 v[246:247], s[56:57], 0, v[146:147]
	s_mov_b32 m0, s78
	s_nop 0
	global_load_lds_dwordx4 v[246:247], off
	s_waitcnt vmcnt(8)
	s_waitcnt lgkmcnt(0)
	s_setprio 1
	s_barrier
	v_mfma_f32_16x16x32_bf16 v[124:127], v[128:131], v[204:207], v[124:127]
	v_mfma_f32_16x16x32_bf16 v[124:127], v[132:135], v[208:211], v[124:127]
	v_mfma_f32_16x16x32_bf16 v[120:123], v[136:139], v[204:207], v[120:123]
	v_mfma_f32_16x16x32_bf16 v[120:123], v[140:143], v[208:211], v[120:123]
	v_mfma_f32_16x16x32_bf16 v[108:111], v[128:131], v[212:215], v[108:111]
	v_mfma_f32_16x16x32_bf16 v[108:111], v[132:135], v[216:219], v[108:111]
	v_mfma_f32_16x16x32_bf16 v[104:107], v[136:139], v[212:215], v[104:107]
	v_mfma_f32_16x16x32_bf16 v[104:107], v[140:143], v[216:219], v[104:107]
	v_mfma_f32_16x16x32_bf16 v[92:95], v[128:131], v[220:223], v[92:95]
	v_mfma_f32_16x16x32_bf16 v[92:95], v[132:135], v[224:227], v[92:95]
	v_mfma_f32_16x16x32_bf16 v[88:91], v[136:139], v[220:223], v[88:91]
	v_mfma_f32_16x16x32_bf16 v[88:91], v[140:143], v[224:227], v[88:91]
	v_mfma_f32_16x16x32_bf16 v[76:79], v[128:131], v[230:233], v[76:79]
	v_mfma_f32_16x16x32_bf16 v[76:79], v[132:135], v[234:237], v[76:79]
	v_mfma_f32_16x16x32_bf16 v[72:75], v[136:139], v[230:233], v[72:75]
	v_mfma_f32_16x16x32_bf16 v[72:75], v[140:143], v[234:237], v[72:75]
	v_mfma_f32_16x16x32_bf16 v[116:119], v[188:191], v[204:207], v[116:119]
	v_mfma_f32_16x16x32_bf16 v[116:119], v[192:195], v[208:211], v[116:119]
	v_mfma_f32_16x16x32_bf16 v[112:115], v[196:199], v[204:207], v[112:115]
	v_mfma_f32_16x16x32_bf16 v[112:115], v[200:203], v[208:211], v[112:115]
	v_mfma_f32_16x16x32_bf16 v[100:103], v[188:191], v[212:215], v[100:103]
	v_mfma_f32_16x16x32_bf16 v[100:103], v[192:195], v[216:219], v[100:103]
	v_mfma_f32_16x16x32_bf16 v[96:99], v[196:199], v[212:215], v[96:99]
	v_mfma_f32_16x16x32_bf16 v[96:99], v[200:203], v[216:219], v[96:99]
	v_mfma_f32_16x16x32_bf16 v[84:87], v[188:191], v[220:223], v[84:87]
	v_mfma_f32_16x16x32_bf16 v[84:87], v[192:195], v[224:227], v[84:87]
	v_mfma_f32_16x16x32_bf16 v[80:83], v[196:199], v[220:223], v[80:83]
	v_mfma_f32_16x16x32_bf16 v[80:83], v[200:203], v[224:227], v[80:83]
	v_mfma_f32_16x16x32_bf16 v[68:71], v[188:191], v[230:233], v[68:71]
	v_mfma_f32_16x16x32_bf16 v[68:71], v[192:195], v[234:237], v[68:71]
	v_mfma_f32_16x16x32_bf16 v[64:67], v[196:199], v[230:233], v[64:67]
	v_mfma_f32_16x16x32_bf16 v[64:67], v[200:203], v[234:237], v[64:67]
	s_barrier
	s_setprio 0
	s_add_i32 s56, s83, s72
	v_lshl_add_u64 v[238:239], v[238:239], 0, s[38:39]
	s_mov_b32 m0, s56
	ds_read_b128 v[204:207], v183 offset:49152
	ds_read_b128 v[208:211], v183 offset:50176
	ds_read_b128 v[212:215], v183 offset:51200
	ds_read_b128 v[216:219], v183 offset:52224
	ds_read_b128 v[220:223], v183 offset:53248
	ds_read_b128 v[224:227], v183 offset:54272
	ds_read_b128 v[230:233], v183 offset:55296
	ds_read_b128 v[234:237], v183 offset:56320
	global_load_lds_dwordx4 v[238:239], off
	s_add_i32 m0, s56, 0x2000
	s_add_u32 s54, s54, 0x40080
	v_lshl_add_u64 v[238:239], v[240:241], 0, s[38:39]
	s_addc_u32 s55, s55, 0
	s_add_i32 s56, vcc_lo, s72
	global_load_lds_dwordx4 v[238:239], off
	v_lshl_add_u64 v[238:239], s[54:55], 0, v[148:149]
	s_mov_b32 m0, s56
	s_nop 0
	global_load_lds_dwordx4 v[238:239], off
	v_lshl_add_u64 v[238:239], s[54:55], 0, v[144:145]
	s_add_i32 m0, s56, 0x2000
	s_nop 0
	global_load_lds_dwordx4 v[238:239], off
	v_lshl_add_u64 v[238:239], v[242:243], 0, s[38:39]
	s_mov_b32 m0, s87
	s_nop 0
	global_load_lds_dwordx4 v[238:239], off
	v_lshl_add_u64 v[238:239], v[244:245], 0, s[38:39]
	s_mov_b32 m0, s88
	s_nop 0
	global_load_lds_dwordx4 v[238:239], off
	s_waitcnt vmcnt(8)
	s_waitcnt lgkmcnt(0)
	s_setprio 1
	s_barrier
	v_mfma_f32_16x16x32_bf16 v[60:63], v[128:131], v[204:207], v[60:63]
	v_mfma_f32_16x16x32_bf16 v[60:63], v[132:135], v[208:211], v[60:63]
	v_mfma_f32_16x16x32_bf16 v[56:59], v[136:139], v[204:207], v[56:59]
	v_mfma_f32_16x16x32_bf16 v[56:59], v[140:143], v[208:211], v[56:59]
	v_mfma_f32_16x16x32_bf16 v[44:47], v[128:131], v[212:215], v[44:47]
	v_mfma_f32_16x16x32_bf16 v[44:47], v[132:135], v[216:219], v[44:47]
	v_mfma_f32_16x16x32_bf16 v[40:43], v[136:139], v[212:215], v[40:43]
	v_mfma_f32_16x16x32_bf16 v[40:43], v[140:143], v[216:219], v[40:43]
	v_mfma_f32_16x16x32_bf16 v[28:31], v[128:131], v[220:223], v[28:31]
	v_mfma_f32_16x16x32_bf16 v[28:31], v[132:135], v[224:227], v[28:31]
	v_mfma_f32_16x16x32_bf16 v[24:27], v[136:139], v[220:223], v[24:27]
	v_mfma_f32_16x16x32_bf16 v[24:27], v[140:143], v[224:227], v[24:27]
	v_mfma_f32_16x16x32_bf16 v[12:15], v[128:131], v[230:233], v[12:15]
	v_mfma_f32_16x16x32_bf16 v[12:15], v[132:135], v[234:237], v[12:15]
	v_mfma_f32_16x16x32_bf16 v[8:11], v[136:139], v[230:233], v[8:11]
	v_mfma_f32_16x16x32_bf16 v[8:11], v[140:143], v[234:237], v[8:11]
	v_mfma_f32_16x16x32_bf16 v[52:55], v[188:191], v[204:207], v[52:55]
	v_mfma_f32_16x16x32_bf16 v[52:55], v[192:195], v[208:211], v[52:55]
	v_mfma_f32_16x16x32_bf16 v[48:51], v[196:199], v[204:207], v[48:51]
	v_mfma_f32_16x16x32_bf16 v[48:51], v[200:203], v[208:211], v[48:51]
	v_mfma_f32_16x16x32_bf16 v[36:39], v[188:191], v[212:215], v[36:39]
	v_mfma_f32_16x16x32_bf16 v[36:39], v[192:195], v[216:219], v[36:39]
	v_mfma_f32_16x16x32_bf16 v[32:35], v[196:199], v[212:215], v[32:35]
	v_mfma_f32_16x16x32_bf16 v[32:35], v[200:203], v[216:219], v[32:35]
	v_mfma_f32_16x16x32_bf16 v[20:23], v[188:191], v[220:223], v[20:23]
	v_mfma_f32_16x16x32_bf16 v[20:23], v[192:195], v[224:227], v[20:23]
	v_mfma_f32_16x16x32_bf16 v[16:19], v[196:199], v[220:223], v[16:19]
	v_mfma_f32_16x16x32_bf16 v[16:19], v[200:203], v[224:227], v[16:19]
	v_mfma_f32_16x16x32_bf16 v[4:7], v[188:191], v[230:233], v[4:7]
	v_mfma_f32_16x16x32_bf16 v[4:7], v[192:195], v[234:237], v[4:7]
	v_mfma_f32_16x16x32_bf16 v[0:3], v[196:199], v[230:233], v[0:3]
	v_mfma_f32_16x16x32_bf16 v[0:3], v[200:203], v[234:237], v[0:3]
	s_barrier
	s_setprio 0
	s_add_i32 s69, s69, 2
	s_add_u32 s52, s52, 0x100
	s_addc_u32 s53, s53, 0
	s_add_u32 s67, s67, 0x100
	s_addc_u32 s68, s68, 0
	s_cmp_gt_u32 s69, 13
.LBB0_313:
	ds_read_b128 v[128:131], v179
	ds_read_b128 v[132:135], v179 offset:1024
	ds_read_b128 v[136:139], v179 offset:2048
	ds_read_b128 v[140:143], v179 offset:3072
	ds_read_b128 v[188:191], v181
	ds_read_b128 v[192:195], v181 offset:1024
	ds_read_b128 v[196:199], v181 offset:2048
	ds_read_b128 v[200:203], v181 offset:3072
	s_add_u32 s54, s52, 0xfffc0080
	s_addc_u32 s55, s53, -1
	s_cmp_eq_u32 s69, 12
	s_cselect_b32 s57, s10, s55
	s_cselect_b32 s56, s43, s54
	s_cselect_b32 s55, s45, s68
	s_cselect_b32 s54, s51, s67
	v_lshl_add_u64 v[238:239], s[52:53], 0, v[162:163]
	s_add_i32 m0, s75, 0xc000
	ds_read_b128 v[204:207], v183
	ds_read_b128 v[208:211], v183 offset:1024
	ds_read_b128 v[212:215], v183 offset:2048
	ds_read_b128 v[216:219], v183 offset:3072
	ds_read_b128 v[220:223], v183 offset:4096
	ds_read_b128 v[224:227], v183 offset:5120
	ds_read_b128 v[230:233], v183 offset:6144
	ds_read_b128 v[234:237], v183 offset:7168
	global_load_lds_dwordx4 v[238:239], off
	v_lshl_add_u64 v[238:239], s[52:53], 0, v[164:165]
	s_add_i32 m0, s75, 0xe000
	s_nop 0
	global_load_lds_dwordx4 v[238:239], off
	s_waitcnt vmcnt(8)
	s_waitcnt lgkmcnt(0)
	s_setprio 1
	s_barrier
	v_mfma_f32_16x16x32_bf16 v[124:127], v[128:131], v[204:207], v[124:127]
	v_mfma_f32_16x16x32_bf16 v[124:127], v[132:135], v[208:211], v[124:127]
	v_mfma_f32_16x16x32_bf16 v[120:123], v[136:139], v[204:207], v[120:123]
	v_mfma_f32_16x16x32_bf16 v[120:123], v[140:143], v[208:211], v[120:123]
	v_mfma_f32_16x16x32_bf16 v[108:111], v[128:131], v[212:215], v[108:111]
	v_mfma_f32_16x16x32_bf16 v[108:111], v[132:135], v[216:219], v[108:111]
	v_mfma_f32_16x16x32_bf16 v[104:107], v[136:139], v[212:215], v[104:107]
	v_mfma_f32_16x16x32_bf16 v[104:107], v[140:143], v[216:219], v[104:107]
	v_mfma_f32_16x16x32_bf16 v[92:95], v[128:131], v[220:223], v[92:95]
	v_mfma_f32_16x16x32_bf16 v[92:95], v[132:135], v[224:227], v[92:95]
	v_mfma_f32_16x16x32_bf16 v[88:91], v[136:139], v[220:223], v[88:91]
	v_mfma_f32_16x16x32_bf16 v[88:91], v[140:143], v[224:227], v[88:91]
	v_mfma_f32_16x16x32_bf16 v[76:79], v[128:131], v[230:233], v[76:79]
	v_mfma_f32_16x16x32_bf16 v[76:79], v[132:135], v[234:237], v[76:79]
	v_mfma_f32_16x16x32_bf16 v[72:75], v[136:139], v[230:233], v[72:75]
	v_mfma_f32_16x16x32_bf16 v[72:75], v[140:143], v[234:237], v[72:75]
	v_mfma_f32_16x16x32_bf16 v[116:119], v[188:191], v[204:207], v[116:119]
	v_mfma_f32_16x16x32_bf16 v[116:119], v[192:195], v[208:211], v[116:119]
	v_mfma_f32_16x16x32_bf16 v[112:115], v[196:199], v[204:207], v[112:115]
	v_mfma_f32_16x16x32_bf16 v[112:115], v[200:203], v[208:211], v[112:115]
	v_mfma_f32_16x16x32_bf16 v[100:103], v[188:191], v[212:215], v[100:103]
	v_mfma_f32_16x16x32_bf16 v[100:103], v[192:195], v[216:219], v[100:103]
	v_mfma_f32_16x16x32_bf16 v[96:99], v[196:199], v[212:215], v[96:99]
	v_mfma_f32_16x16x32_bf16 v[96:99], v[200:203], v[216:219], v[96:99]
	v_mfma_f32_16x16x32_bf16 v[84:87], v[188:191], v[220:223], v[84:87]
	v_mfma_f32_16x16x32_bf16 v[84:87], v[192:195], v[224:227], v[84:87]
	v_mfma_f32_16x16x32_bf16 v[80:83], v[196:199], v[220:223], v[80:83]
	v_mfma_f32_16x16x32_bf16 v[80:83], v[200:203], v[224:227], v[80:83]
	v_mfma_f32_16x16x32_bf16 v[68:71], v[188:191], v[230:233], v[68:71]
	v_mfma_f32_16x16x32_bf16 v[68:71], v[192:195], v[234:237], v[68:71]
	v_mfma_f32_16x16x32_bf16 v[64:67], v[196:199], v[230:233], v[64:67]
	v_mfma_f32_16x16x32_bf16 v[64:67], v[200:203], v[234:237], v[64:67]
	s_barrier
	s_setprio 0
	s_add_i32 vcc_lo, s92, s72
	v_lshl_add_u64 v[238:239], s[54:55], 0, v[148:149]
	s_mov_b32 m0, vcc_lo
	ds_read_b128 v[204:207], v183 offset:16384
	ds_read_b128 v[208:211], v183 offset:17408
	ds_read_b128 v[212:215], v183 offset:18432
	ds_read_b128 v[216:219], v183 offset:19456
	ds_read_b128 v[220:223], v183 offset:20480
	ds_read_b128 v[224:227], v183 offset:21504
	ds_read_b128 v[230:233], v183 offset:22528
	ds_read_b128 v[234:237], v183 offset:23552
	global_load_lds_dwordx4 v[238:239], off
	s_add_i32 m0, vcc_lo, 0x2000
	s_add_u32 vcc_lo, s54, 0x40000
	v_lshl_add_u64 v[240:241], s[54:55], 0, v[144:145]
	s_addc_u32 vcc_hi, s55, 0
	s_add_i32 s83, s93, s72
	global_load_lds_dwordx4 v[240:241], off
	v_lshl_add_u64 v[242:243], vcc, 0, v[148:149]
	s_mov_b32 m0, s83
	v_lshl_add_u64 v[244:245], s[56:57], 0, v[146:147]
	global_load_lds_dwordx4 v[242:243], off
	v_lshl_add_u64 v[242:243], vcc, 0, v[144:145]
	s_add_i32 m0, s83, 0x2000
	s_nop 0
	global_load_lds_dwordx4 v[242:243], off
	v_lshl_add_u64 v[242:243], s[56:57], 0, v[150:151]
	s_mov_b32 m0, s75
	s_nop 0
	global_load_lds_dwordx4 v[242:243], off
	s_mov_b32 m0, s76
	s_nop 0
	global_load_lds_dwordx4 v[244:245], off
	s_waitcnt vmcnt(8)
	s_waitcnt lgkmcnt(0)
	s_setprio 1
	s_barrier
	v_mfma_f32_16x16x32_bf16 v[60:63], v[128:131], v[204:207], v[60:63]
	v_mfma_f32_16x16x32_bf16 v[60:63], v[132:135], v[208:211], v[60:63]
	v_mfma_f32_16x16x32_bf16 v[56:59], v[136:139], v[204:207], v[56:59]
	v_mfma_f32_16x16x32_bf16 v[56:59], v[140:143], v[208:211], v[56:59]
	v_mfma_f32_16x16x32_bf16 v[44:47], v[128:131], v[212:215], v[44:47]
	v_mfma_f32_16x16x32_bf16 v[44:47], v[132:135], v[216:219], v[44:47]
	v_mfma_f32_16x16x32_bf16 v[40:43], v[136:139], v[212:215], v[40:43]
	v_mfma_f32_16x16x32_bf16 v[40:43], v[140:143], v[216:219], v[40:43]
	v_mfma_f32_16x16x32_bf16 v[28:31], v[128:131], v[220:223], v[28:31]
	v_mfma_f32_16x16x32_bf16 v[28:31], v[132:135], v[224:227], v[28:31]
	v_mfma_f32_16x16x32_bf16 v[24:27], v[136:139], v[220:223], v[24:27]
	v_mfma_f32_16x16x32_bf16 v[24:27], v[140:143], v[224:227], v[24:27]
	v_mfma_f32_16x16x32_bf16 v[12:15], v[128:131], v[230:233], v[12:15]
	v_mfma_f32_16x16x32_bf16 v[12:15], v[132:135], v[234:237], v[12:15]
	v_mfma_f32_16x16x32_bf16 v[8:11], v[136:139], v[230:233], v[8:11]
	v_mfma_f32_16x16x32_bf16 v[8:11], v[140:143], v[234:237], v[8:11]
	v_mfma_f32_16x16x32_bf16 v[52:55], v[188:191], v[204:207], v[52:55]
	v_mfma_f32_16x16x32_bf16 v[52:55], v[192:195], v[208:211], v[52:55]
	v_mfma_f32_16x16x32_bf16 v[48:51], v[196:199], v[204:207], v[48:51]
	v_mfma_f32_16x16x32_bf16 v[48:51], v[200:203], v[208:211], v[48:51]
	v_mfma_f32_16x16x32_bf16 v[36:39], v[188:191], v[212:215], v[36:39]
	v_mfma_f32_16x16x32_bf16 v[36:39], v[192:195], v[216:219], v[36:39]
	v_mfma_f32_16x16x32_bf16 v[32:35], v[196:199], v[212:215], v[32:35]
	v_mfma_f32_16x16x32_bf16 v[32:35], v[200:203], v[216:219], v[32:35]
	v_mfma_f32_16x16x32_bf16 v[20:23], v[188:191], v[220:223], v[20:23]
	v_mfma_f32_16x16x32_bf16 v[20:23], v[192:195], v[224:227], v[20:23]
	v_mfma_f32_16x16x32_bf16 v[16:19], v[196:199], v[220:223], v[16:19]
	v_mfma_f32_16x16x32_bf16 v[16:19], v[200:203], v[224:227], v[16:19]
	v_mfma_f32_16x16x32_bf16 v[4:7], v[188:191], v[230:233], v[4:7]
	v_mfma_f32_16x16x32_bf16 v[4:7], v[192:195], v[234:237], v[4:7]
	v_mfma_f32_16x16x32_bf16 v[0:3], v[196:199], v[230:233], v[0:3]
	v_mfma_f32_16x16x32_bf16 v[0:3], v[200:203], v[234:237], v[0:3]
	s_barrier
	s_setprio 0
	s_add_i32 s83, 0, 0x18000
	s_add_i32 vcc_lo, 0, 0x1c000
	v_add_u32_e32 v140, s83, v157
	v_add_u32_e32 v171, vcc_lo, v157
	ds_read_b128 v[128:131], v140
	ds_read_b128 v[132:135], v140 offset:1024
	ds_read_b128 v[136:139], v140 offset:2048
	ds_read_b128 v[140:143], v140 offset:3072
	ds_read_b128 v[188:191], v171
	ds_read_b128 v[192:195], v171 offset:1024
	ds_read_b128 v[196:199], v171 offset:2048
	ds_read_b128 v[200:203], v171 offset:3072
	s_add_u32 s56, s56, 0x40000
	s_addc_u32 s57, s57, 0
	s_mov_b32 m0, s77
	v_lshl_add_u64 v[246:247], s[56:57], 0, v[150:151]
	ds_read_b128 v[204:207], v183 offset:32768
	ds_read_b128 v[208:211], v183 offset:33792
	ds_read_b128 v[212:215], v183 offset:34816
	ds_read_b128 v[216:219], v183 offset:35840
	ds_read_b128 v[220:223], v183 offset:36864
	ds_read_b128 v[224:227], v183 offset:37888
	ds_read_b128 v[230:233], v183 offset:38912
	ds_read_b128 v[234:237], v183 offset:39936
	global_load_lds_dwordx4 v[246:247], off
	v_lshl_add_u64 v[246:247], s[56:57], 0, v[146:147]
	s_mov_b32 m0, s78
	s_nop 0
	global_load_lds_dwordx4 v[246:247], off
	s_waitcnt vmcnt(8)
	s_waitcnt lgkmcnt(0)
	s_setprio 1
	s_barrier
	v_mfma_f32_16x16x32_bf16 v[124:127], v[128:131], v[204:207], v[124:127]
	v_mfma_f32_16x16x32_bf16 v[124:127], v[132:135], v[208:211], v[124:127]
	v_mfma_f32_16x16x32_bf16 v[120:123], v[136:139], v[204:207], v[120:123]
	v_mfma_f32_16x16x32_bf16 v[120:123], v[140:143], v[208:211], v[120:123]
	v_mfma_f32_16x16x32_bf16 v[108:111], v[128:131], v[212:215], v[108:111]
	v_mfma_f32_16x16x32_bf16 v[108:111], v[132:135], v[216:219], v[108:111]
	v_mfma_f32_16x16x32_bf16 v[104:107], v[136:139], v[212:215], v[104:107]
	v_mfma_f32_16x16x32_bf16 v[104:107], v[140:143], v[216:219], v[104:107]
	v_mfma_f32_16x16x32_bf16 v[92:95], v[128:131], v[220:223], v[92:95]
	v_mfma_f32_16x16x32_bf16 v[92:95], v[132:135], v[224:227], v[92:95]
	v_mfma_f32_16x16x32_bf16 v[88:91], v[136:139], v[220:223], v[88:91]
	v_mfma_f32_16x16x32_bf16 v[88:91], v[140:143], v[224:227], v[88:91]
	v_mfma_f32_16x16x32_bf16 v[76:79], v[128:131], v[230:233], v[76:79]
	v_mfma_f32_16x16x32_bf16 v[76:79], v[132:135], v[234:237], v[76:79]
	v_mfma_f32_16x16x32_bf16 v[72:75], v[136:139], v[230:233], v[72:75]
	v_mfma_f32_16x16x32_bf16 v[72:75], v[140:143], v[234:237], v[72:75]
	v_mfma_f32_16x16x32_bf16 v[116:119], v[188:191], v[204:207], v[116:119]
	v_mfma_f32_16x16x32_bf16 v[116:119], v[192:195], v[208:211], v[116:119]
	v_mfma_f32_16x16x32_bf16 v[112:115], v[196:199], v[204:207], v[112:115]
	v_mfma_f32_16x16x32_bf16 v[112:115], v[200:203], v[208:211], v[112:115]
	v_mfma_f32_16x16x32_bf16 v[100:103], v[188:191], v[212:215], v[100:103]
	v_mfma_f32_16x16x32_bf16 v[100:103], v[192:195], v[216:219], v[100:103]
	v_mfma_f32_16x16x32_bf16 v[96:99], v[196:199], v[212:215], v[96:99]
	v_mfma_f32_16x16x32_bf16 v[96:99], v[200:203], v[216:219], v[96:99]
	v_mfma_f32_16x16x32_bf16 v[84:87], v[188:191], v[220:223], v[84:87]
	v_mfma_f32_16x16x32_bf16 v[84:87], v[192:195], v[224:227], v[84:87]
	v_mfma_f32_16x16x32_bf16 v[80:83], v[196:199], v[220:223], v[80:83]
	v_mfma_f32_16x16x32_bf16 v[80:83], v[200:203], v[224:227], v[80:83]
	v_mfma_f32_16x16x32_bf16 v[68:71], v[188:191], v[230:233], v[68:71]
	v_mfma_f32_16x16x32_bf16 v[68:71], v[192:195], v[234:237], v[68:71]
	v_mfma_f32_16x16x32_bf16 v[64:67], v[196:199], v[230:233], v[64:67]
	v_mfma_f32_16x16x32_bf16 v[64:67], v[200:203], v[234:237], v[64:67]
	s_barrier
	s_setprio 0
	s_add_i32 s56, s83, s72
	v_lshl_add_u64 v[238:239], v[238:239], 0, s[38:39]
	s_mov_b32 m0, s56
	ds_read_b128 v[204:207], v183 offset:49152
	ds_read_b128 v[208:211], v183 offset:50176
	ds_read_b128 v[212:215], v183 offset:51200
	ds_read_b128 v[216:219], v183 offset:52224
	ds_read_b128 v[220:223], v183 offset:53248
	ds_read_b128 v[224:227], v183 offset:54272
	ds_read_b128 v[230:233], v183 offset:55296
	ds_read_b128 v[234:237], v183 offset:56320
	global_load_lds_dwordx4 v[238:239], off
	s_add_i32 m0, s56, 0x2000
	s_add_u32 s54, s54, 0x40080
	v_lshl_add_u64 v[238:239], v[240:241], 0, s[38:39]
	s_addc_u32 s55, s55, 0
	s_add_i32 s56, vcc_lo, s72
	global_load_lds_dwordx4 v[238:239], off
	v_lshl_add_u64 v[238:239], s[54:55], 0, v[148:149]
	s_mov_b32 m0, s56
	s_nop 0
	global_load_lds_dwordx4 v[238:239], off
	v_lshl_add_u64 v[238:239], s[54:55], 0, v[144:145]
	s_add_i32 m0, s56, 0x2000
	s_nop 0
	global_load_lds_dwordx4 v[238:239], off
	v_lshl_add_u64 v[238:239], v[242:243], 0, s[38:39]
	s_mov_b32 m0, s87
	s_nop 0
	global_load_lds_dwordx4 v[238:239], off
	v_lshl_add_u64 v[238:239], v[244:245], 0, s[38:39]
	s_mov_b32 m0, s88
	s_nop 0
	global_load_lds_dwordx4 v[238:239], off
	s_waitcnt vmcnt(8)
	s_waitcnt lgkmcnt(0)
	s_setprio 1
	s_barrier
	v_mfma_f32_16x16x32_bf16 v[60:63], v[128:131], v[204:207], v[60:63]
	v_mfma_f32_16x16x32_bf16 v[60:63], v[132:135], v[208:211], v[60:63]
	v_mfma_f32_16x16x32_bf16 v[56:59], v[136:139], v[204:207], v[56:59]
	v_mfma_f32_16x16x32_bf16 v[56:59], v[140:143], v[208:211], v[56:59]
	v_mfma_f32_16x16x32_bf16 v[44:47], v[128:131], v[212:215], v[44:47]
	v_mfma_f32_16x16x32_bf16 v[44:47], v[132:135], v[216:219], v[44:47]
	v_mfma_f32_16x16x32_bf16 v[40:43], v[136:139], v[212:215], v[40:43]
	v_mfma_f32_16x16x32_bf16 v[40:43], v[140:143], v[216:219], v[40:43]
	v_mfma_f32_16x16x32_bf16 v[28:31], v[128:131], v[220:223], v[28:31]
	v_mfma_f32_16x16x32_bf16 v[28:31], v[132:135], v[224:227], v[28:31]
	v_mfma_f32_16x16x32_bf16 v[24:27], v[136:139], v[220:223], v[24:27]
	v_mfma_f32_16x16x32_bf16 v[24:27], v[140:143], v[224:227], v[24:27]
	v_mfma_f32_16x16x32_bf16 v[12:15], v[128:131], v[230:233], v[12:15]
	v_mfma_f32_16x16x32_bf16 v[12:15], v[132:135], v[234:237], v[12:15]
	v_mfma_f32_16x16x32_bf16 v[8:11], v[136:139], v[230:233], v[8:11]
	v_mfma_f32_16x16x32_bf16 v[8:11], v[140:143], v[234:237], v[8:11]
	v_mfma_f32_16x16x32_bf16 v[52:55], v[188:191], v[204:207], v[52:55]
	v_mfma_f32_16x16x32_bf16 v[52:55], v[192:195], v[208:211], v[52:55]
	v_mfma_f32_16x16x32_bf16 v[48:51], v[196:199], v[204:207], v[48:51]
	v_mfma_f32_16x16x32_bf16 v[48:51], v[200:203], v[208:211], v[48:51]
	v_mfma_f32_16x16x32_bf16 v[36:39], v[188:191], v[212:215], v[36:39]
	v_mfma_f32_16x16x32_bf16 v[36:39], v[192:195], v[216:219], v[36:39]
	v_mfma_f32_16x16x32_bf16 v[32:35], v[196:199], v[212:215], v[32:35]
	v_mfma_f32_16x16x32_bf16 v[32:35], v[200:203], v[216:219], v[32:35]
	v_mfma_f32_16x16x32_bf16 v[20:23], v[188:191], v[220:223], v[20:23]
	v_mfma_f32_16x16x32_bf16 v[20:23], v[192:195], v[224:227], v[20:23]
	v_mfma_f32_16x16x32_bf16 v[16:19], v[196:199], v[220:223], v[16:19]
	v_mfma_f32_16x16x32_bf16 v[16:19], v[200:203], v[224:227], v[16:19]
	v_mfma_f32_16x16x32_bf16 v[4:7], v[188:191], v[230:233], v[4:7]
	v_mfma_f32_16x16x32_bf16 v[4:7], v[192:195], v[234:237], v[4:7]
	v_mfma_f32_16x16x32_bf16 v[0:3], v[196:199], v[230:233], v[0:3]
	v_mfma_f32_16x16x32_bf16 v[0:3], v[200:203], v[234:237], v[0:3]
	s_barrier
	s_setprio 0
	s_add_i32 s69, s69, 2
	s_add_u32 s52, s52, 0x100
	s_addc_u32 s53, s53, 0
	s_add_u32 s67, s67, 0x100
	s_addc_u32 s68, s68, 0
	s_cmp_gt_u32 s69, 13
	s_cbranch_scc0 .LBB0_313
	s_and_b64 vcc, exec, s[40:41]
	s_cbranch_vccz .LBB0_316
	s_barrier

.LBB0_667:
	s_ashr_i32 s23, s22, 31
	s_lshl_b64 s[38:39], s[22:23], 19
	s_add_u32 s38, s26, s38
	s_addc_u32 s39, s27, s39
	s_and_b64 s[40:41], s[6:7], exec
	s_cselect_b32 s23, s39, s45
	s_cselect_b32 s43, s38, s44
	s_ashr_i32 s37, s36, 31
	s_lshl_b64 s[40:41], s[36:37], 19
	s_add_u32 s40, s50, s40
	s_addc_u32 s41, s51, s41
	s_and_b64 s[48:49], s[6:7], exec
	s_cselect_b32 s37, s41, s47
	s_cselect_b32 s92, s40, s46
	s_add_u32 s44, s44, 0x40080
	s_addc_u32 s45, s45, 0
	s_add_u32 s93, s46, 0x100
	s_addc_u32 s94, s47, 0
	s_mov_b32 s95, -2
	s_waitcnt lgkmcnt(0)
	ds_read_b128 v[80:83], v216
	ds_read_b128 v[84:87], v216 offset:1024
	ds_read_b128 v[104:107], v216 offset:2048
	ds_read_b128 v[108:111], v216 offset:3072
	ds_read_b128 v[128:131], v217
	ds_read_b128 v[132:135], v217 offset:1024
	ds_read_b128 v[152:155], v217 offset:2048
	ds_read_b128 v[156:159], v217 offset:3072
	s_add_u32 s46, s44, 0xfffc0080
	s_addc_u32 s47, s45, -1
	s_cmp_eq_u32 s95, 12
	s_cselect_b32 s49, s23, s47
	s_cselect_b32 s48, s43, s46
	s_cselect_b32 s47, s37, s94
	s_cselect_b32 s46, s92, s93
	v_lshl_add_u64 v[224:225], s[44:45], 0, v[194:195]
	s_add_i32 m0, s53, 0xc000
	ds_read_b128 v[160:163], v218
	ds_read_b128 v[164:167], v218 offset:1024
	ds_read_b128 v[168:171], v218 offset:2048
	ds_read_b128 v[172:175], v218 offset:3072
	ds_read_b128 v[176:179], v218 offset:4096
	ds_read_b128 v[180:183], v218 offset:5120
	ds_read_b128 v[208:211], v218 offset:6144
	ds_read_b128 v[220:223], v218 offset:7168
	global_load_lds_dwordx4 v[224:225], off
	v_lshl_add_u64 v[224:225], s[44:45], 0, v[196:197]
	s_add_i32 m0, s53, 0xe000
	s_nop 0
	global_load_lds_dwordx4 v[224:225], off
	s_waitcnt vmcnt(8)
	s_waitcnt lgkmcnt(0)
	s_setprio 1
	s_barrier
	v_mfma_f32_16x16x32_bf16 v[148:151], v[80:83], v[160:163], 0
	v_mfma_f32_16x16x32_bf16 v[148:151], v[84:87], v[164:167], v[148:151]
	v_mfma_f32_16x16x32_bf16 v[144:147], v[104:107], v[160:163], 0
	v_mfma_f32_16x16x32_bf16 v[144:147], v[108:111], v[164:167], v[144:147]
	v_mfma_f32_16x16x32_bf16 v[124:127], v[80:83], v[168:171], 0
	v_mfma_f32_16x16x32_bf16 v[124:127], v[84:87], v[172:175], v[124:127]
	v_mfma_f32_16x16x32_bf16 v[120:123], v[104:107], v[168:171], 0
	v_mfma_f32_16x16x32_bf16 v[120:123], v[108:111], v[172:175], v[120:123]
	v_mfma_f32_16x16x32_bf16 v[100:103], v[80:83], v[176:179], 0
	v_mfma_f32_16x16x32_bf16 v[100:103], v[84:87], v[180:183], v[100:103]
	v_mfma_f32_16x16x32_bf16 v[96:99], v[104:107], v[176:179], 0
	v_mfma_f32_16x16x32_bf16 v[96:99], v[108:111], v[180:183], v[96:99]
	v_mfma_f32_16x16x32_bf16 v[76:79], v[80:83], v[208:211], 0
	v_mfma_f32_16x16x32_bf16 v[76:79], v[84:87], v[220:223], v[76:79]
	v_mfma_f32_16x16x32_bf16 v[72:75], v[104:107], v[208:211], 0
	v_mfma_f32_16x16x32_bf16 v[72:75], v[108:111], v[220:223], v[72:75]
	v_mfma_f32_16x16x32_bf16 v[140:143], v[128:131], v[160:163], 0
	v_mfma_f32_16x16x32_bf16 v[140:143], v[132:135], v[164:167], v[140:143]
	v_mfma_f32_16x16x32_bf16 v[136:139], v[152:155], v[160:163], 0
	v_mfma_f32_16x16x32_bf16 v[136:139], v[156:159], v[164:167], v[136:139]
	v_mfma_f32_16x16x32_bf16 v[116:119], v[128:131], v[168:171], 0
	v_mfma_f32_16x16x32_bf16 v[116:119], v[132:135], v[172:175], v[116:119]
	v_mfma_f32_16x16x32_bf16 v[112:115], v[152:155], v[168:171], 0
	v_mfma_f32_16x16x32_bf16 v[112:115], v[156:159], v[172:175], v[112:115]
	v_mfma_f32_16x16x32_bf16 v[92:95], v[128:131], v[176:179], 0
	v_mfma_f32_16x16x32_bf16 v[92:95], v[132:135], v[180:183], v[92:95]
	v_mfma_f32_16x16x32_bf16 v[88:91], v[152:155], v[176:179], 0
	v_mfma_f32_16x16x32_bf16 v[88:91], v[156:159], v[180:183], v[88:91]
	v_mfma_f32_16x16x32_bf16 v[68:71], v[128:131], v[208:211], 0
	v_mfma_f32_16x16x32_bf16 v[68:71], v[132:135], v[220:223], v[68:71]
	v_mfma_f32_16x16x32_bf16 v[64:67], v[152:155], v[208:211], 0
	v_mfma_f32_16x16x32_bf16 v[64:67], v[156:159], v[220:223], v[64:67]
	s_barrier
	s_setprio 0
	s_add_i32 s83, s78, s52
	v_lshl_add_u64 v[224:225], s[46:47], 0, v[186:187]
	s_mov_b32 m0, s83
	ds_read_b128 v[160:163], v218 offset:16384
	ds_read_b128 v[164:167], v218 offset:17408
	ds_read_b128 v[168:171], v218 offset:18432
	ds_read_b128 v[172:175], v218 offset:19456
	ds_read_b128 v[176:179], v218 offset:20480
	ds_read_b128 v[180:183], v218 offset:21504
	ds_read_b128 v[208:211], v218 offset:22528
	ds_read_b128 v[220:223], v218 offset:23552
	global_load_lds_dwordx4 v[224:225], off
	s_add_i32 m0, s83, 0x2000
	s_add_u32 s96, s46, 0x40000
	v_lshl_add_u64 v[226:227], s[46:47], 0, v[190:191]
	s_addc_u32 s97, s47, 0
	s_add_i32 s83, s79, s52
	global_load_lds_dwordx4 v[226:227], off
	v_lshl_add_u64 v[230:231], s[96:97], 0, v[186:187]
	s_mov_b32 m0, s83
	v_lshl_add_u64 v[232:233], s[48:49], 0, v[188:189]
	global_load_lds_dwordx4 v[230:231], off
	v_lshl_add_u64 v[230:231], s[96:97], 0, v[190:191]
	s_add_i32 m0, s83, 0x2000
	s_nop 0
	global_load_lds_dwordx4 v[230:231], off
	v_lshl_add_u64 v[230:231], s[48:49], 0, v[184:185]
	s_mov_b32 m0, s53
	s_nop 0
	global_load_lds_dwordx4 v[230:231], off
	s_mov_b32 m0, s54
	s_nop 0
	global_load_lds_dwordx4 v[232:233], off
	s_waitcnt vmcnt(8)
	s_waitcnt lgkmcnt(0)
	s_setprio 1
	s_barrier
	v_mfma_f32_16x16x32_bf16 v[60:63], v[80:83], v[160:163], 0
	v_mfma_f32_16x16x32_bf16 v[60:63], v[84:87], v[164:167], v[60:63]
	v_mfma_f32_16x16x32_bf16 v[56:59], v[104:107], v[160:163], 0
	v_mfma_f32_16x16x32_bf16 v[56:59], v[108:111], v[164:167], v[56:59]
	v_mfma_f32_16x16x32_bf16 v[44:47], v[80:83], v[168:171], 0
	v_mfma_f32_16x16x32_bf16 v[44:47], v[84:87], v[172:175], v[44:47]
	v_mfma_f32_16x16x32_bf16 v[40:43], v[104:107], v[168:171], 0
	v_mfma_f32_16x16x32_bf16 v[40:43], v[108:111], v[172:175], v[40:43]
	v_mfma_f32_16x16x32_bf16 v[28:31], v[80:83], v[176:179], 0
	v_mfma_f32_16x16x32_bf16 v[28:31], v[84:87], v[180:183], v[28:31]
	v_mfma_f32_16x16x32_bf16 v[24:27], v[104:107], v[176:179], 0
	v_mfma_f32_16x16x32_bf16 v[24:27], v[108:111], v[180:183], v[24:27]
	v_mfma_f32_16x16x32_bf16 v[12:15], v[80:83], v[208:211], 0
	v_mfma_f32_16x16x32_bf16 v[12:15], v[84:87], v[220:223], v[12:15]
	v_mfma_f32_16x16x32_bf16 v[8:11], v[104:107], v[208:211], 0
	v_mfma_f32_16x16x32_bf16 v[8:11], v[108:111], v[220:223], v[8:11]
	v_mfma_f32_16x16x32_bf16 v[52:55], v[128:131], v[160:163], 0
	v_mfma_f32_16x16x32_bf16 v[52:55], v[132:135], v[164:167], v[52:55]
	v_mfma_f32_16x16x32_bf16 v[48:51], v[152:155], v[160:163], 0
	v_mfma_f32_16x16x32_bf16 v[48:51], v[156:159], v[164:167], v[48:51]
	v_mfma_f32_16x16x32_bf16 v[36:39], v[128:131], v[168:171], 0
	v_mfma_f32_16x16x32_bf16 v[36:39], v[132:135], v[172:175], v[36:39]
	v_mfma_f32_16x16x32_bf16 v[32:35], v[152:155], v[168:171], 0
	v_mfma_f32_16x16x32_bf16 v[32:35], v[156:159], v[172:175], v[32:35]
	v_mfma_f32_16x16x32_bf16 v[20:23], v[128:131], v[176:179], 0
	v_mfma_f32_16x16x32_bf16 v[20:23], v[132:135], v[180:183], v[20:23]
	v_mfma_f32_16x16x32_bf16 v[16:19], v[152:155], v[176:179], 0
	v_mfma_f32_16x16x32_bf16 v[16:19], v[156:159], v[180:183], v[16:19]
	v_mfma_f32_16x16x32_bf16 v[4:7], v[128:131], v[208:211], 0
	v_mfma_f32_16x16x32_bf16 v[4:7], v[132:135], v[220:223], v[4:7]
	v_mfma_f32_16x16x32_bf16 v[0:3], v[152:155], v[208:211], 0
	v_mfma_f32_16x16x32_bf16 v[0:3], v[156:159], v[220:223], v[0:3]
	s_barrier
	s_setprio 0
	s_add_i32 s83, 0, 0x18000
	s_add_i32 s96, 0, 0x1c000
	v_add_u32_e32 v108, s83, v213
	v_add_u32_e32 v156, s96, v213
	ds_read_b128 v[80:83], v108
	ds_read_b128 v[84:87], v108 offset:1024
	ds_read_b128 v[104:107], v108 offset:2048
	ds_read_b128 v[108:111], v108 offset:3072
	ds_read_b128 v[128:131], v156
	ds_read_b128 v[132:135], v156 offset:1024
	ds_read_b128 v[152:155], v156 offset:2048
	ds_read_b128 v[156:159], v156 offset:3072
	s_add_u32 s48, s48, 0x40000
	s_addc_u32 s49, s49, 0
	s_mov_b32 m0, s55
	v_lshl_add_u64 v[234:235], s[48:49], 0, v[184:185]
	ds_read_b128 v[160:163], v218 offset:32768
	ds_read_b128 v[164:167], v218 offset:33792
	ds_read_b128 v[168:171], v218 offset:34816
	ds_read_b128 v[172:175], v218 offset:35840
	ds_read_b128 v[176:179], v218 offset:36864
	ds_read_b128 v[180:183], v218 offset:37888
	ds_read_b128 v[208:211], v218 offset:38912
	ds_read_b128 v[220:223], v218 offset:39936
	global_load_lds_dwordx4 v[234:235], off
	v_lshl_add_u64 v[234:235], s[48:49], 0, v[188:189]
	s_mov_b32 m0, s56
	s_nop 0
	global_load_lds_dwordx4 v[234:235], off
	s_waitcnt vmcnt(8)
	s_waitcnt lgkmcnt(0)
	s_setprio 1
	s_barrier
	v_mfma_f32_16x16x32_bf16 v[148:151], v[80:83], v[160:163], v[148:151]
	v_mfma_f32_16x16x32_bf16 v[148:151], v[84:87], v[164:167], v[148:151]
	v_mfma_f32_16x16x32_bf16 v[144:147], v[104:107], v[160:163], v[144:147]
	v_mfma_f32_16x16x32_bf16 v[144:147], v[108:111], v[164:167], v[144:147]
	v_mfma_f32_16x16x32_bf16 v[124:127], v[80:83], v[168:171], v[124:127]
	v_mfma_f32_16x16x32_bf16 v[124:127], v[84:87], v[172:175], v[124:127]
	v_mfma_f32_16x16x32_bf16 v[120:123], v[104:107], v[168:171], v[120:123]
	v_mfma_f32_16x16x32_bf16 v[120:123], v[108:111], v[172:175], v[120:123]
	v_mfma_f32_16x16x32_bf16 v[100:103], v[80:83], v[176:179], v[100:103]
	v_mfma_f32_16x16x32_bf16 v[100:103], v[84:87], v[180:183], v[100:103]
	v_mfma_f32_16x16x32_bf16 v[96:99], v[104:107], v[176:179], v[96:99]
	v_mfma_f32_16x16x32_bf16 v[96:99], v[108:111], v[180:183], v[96:99]
	v_mfma_f32_16x16x32_bf16 v[76:79], v[80:83], v[208:211], v[76:79]
	v_mfma_f32_16x16x32_bf16 v[76:79], v[84:87], v[220:223], v[76:79]
	v_mfma_f32_16x16x32_bf16 v[72:75], v[104:107], v[208:211], v[72:75]
	v_mfma_f32_16x16x32_bf16 v[72:75], v[108:111], v[220:223], v[72:75]
	v_mfma_f32_16x16x32_bf16 v[140:143], v[128:131], v[160:163], v[140:143]
	v_mfma_f32_16x16x32_bf16 v[140:143], v[132:135], v[164:167], v[140:143]
	v_mfma_f32_16x16x32_bf16 v[136:139], v[152:155], v[160:163], v[136:139]
	v_mfma_f32_16x16x32_bf16 v[136:139], v[156:159], v[164:167], v[136:139]
	v_mfma_f32_16x16x32_bf16 v[116:119], v[128:131], v[168:171], v[116:119]
	v_mfma_f32_16x16x32_bf16 v[116:119], v[132:135], v[172:175], v[116:119]
	v_mfma_f32_16x16x32_bf16 v[112:115], v[152:155], v[168:171], v[112:115]
	v_mfma_f32_16x16x32_bf16 v[112:115], v[156:159], v[172:175], v[112:115]
	v_mfma_f32_16x16x32_bf16 v[92:95], v[128:131], v[176:179], v[92:95]
	v_mfma_f32_16x16x32_bf16 v[92:95], v[132:135], v[180:183], v[92:95]
	v_mfma_f32_16x16x32_bf16 v[88:91], v[152:155], v[176:179], v[88:91]
	v_mfma_f32_16x16x32_bf16 v[88:91], v[156:159], v[180:183], v[88:91]
	v_mfma_f32_16x16x32_bf16 v[68:71], v[128:131], v[208:211], v[68:71]
	v_mfma_f32_16x16x32_bf16 v[68:71], v[132:135], v[220:223], v[68:71]
	v_mfma_f32_16x16x32_bf16 v[64:67], v[152:155], v[208:211], v[64:67]
	v_mfma_f32_16x16x32_bf16 v[64:67], v[156:159], v[220:223], v[64:67]
	s_barrier
	s_setprio 0
	s_add_i32 s48, s83, s52
	v_lshl_add_u64 v[224:225], v[224:225], 0, s[18:19]
	s_mov_b32 m0, s48
	ds_read_b128 v[160:163], v218 offset:49152
	ds_read_b128 v[164:167], v218 offset:50176
	ds_read_b128 v[168:171], v218 offset:51200
	ds_read_b128 v[172:175], v218 offset:52224
	ds_read_b128 v[176:179], v218 offset:53248
	ds_read_b128 v[180:183], v218 offset:54272
	ds_read_b128 v[208:211], v218 offset:55296
	ds_read_b128 v[220:223], v218 offset:56320
	global_load_lds_dwordx4 v[224:225], off
	s_add_i32 m0, s48, 0x2000
	s_add_u32 s46, s46, 0x40080
	v_lshl_add_u64 v[224:225], v[226:227], 0, s[18:19]
	s_addc_u32 s47, s47, 0
	s_add_i32 s48, s96, s52
	global_load_lds_dwordx4 v[224:225], off
	v_lshl_add_u64 v[224:225], s[46:47], 0, v[186:187]
	s_mov_b32 m0, s48
	s_nop 0
	global_load_lds_dwordx4 v[224:225], off
	v_lshl_add_u64 v[224:225], s[46:47], 0, v[190:191]
	s_add_i32 m0, s48, 0x2000
	s_nop 0
	global_load_lds_dwordx4 v[224:225], off
	v_lshl_add_u64 v[224:225], v[230:231], 0, s[18:19]
	s_mov_b32 m0, s68
	s_nop 0
	global_load_lds_dwordx4 v[224:225], off
	v_lshl_add_u64 v[224:225], v[232:233], 0, s[18:19]
	s_mov_b32 m0, s69
	s_nop 0
	global_load_lds_dwordx4 v[224:225], off
	s_waitcnt vmcnt(8)
	s_waitcnt lgkmcnt(0)
	s_setprio 1
	s_barrier
	v_mfma_f32_16x16x32_bf16 v[60:63], v[80:83], v[160:163], v[60:63]
	v_mfma_f32_16x16x32_bf16 v[60:63], v[84:87], v[164:167], v[60:63]
	v_mfma_f32_16x16x32_bf16 v[56:59], v[104:107], v[160:163], v[56:59]
	v_mfma_f32_16x16x32_bf16 v[56:59], v[108:111], v[164:167], v[56:59]
	v_mfma_f32_16x16x32_bf16 v[44:47], v[80:83], v[168:171], v[44:47]
	v_mfma_f32_16x16x32_bf16 v[44:47], v[84:87], v[172:175], v[44:47]
	v_mfma_f32_16x16x32_bf16 v[40:43], v[104:107], v[168:171], v[40:43]
	v_mfma_f32_16x16x32_bf16 v[40:43], v[108:111], v[172:175], v[40:43]
	v_mfma_f32_16x16x32_bf16 v[28:31], v[80:83], v[176:179], v[28:31]
	v_mfma_f32_16x16x32_bf16 v[28:31], v[84:87], v[180:183], v[28:31]
	v_mfma_f32_16x16x32_bf16 v[24:27], v[104:107], v[176:179], v[24:27]
	v_mfma_f32_16x16x32_bf16 v[24:27], v[108:111], v[180:183], v[24:27]
	v_mfma_f32_16x16x32_bf16 v[12:15], v[80:83], v[208:211], v[12:15]
	v_mfma_f32_16x16x32_bf16 v[12:15], v[84:87], v[220:223], v[12:15]
	v_mfma_f32_16x16x32_bf16 v[8:11], v[104:107], v[208:211], v[8:11]
	v_mfma_f32_16x16x32_bf16 v[8:11], v[108:111], v[220:223], v[8:11]
	v_mfma_f32_16x16x32_bf16 v[52:55], v[128:131], v[160:163], v[52:55]
	v_mfma_f32_16x16x32_bf16 v[52:55], v[132:135], v[164:167], v[52:55]
	v_mfma_f32_16x16x32_bf16 v[48:51], v[152:155], v[160:163], v[48:51]
	v_mfma_f32_16x16x32_bf16 v[48:51], v[156:159], v[164:167], v[48:51]
	v_mfma_f32_16x16x32_bf16 v[36:39], v[128:131], v[168:171], v[36:39]
	v_mfma_f32_16x16x32_bf16 v[36:39], v[132:135], v[172:175], v[36:39]
	v_mfma_f32_16x16x32_bf16 v[32:35], v[152:155], v[168:171], v[32:35]
	v_mfma_f32_16x16x32_bf16 v[32:35], v[156:159], v[172:175], v[32:35]
	v_mfma_f32_16x16x32_bf16 v[20:23], v[128:131], v[176:179], v[20:23]
	v_mfma_f32_16x16x32_bf16 v[20:23], v[132:135], v[180:183], v[20:23]
	v_mfma_f32_16x16x32_bf16 v[16:19], v[152:155], v[176:179], v[16:19]
	v_mfma_f32_16x16x32_bf16 v[16:19], v[156:159], v[180:183], v[16:19]
	v_mfma_f32_16x16x32_bf16 v[4:7], v[128:131], v[208:211], v[4:7]
	v_mfma_f32_16x16x32_bf16 v[4:7], v[132:135], v[220:223], v[4:7]
	v_mfma_f32_16x16x32_bf16 v[0:3], v[152:155], v[208:211], v[0:3]
	v_mfma_f32_16x16x32_bf16 v[0:3], v[156:159], v[220:223], v[0:3]
	s_barrier
	s_setprio 0
	s_add_i32 s95, s95, 2
	s_add_u32 s44, s44, 0x100
	s_addc_u32 s45, s45, 0
	s_add_u32 s93, s93, 0x100
	s_addc_u32 s94, s94, 0
	s_cmp_gt_u32 s95, 13
.LBB0_668:
	ds_read_b128 v[80:83], v216
	ds_read_b128 v[84:87], v216 offset:1024
	ds_read_b128 v[104:107], v216 offset:2048
	ds_read_b128 v[108:111], v216 offset:3072
	ds_read_b128 v[128:131], v217
	ds_read_b128 v[132:135], v217 offset:1024
	ds_read_b128 v[152:155], v217 offset:2048
	ds_read_b128 v[156:159], v217 offset:3072
	s_add_u32 s46, s44, 0xfffc0080
	s_addc_u32 s47, s45, -1
	s_cmp_eq_u32 s95, 12
	s_cselect_b32 s49, s23, s47
	s_cselect_b32 s48, s43, s46
	s_cselect_b32 s47, s37, s94
	s_cselect_b32 s46, s92, s93
	v_lshl_add_u64 v[224:225], s[44:45], 0, v[194:195]
	s_add_i32 m0, s53, 0xc000
	ds_read_b128 v[160:163], v218
	ds_read_b128 v[164:167], v218 offset:1024
	ds_read_b128 v[168:171], v218 offset:2048
	ds_read_b128 v[172:175], v218 offset:3072
	ds_read_b128 v[176:179], v218 offset:4096
	ds_read_b128 v[180:183], v218 offset:5120
	ds_read_b128 v[208:211], v218 offset:6144
	ds_read_b128 v[220:223], v218 offset:7168
	global_load_lds_dwordx4 v[224:225], off
	v_lshl_add_u64 v[224:225], s[44:45], 0, v[196:197]
	s_add_i32 m0, s53, 0xe000
	s_nop 0
	global_load_lds_dwordx4 v[224:225], off
	s_waitcnt vmcnt(8)
	s_waitcnt lgkmcnt(0)
	s_setprio 1
	s_barrier
	v_mfma_f32_16x16x32_bf16 v[148:151], v[80:83], v[160:163], v[148:151]
	v_mfma_f32_16x16x32_bf16 v[148:151], v[84:87], v[164:167], v[148:151]
	v_mfma_f32_16x16x32_bf16 v[144:147], v[104:107], v[160:163], v[144:147]
	v_mfma_f32_16x16x32_bf16 v[144:147], v[108:111], v[164:167], v[144:147]
	v_mfma_f32_16x16x32_bf16 v[124:127], v[80:83], v[168:171], v[124:127]
	v_mfma_f32_16x16x32_bf16 v[124:127], v[84:87], v[172:175], v[124:127]
	v_mfma_f32_16x16x32_bf16 v[120:123], v[104:107], v[168:171], v[120:123]
	v_mfma_f32_16x16x32_bf16 v[120:123], v[108:111], v[172:175], v[120:123]
	v_mfma_f32_16x16x32_bf16 v[100:103], v[80:83], v[176:179], v[100:103]
	v_mfma_f32_16x16x32_bf16 v[100:103], v[84:87], v[180:183], v[100:103]
	v_mfma_f32_16x16x32_bf16 v[96:99], v[104:107], v[176:179], v[96:99]
	v_mfma_f32_16x16x32_bf16 v[96:99], v[108:111], v[180:183], v[96:99]
	v_mfma_f32_16x16x32_bf16 v[76:79], v[80:83], v[208:211], v[76:79]
	v_mfma_f32_16x16x32_bf16 v[76:79], v[84:87], v[220:223], v[76:79]
	v_mfma_f32_16x16x32_bf16 v[72:75], v[104:107], v[208:211], v[72:75]
	v_mfma_f32_16x16x32_bf16 v[72:75], v[108:111], v[220:223], v[72:75]
	v_mfma_f32_16x16x32_bf16 v[140:143], v[128:131], v[160:163], v[140:143]
	v_mfma_f32_16x16x32_bf16 v[140:143], v[132:135], v[164:167], v[140:143]
	v_mfma_f32_16x16x32_bf16 v[136:139], v[152:155], v[160:163], v[136:139]
	v_mfma_f32_16x16x32_bf16 v[136:139], v[156:159], v[164:167], v[136:139]
	v_mfma_f32_16x16x32_bf16 v[116:119], v[128:131], v[168:171], v[116:119]
	v_mfma_f32_16x16x32_bf16 v[116:119], v[132:135], v[172:175], v[116:119]
	v_mfma_f32_16x16x32_bf16 v[112:115], v[152:155], v[168:171], v[112:115]
	v_mfma_f32_16x16x32_bf16 v[112:115], v[156:159], v[172:175], v[112:115]
	v_mfma_f32_16x16x32_bf16 v[92:95], v[128:131], v[176:179], v[92:95]
	v_mfma_f32_16x16x32_bf16 v[92:95], v[132:135], v[180:183], v[92:95]
	v_mfma_f32_16x16x32_bf16 v[88:91], v[152:155], v[176:179], v[88:91]
	v_mfma_f32_16x16x32_bf16 v[88:91], v[156:159], v[180:183], v[88:91]
	v_mfma_f32_16x16x32_bf16 v[68:71], v[128:131], v[208:211], v[68:71]
	v_mfma_f32_16x16x32_bf16 v[68:71], v[132:135], v[220:223], v[68:71]
	v_mfma_f32_16x16x32_bf16 v[64:67], v[152:155], v[208:211], v[64:67]
	v_mfma_f32_16x16x32_bf16 v[64:67], v[156:159], v[220:223], v[64:67]
	s_barrier
	s_setprio 0
	s_add_i32 s83, s78, s52
	v_lshl_add_u64 v[224:225], s[46:47], 0, v[186:187]
	s_mov_b32 m0, s83
	ds_read_b128 v[160:163], v218 offset:16384
	ds_read_b128 v[164:167], v218 offset:17408
	ds_read_b128 v[168:171], v218 offset:18432
	ds_read_b128 v[172:175], v218 offset:19456
	ds_read_b128 v[176:179], v218 offset:20480
	ds_read_b128 v[180:183], v218 offset:21504
	ds_read_b128 v[208:211], v218 offset:22528
	ds_read_b128 v[220:223], v218 offset:23552
	global_load_lds_dwordx4 v[224:225], off
	s_add_i32 m0, s83, 0x2000
	s_add_u32 s96, s46, 0x40000
	v_lshl_add_u64 v[226:227], s[46:47], 0, v[190:191]
	s_addc_u32 s97, s47, 0
	s_add_i32 s83, s79, s52
	global_load_lds_dwordx4 v[226:227], off
	v_lshl_add_u64 v[230:231], s[96:97], 0, v[186:187]
	s_mov_b32 m0, s83
	v_lshl_add_u64 v[232:233], s[48:49], 0, v[188:189]
	global_load_lds_dwordx4 v[230:231], off
	v_lshl_add_u64 v[230:231], s[96:97], 0, v[190:191]
	s_add_i32 m0, s83, 0x2000
	s_nop 0
	global_load_lds_dwordx4 v[230:231], off
	v_lshl_add_u64 v[230:231], s[48:49], 0, v[184:185]
	s_mov_b32 m0, s53
	s_nop 0
	global_load_lds_dwordx4 v[230:231], off
	s_mov_b32 m0, s54
	s_nop 0
	global_load_lds_dwordx4 v[232:233], off
	s_waitcnt vmcnt(8)
	s_waitcnt lgkmcnt(0)
	s_setprio 1
	s_barrier
	v_mfma_f32_16x16x32_bf16 v[60:63], v[80:83], v[160:163], v[60:63]
	v_mfma_f32_16x16x32_bf16 v[60:63], v[84:87], v[164:167], v[60:63]
	v_mfma_f32_16x16x32_bf16 v[56:59], v[104:107], v[160:163], v[56:59]
	v_mfma_f32_16x16x32_bf16 v[56:59], v[108:111], v[164:167], v[56:59]
	v_mfma_f32_16x16x32_bf16 v[44:47], v[80:83], v[168:171], v[44:47]
	v_mfma_f32_16x16x32_bf16 v[44:47], v[84:87], v[172:175], v[44:47]
	v_mfma_f32_16x16x32_bf16 v[40:43], v[104:107], v[168:171], v[40:43]
	v_mfma_f32_16x16x32_bf16 v[40:43], v[108:111], v[172:175], v[40:43]
	v_mfma_f32_16x16x32_bf16 v[28:31], v[80:83], v[176:179], v[28:31]
	v_mfma_f32_16x16x32_bf16 v[28:31], v[84:87], v[180:183], v[28:31]
	v_mfma_f32_16x16x32_bf16 v[24:27], v[104:107], v[176:179], v[24:27]
	v_mfma_f32_16x16x32_bf16 v[24:27], v[108:111], v[180:183], v[24:27]
	v_mfma_f32_16x16x32_bf16 v[12:15], v[80:83], v[208:211], v[12:15]
	v_mfma_f32_16x16x32_bf16 v[12:15], v[84:87], v[220:223], v[12:15]
	v_mfma_f32_16x16x32_bf16 v[8:11], v[104:107], v[208:211], v[8:11]
	v_mfma_f32_16x16x32_bf16 v[8:11], v[108:111], v[220:223], v[8:11]
	v_mfma_f32_16x16x32_bf16 v[52:55], v[128:131], v[160:163], v[52:55]
	v_mfma_f32_16x16x32_bf16 v[52:55], v[132:135], v[164:167], v[52:55]
	v_mfma_f32_16x16x32_bf16 v[48:51], v[152:155], v[160:163], v[48:51]
	v_mfma_f32_16x16x32_bf16 v[48:51], v[156:159], v[164:167], v[48:51]
	v_mfma_f32_16x16x32_bf16 v[36:39], v[128:131], v[168:171], v[36:39]
	v_mfma_f32_16x16x32_bf16 v[36:39], v[132:135], v[172:175], v[36:39]
	v_mfma_f32_16x16x32_bf16 v[32:35], v[152:155], v[168:171], v[32:35]
	v_mfma_f32_16x16x32_bf16 v[32:35], v[156:159], v[172:175], v[32:35]
	v_mfma_f32_16x16x32_bf16 v[20:23], v[128:131], v[176:179], v[20:23]
	v_mfma_f32_16x16x32_bf16 v[20:23], v[132:135], v[180:183], v[20:23]
	v_mfma_f32_16x16x32_bf16 v[16:19], v[152:155], v[176:179], v[16:19]
	v_mfma_f32_16x16x32_bf16 v[16:19], v[156:159], v[180:183], v[16:19]
	v_mfma_f32_16x16x32_bf16 v[4:7], v[128:131], v[208:211], v[4:7]
	v_mfma_f32_16x16x32_bf16 v[4:7], v[132:135], v[220:223], v[4:7]
	v_mfma_f32_16x16x32_bf16 v[0:3], v[152:155], v[208:211], v[0:3]
	v_mfma_f32_16x16x32_bf16 v[0:3], v[156:159], v[220:223], v[0:3]
	s_barrier
	s_setprio 0
	s_add_i32 s83, 0, 0x18000
	s_add_i32 s96, 0, 0x1c000
	v_add_u32_e32 v108, s83, v213
	v_add_u32_e32 v156, s96, v213
	ds_read_b128 v[80:83], v108
	ds_read_b128 v[84:87], v108 offset:1024
	ds_read_b128 v[104:107], v108 offset:2048
	ds_read_b128 v[108:111], v108 offset:3072
	ds_read_b128 v[128:131], v156
	ds_read_b128 v[132:135], v156 offset:1024
	ds_read_b128 v[152:155], v156 offset:2048
	ds_read_b128 v[156:159], v156 offset:3072
	s_add_u32 s48, s48, 0x40000
	s_addc_u32 s49, s49, 0
	s_mov_b32 m0, s55
	v_lshl_add_u64 v[234:235], s[48:49], 0, v[184:185]
	ds_read_b128 v[160:163], v218 offset:32768
	ds_read_b128 v[164:167], v218 offset:33792
	ds_read_b128 v[168:171], v218 offset:34816
	ds_read_b128 v[172:175], v218 offset:35840
	ds_read_b128 v[176:179], v218 offset:36864
	ds_read_b128 v[180:183], v218 offset:37888
	ds_read_b128 v[208:211], v218 offset:38912
	ds_read_b128 v[220:223], v218 offset:39936
	global_load_lds_dwordx4 v[234:235], off
	v_lshl_add_u64 v[234:235], s[48:49], 0, v[188:189]
	s_mov_b32 m0, s56
	s_nop 0
	global_load_lds_dwordx4 v[234:235], off
	s_waitcnt vmcnt(8)
	s_waitcnt lgkmcnt(0)
	s_setprio 1
	s_barrier
	v_mfma_f32_16x16x32_bf16 v[148:151], v[80:83], v[160:163], v[148:151]
	v_mfma_f32_16x16x32_bf16 v[148:151], v[84:87], v[164:167], v[148:151]
	v_mfma_f32_16x16x32_bf16 v[144:147], v[104:107], v[160:163], v[144:147]
	v_mfma_f32_16x16x32_bf16 v[144:147], v[108:111], v[164:167], v[144:147]
	v_mfma_f32_16x16x32_bf16 v[124:127], v[80:83], v[168:171], v[124:127]
	v_mfma_f32_16x16x32_bf16 v[124:127], v[84:87], v[172:175], v[124:127]
	v_mfma_f32_16x16x32_bf16 v[120:123], v[104:107], v[168:171], v[120:123]
	v_mfma_f32_16x16x32_bf16 v[120:123], v[108:111], v[172:175], v[120:123]
	v_mfma_f32_16x16x32_bf16 v[100:103], v[80:83], v[176:179], v[100:103]
	v_mfma_f32_16x16x32_bf16 v[100:103], v[84:87], v[180:183], v[100:103]
	v_mfma_f32_16x16x32_bf16 v[96:99], v[104:107], v[176:179], v[96:99]
	v_mfma_f32_16x16x32_bf16 v[96:99], v[108:111], v[180:183], v[96:99]
	v_mfma_f32_16x16x32_bf16 v[76:79], v[80:83], v[208:211], v[76:79]
	v_mfma_f32_16x16x32_bf16 v[76:79], v[84:87], v[220:223], v[76:79]
	v_mfma_f32_16x16x32_bf16 v[72:75], v[104:107], v[208:211], v[72:75]
	v_mfma_f32_16x16x32_bf16 v[72:75], v[108:111], v[220:223], v[72:75]
	v_mfma_f32_16x16x32_bf16 v[140:143], v[128:131], v[160:163], v[140:143]
	v_mfma_f32_16x16x32_bf16 v[140:143], v[132:135], v[164:167], v[140:143]
	v_mfma_f32_16x16x32_bf16 v[136:139], v[152:155], v[160:163], v[136:139]
	v_mfma_f32_16x16x32_bf16 v[136:139], v[156:159], v[164:167], v[136:139]
	v_mfma_f32_16x16x32_bf16 v[116:119], v[128:131], v[168:171], v[116:119]
	v_mfma_f32_16x16x32_bf16 v[116:119], v[132:135], v[172:175], v[116:119]
	v_mfma_f32_16x16x32_bf16 v[112:115], v[152:155], v[168:171], v[112:115]
	v_mfma_f32_16x16x32_bf16 v[112:115], v[156:159], v[172:175], v[112:115]
	v_mfma_f32_16x16x32_bf16 v[92:95], v[128:131], v[176:179], v[92:95]
	v_mfma_f32_16x16x32_bf16 v[92:95], v[132:135], v[180:183], v[92:95]
	v_mfma_f32_16x16x32_bf16 v[88:91], v[152:155], v[176:179], v[88:91]
	v_mfma_f32_16x16x32_bf16 v[88:91], v[156:159], v[180:183], v[88:91]
	v_mfma_f32_16x16x32_bf16 v[68:71], v[128:131], v[208:211], v[68:71]
	v_mfma_f32_16x16x32_bf16 v[68:71], v[132:135], v[220:223], v[68:71]
	v_mfma_f32_16x16x32_bf16 v[64:67], v[152:155], v[208:211], v[64:67]
	v_mfma_f32_16x16x32_bf16 v[64:67], v[156:159], v[220:223], v[64:67]
	s_barrier
	s_setprio 0
	s_add_i32 s48, s83, s52
	v_lshl_add_u64 v[224:225], v[224:225], 0, s[18:19]
	s_mov_b32 m0, s48
	ds_read_b128 v[160:163], v218 offset:49152
	ds_read_b128 v[164:167], v218 offset:50176
	ds_read_b128 v[168:171], v218 offset:51200
	ds_read_b128 v[172:175], v218 offset:52224
	ds_read_b128 v[176:179], v218 offset:53248
	ds_read_b128 v[180:183], v218 offset:54272
	ds_read_b128 v[208:211], v218 offset:55296
	ds_read_b128 v[220:223], v218 offset:56320
	global_load_lds_dwordx4 v[224:225], off
	s_add_i32 m0, s48, 0x2000
	s_add_u32 s46, s46, 0x40080
	v_lshl_add_u64 v[224:225], v[226:227], 0, s[18:19]
	s_addc_u32 s47, s47, 0
	s_add_i32 s48, s96, s52
	global_load_lds_dwordx4 v[224:225], off
	v_lshl_add_u64 v[224:225], s[46:47], 0, v[186:187]
	s_mov_b32 m0, s48
	s_nop 0
	global_load_lds_dwordx4 v[224:225], off
	v_lshl_add_u64 v[224:225], s[46:47], 0, v[190:191]
	s_add_i32 m0, s48, 0x2000
	s_nop 0
	global_load_lds_dwordx4 v[224:225], off
	v_lshl_add_u64 v[224:225], v[230:231], 0, s[18:19]
	s_mov_b32 m0, s68
	s_nop 0
	global_load_lds_dwordx4 v[224:225], off
	v_lshl_add_u64 v[224:225], v[232:233], 0, s[18:19]
	s_mov_b32 m0, s69
	s_nop 0
	global_load_lds_dwordx4 v[224:225], off
	s_waitcnt vmcnt(8)
	s_waitcnt lgkmcnt(0)
	s_setprio 1
	s_barrier
	v_mfma_f32_16x16x32_bf16 v[60:63], v[80:83], v[160:163], v[60:63]
	v_mfma_f32_16x16x32_bf16 v[60:63], v[84:87], v[164:167], v[60:63]
	v_mfma_f32_16x16x32_bf16 v[56:59], v[104:107], v[160:163], v[56:59]
	v_mfma_f32_16x16x32_bf16 v[56:59], v[108:111], v[164:167], v[56:59]
	v_mfma_f32_16x16x32_bf16 v[44:47], v[80:83], v[168:171], v[44:47]
	v_mfma_f32_16x16x32_bf16 v[44:47], v[84:87], v[172:175], v[44:47]
	v_mfma_f32_16x16x32_bf16 v[40:43], v[104:107], v[168:171], v[40:43]
	v_mfma_f32_16x16x32_bf16 v[40:43], v[108:111], v[172:175], v[40:43]
	v_mfma_f32_16x16x32_bf16 v[28:31], v[80:83], v[176:179], v[28:31]
	v_mfma_f32_16x16x32_bf16 v[28:31], v[84:87], v[180:183], v[28:31]
	v_mfma_f32_16x16x32_bf16 v[24:27], v[104:107], v[176:179], v[24:27]
	v_mfma_f32_16x16x32_bf16 v[24:27], v[108:111], v[180:183], v[24:27]
	v_mfma_f32_16x16x32_bf16 v[12:15], v[80:83], v[208:211], v[12:15]
	v_mfma_f32_16x16x32_bf16 v[12:15], v[84:87], v[220:223], v[12:15]
	v_mfma_f32_16x16x32_bf16 v[8:11], v[104:107], v[208:211], v[8:11]
	v_mfma_f32_16x16x32_bf16 v[8:11], v[108:111], v[220:223], v[8:11]
	v_mfma_f32_16x16x32_bf16 v[52:55], v[128:131], v[160:163], v[52:55]
	v_mfma_f32_16x16x32_bf16 v[52:55], v[132:135], v[164:167], v[52:55]
	v_mfma_f32_16x16x32_bf16 v[48:51], v[152:155], v[160:163], v[48:51]
	v_mfma_f32_16x16x32_bf16 v[48:51], v[156:159], v[164:167], v[48:51]
	v_mfma_f32_16x16x32_bf16 v[36:39], v[128:131], v[168:171], v[36:39]
	v_mfma_f32_16x16x32_bf16 v[36:39], v[132:135], v[172:175], v[36:39]
	v_mfma_f32_16x16x32_bf16 v[32:35], v[152:155], v[168:171], v[32:35]
	v_mfma_f32_16x16x32_bf16 v[32:35], v[156:159], v[172:175], v[32:35]
	v_mfma_f32_16x16x32_bf16 v[20:23], v[128:131], v[176:179], v[20:23]
	v_mfma_f32_16x16x32_bf16 v[20:23], v[132:135], v[180:183], v[20:23]
	v_mfma_f32_16x16x32_bf16 v[16:19], v[152:155], v[176:179], v[16:19]
	v_mfma_f32_16x16x32_bf16 v[16:19], v[156:159], v[180:183], v[16:19]
	v_mfma_f32_16x16x32_bf16 v[4:7], v[128:131], v[208:211], v[4:7]
	v_mfma_f32_16x16x32_bf16 v[4:7], v[132:135], v[220:223], v[4:7]
	v_mfma_f32_16x16x32_bf16 v[0:3], v[152:155], v[208:211], v[0:3]
	v_mfma_f32_16x16x32_bf16 v[0:3], v[156:159], v[220:223], v[0:3]
	s_barrier
	s_setprio 0
	s_add_i32 s95, s95, 2
	s_add_u32 s44, s44, 0x100
	s_addc_u32 s45, s45, 0
	s_add_u32 s93, s93, 0x100
	s_addc_u32 s94, s94, 0
	s_cmp_gt_u32 s95, 13
	s_cbranch_scc0 .LBB0_668
	s_and_b64 vcc, exec, s[20:21]
	s_cbranch_vccz .LBB0_671
	s_barrier

.LBB0_758:
	s_ashr_i32 s19, s18, 31
	s_lshl_b64 s[20:21], s[18:19], 19
	s_add_u32 s20, s62, s20
	s_addc_u32 s21, s63, s21
	s_and_b64 s[22:23], s[4:5], exec
	s_cselect_b32 s19, s21, s39
	s_cselect_b32 s57, s20, s38
	s_ashr_i32 s11, s10, 31
	s_lshl_b64 s[22:23], s[10:11], 19
	s_add_u32 s22, s40, s22
	s_addc_u32 s23, s41, s23
	s_and_b64 s[4:5], s[4:5], exec
	s_cselect_b32 s11, s23, s37
	s_cselect_b32 s58, s22, s36
	s_add_u32 s4, s38, 0x40080
	s_addc_u32 s5, s39, 0
	s_add_u32 s59, s36, 0x100
	s_addc_u32 s66, s37, 0
	s_mov_b32 s67, -2
	ds_read_b128 v[146:149], v172
	ds_read_b128 v[166:169], v172 offset:1024
	ds_read_b128 v[176:179], v172 offset:2048
	ds_read_b128 v[180:183], v172 offset:3072
	ds_read_b128 v[184:187], v173
	ds_read_b128 v[188:191], v173 offset:1024
	ds_read_b128 v[192:195], v173 offset:2048
	ds_read_b128 v[196:199], v173 offset:3072
	s_add_u32 s36, s4, 0xfffc0080
	s_addc_u32 s37, s5, -1
	s_cmp_eq_u32 s67, 12
	s_cselect_b32 s39, s19, s37
	s_cselect_b32 s38, s57, s36
	s_cselect_b32 s37, s11, s66
	s_cselect_b32 s36, s58, s59
	v_lshl_add_u64 v[150:151], s[4:5], 0, v[138:139]
	s_add_i32 m0, s27, 0xc000
	ds_read_b128 v[200:203], v174
	ds_read_b128 v[204:207], v174 offset:1024
	ds_read_b128 v[208:211], v174 offset:2048
	ds_read_b128 v[212:215], v174 offset:3072
	ds_read_b128 v[216:219], v174 offset:4096
	ds_read_b128 v[220:223], v174 offset:5120
	ds_read_b128 v[224:227], v174 offset:6144
	ds_read_b128 v[230:233], v174 offset:7168
	global_load_lds_dwordx4 v[150:151], off
	v_lshl_add_u64 v[150:151], s[4:5], 0, v[140:141]
	s_add_i32 m0, s27, 0xe000
	s_nop 0
	global_load_lds_dwordx4 v[150:151], off
	s_waitcnt vmcnt(8)
	s_waitcnt lgkmcnt(0)
	s_setprio 1
	s_barrier
	v_mfma_f32_16x16x32_bf16 v[124:127], v[146:149], v[200:203], 0
	v_mfma_f32_16x16x32_bf16 v[124:127], v[166:169], v[204:207], v[124:127]
	v_mfma_f32_16x16x32_bf16 v[120:123], v[176:179], v[200:203], 0
	v_mfma_f32_16x16x32_bf16 v[120:123], v[180:183], v[204:207], v[120:123]
	v_mfma_f32_16x16x32_bf16 v[108:111], v[146:149], v[208:211], 0
	v_mfma_f32_16x16x32_bf16 v[108:111], v[166:169], v[212:215], v[108:111]
	v_mfma_f32_16x16x32_bf16 v[104:107], v[176:179], v[208:211], 0
	v_mfma_f32_16x16x32_bf16 v[104:107], v[180:183], v[212:215], v[104:107]
	v_mfma_f32_16x16x32_bf16 v[92:95], v[146:149], v[216:219], 0
	v_mfma_f32_16x16x32_bf16 v[92:95], v[166:169], v[220:223], v[92:95]
	v_mfma_f32_16x16x32_bf16 v[88:91], v[176:179], v[216:219], 0
	v_mfma_f32_16x16x32_bf16 v[88:91], v[180:183], v[220:223], v[88:91]
	v_mfma_f32_16x16x32_bf16 v[76:79], v[146:149], v[224:227], 0
	v_mfma_f32_16x16x32_bf16 v[76:79], v[166:169], v[230:233], v[76:79]
	v_mfma_f32_16x16x32_bf16 v[72:75], v[176:179], v[224:227], 0
	v_mfma_f32_16x16x32_bf16 v[72:75], v[180:183], v[230:233], v[72:75]
	v_mfma_f32_16x16x32_bf16 v[116:119], v[184:187], v[200:203], 0
	v_mfma_f32_16x16x32_bf16 v[116:119], v[188:191], v[204:207], v[116:119]
	v_mfma_f32_16x16x32_bf16 v[112:115], v[192:195], v[200:203], 0
	v_mfma_f32_16x16x32_bf16 v[112:115], v[196:199], v[204:207], v[112:115]
	v_mfma_f32_16x16x32_bf16 v[100:103], v[184:187], v[208:211], 0
	v_mfma_f32_16x16x32_bf16 v[100:103], v[188:191], v[212:215], v[100:103]
	v_mfma_f32_16x16x32_bf16 v[96:99], v[192:195], v[208:211], 0
	v_mfma_f32_16x16x32_bf16 v[96:99], v[196:199], v[212:215], v[96:99]
	v_mfma_f32_16x16x32_bf16 v[84:87], v[184:187], v[216:219], 0
	v_mfma_f32_16x16x32_bf16 v[84:87], v[188:191], v[220:223], v[84:87]
	v_mfma_f32_16x16x32_bf16 v[80:83], v[192:195], v[216:219], 0
	v_mfma_f32_16x16x32_bf16 v[80:83], v[196:199], v[220:223], v[80:83]
	v_mfma_f32_16x16x32_bf16 v[68:71], v[184:187], v[224:227], 0
	v_mfma_f32_16x16x32_bf16 v[68:71], v[188:191], v[230:233], v[68:71]
	v_mfma_f32_16x16x32_bf16 v[64:67], v[192:195], v[224:227], 0
	v_mfma_f32_16x16x32_bf16 v[64:67], v[196:199], v[230:233], v[64:67]
	s_barrier
	s_setprio 0
	s_add_i32 s68, s53, s42
	v_lshl_add_u64 v[150:151], s[36:37], 0, v[132:133]
	s_mov_b32 m0, s68
	ds_read_b128 v[200:203], v174 offset:16384
	ds_read_b128 v[204:207], v174 offset:17408
	ds_read_b128 v[208:211], v174 offset:18432
	ds_read_b128 v[212:215], v174 offset:19456
	ds_read_b128 v[216:219], v174 offset:20480
	ds_read_b128 v[220:223], v174 offset:21504
	ds_read_b128 v[224:227], v174 offset:22528
	ds_read_b128 v[230:233], v174 offset:23552
	global_load_lds_dwordx4 v[150:151], off
	s_add_i32 m0, s68, 0x2000
	s_add_u32 s68, s36, 0x40000
	v_lshl_add_u64 v[154:155], s[36:37], 0, v[128:129]
	s_addc_u32 s69, s37, 0
	s_add_i32 s70, s54, s42
	global_load_lds_dwordx4 v[154:155], off
	v_lshl_add_u64 v[158:159], s[68:69], 0, v[132:133]
	s_mov_b32 m0, s70
	v_lshl_add_u64 v[162:163], s[38:39], 0, v[130:131]
	global_load_lds_dwordx4 v[158:159], off
	v_lshl_add_u64 v[158:159], s[68:69], 0, v[128:129]
	s_add_i32 m0, s70, 0x2000
	s_nop 0
	global_load_lds_dwordx4 v[158:159], off
	v_lshl_add_u64 v[158:159], s[38:39], 0, v[134:135]
	s_mov_b32 m0, s27
	s_nop 0
	global_load_lds_dwordx4 v[158:159], off
	s_mov_b32 m0, s45
	s_nop 0
	global_load_lds_dwordx4 v[162:163], off
	s_waitcnt vmcnt(8)
	s_waitcnt lgkmcnt(0)
	s_setprio 1
	s_barrier
	v_mfma_f32_16x16x32_bf16 v[60:63], v[146:149], v[200:203], 0
	v_mfma_f32_16x16x32_bf16 v[60:63], v[166:169], v[204:207], v[60:63]
	v_mfma_f32_16x16x32_bf16 v[56:59], v[176:179], v[200:203], 0
	v_mfma_f32_16x16x32_bf16 v[56:59], v[180:183], v[204:207], v[56:59]
	v_mfma_f32_16x16x32_bf16 v[44:47], v[146:149], v[208:211], 0
	v_mfma_f32_16x16x32_bf16 v[44:47], v[166:169], v[212:215], v[44:47]
	v_mfma_f32_16x16x32_bf16 v[40:43], v[176:179], v[208:211], 0
	v_mfma_f32_16x16x32_bf16 v[40:43], v[180:183], v[212:215], v[40:43]
	v_mfma_f32_16x16x32_bf16 v[28:31], v[146:149], v[216:219], 0
	v_mfma_f32_16x16x32_bf16 v[28:31], v[166:169], v[220:223], v[28:31]
	v_mfma_f32_16x16x32_bf16 v[24:27], v[176:179], v[216:219], 0
	v_mfma_f32_16x16x32_bf16 v[24:27], v[180:183], v[220:223], v[24:27]
	v_mfma_f32_16x16x32_bf16 v[12:15], v[146:149], v[224:227], 0
	v_mfma_f32_16x16x32_bf16 v[12:15], v[166:169], v[230:233], v[12:15]
	v_mfma_f32_16x16x32_bf16 v[8:11], v[176:179], v[224:227], 0
	v_mfma_f32_16x16x32_bf16 v[8:11], v[180:183], v[230:233], v[8:11]
	v_mfma_f32_16x16x32_bf16 v[52:55], v[184:187], v[200:203], 0
	v_mfma_f32_16x16x32_bf16 v[52:55], v[188:191], v[204:207], v[52:55]
	v_mfma_f32_16x16x32_bf16 v[48:51], v[192:195], v[200:203], 0
	v_mfma_f32_16x16x32_bf16 v[48:51], v[196:199], v[204:207], v[48:51]
	v_mfma_f32_16x16x32_bf16 v[36:39], v[184:187], v[208:211], 0
	v_mfma_f32_16x16x32_bf16 v[36:39], v[188:191], v[212:215], v[36:39]
	v_mfma_f32_16x16x32_bf16 v[32:35], v[192:195], v[208:211], 0
	v_mfma_f32_16x16x32_bf16 v[32:35], v[196:199], v[212:215], v[32:35]
	v_mfma_f32_16x16x32_bf16 v[20:23], v[184:187], v[216:219], 0
	v_mfma_f32_16x16x32_bf16 v[20:23], v[188:191], v[220:223], v[20:23]
	v_mfma_f32_16x16x32_bf16 v[16:19], v[192:195], v[216:219], 0
	v_mfma_f32_16x16x32_bf16 v[16:19], v[196:199], v[220:223], v[16:19]
	v_mfma_f32_16x16x32_bf16 v[4:7], v[184:187], v[224:227], 0
	v_mfma_f32_16x16x32_bf16 v[4:7], v[188:191], v[230:233], v[4:7]
	v_mfma_f32_16x16x32_bf16 v[0:3], v[192:195], v[224:227], 0
	v_mfma_f32_16x16x32_bf16 v[0:3], v[196:199], v[230:233], v[0:3]
	s_barrier
	s_setprio 0
	s_add_i32 s68, 0, 0x18000
	v_add_u32_e32 v152, s68, v157
	s_add_i32 s69, 0, 0x1c000
	ds_read_b128 v[146:149], v152
	ds_read_b128 v[166:169], v152 offset:1024
	ds_read_b128 v[176:179], v152 offset:2048
	ds_read_b128 v[180:183], v152 offset:3072
	v_add_u32_e32 v152, s69, v157
	ds_read_b128 v[184:187], v152
	ds_read_b128 v[188:191], v152 offset:1024
	ds_read_b128 v[192:195], v152 offset:2048
	ds_read_b128 v[196:199], v152 offset:3072
	s_add_u32 s38, s38, 0x40000
	s_addc_u32 s39, s39, 0
	s_mov_b32 m0, s46
	v_lshl_add_u64 v[234:235], s[38:39], 0, v[134:135]
	ds_read_b128 v[200:203], v174 offset:32768
	ds_read_b128 v[204:207], v174 offset:33792
	ds_read_b128 v[208:211], v174 offset:34816
	ds_read_b128 v[212:215], v174 offset:35840
	ds_read_b128 v[216:219], v174 offset:36864
	ds_read_b128 v[220:223], v174 offset:37888
	ds_read_b128 v[224:227], v174 offset:38912
	ds_read_b128 v[230:233], v174 offset:39936
	global_load_lds_dwordx4 v[234:235], off
	v_lshl_add_u64 v[234:235], s[38:39], 0, v[130:131]
	s_mov_b32 m0, s47
	s_nop 0
	global_load_lds_dwordx4 v[234:235], off
	s_waitcnt vmcnt(8)
	s_waitcnt lgkmcnt(0)
	s_setprio 1
	s_barrier
	v_mfma_f32_16x16x32_bf16 v[124:127], v[146:149], v[200:203], v[124:127]
	v_mfma_f32_16x16x32_bf16 v[124:127], v[166:169], v[204:207], v[124:127]
	v_mfma_f32_16x16x32_bf16 v[120:123], v[176:179], v[200:203], v[120:123]
	v_mfma_f32_16x16x32_bf16 v[120:123], v[180:183], v[204:207], v[120:123]
	v_mfma_f32_16x16x32_bf16 v[108:111], v[146:149], v[208:211], v[108:111]
	v_mfma_f32_16x16x32_bf16 v[108:111], v[166:169], v[212:215], v[108:111]
	v_mfma_f32_16x16x32_bf16 v[104:107], v[176:179], v[208:211], v[104:107]
	v_mfma_f32_16x16x32_bf16 v[104:107], v[180:183], v[212:215], v[104:107]
	v_mfma_f32_16x16x32_bf16 v[92:95], v[146:149], v[216:219], v[92:95]
	v_mfma_f32_16x16x32_bf16 v[92:95], v[166:169], v[220:223], v[92:95]
	v_mfma_f32_16x16x32_bf16 v[88:91], v[176:179], v[216:219], v[88:91]
	v_mfma_f32_16x16x32_bf16 v[88:91], v[180:183], v[220:223], v[88:91]
	v_mfma_f32_16x16x32_bf16 v[76:79], v[146:149], v[224:227], v[76:79]
	v_mfma_f32_16x16x32_bf16 v[76:79], v[166:169], v[230:233], v[76:79]
	v_mfma_f32_16x16x32_bf16 v[72:75], v[176:179], v[224:227], v[72:75]
	v_mfma_f32_16x16x32_bf16 v[72:75], v[180:183], v[230:233], v[72:75]
	v_mfma_f32_16x16x32_bf16 v[116:119], v[184:187], v[200:203], v[116:119]
	v_mfma_f32_16x16x32_bf16 v[116:119], v[188:191], v[204:207], v[116:119]
	v_mfma_f32_16x16x32_bf16 v[112:115], v[192:195], v[200:203], v[112:115]
	v_mfma_f32_16x16x32_bf16 v[112:115], v[196:199], v[204:207], v[112:115]
	v_mfma_f32_16x16x32_bf16 v[100:103], v[184:187], v[208:211], v[100:103]
	v_mfma_f32_16x16x32_bf16 v[100:103], v[188:191], v[212:215], v[100:103]
	v_mfma_f32_16x16x32_bf16 v[96:99], v[192:195], v[208:211], v[96:99]
	v_mfma_f32_16x16x32_bf16 v[96:99], v[196:199], v[212:215], v[96:99]
	v_mfma_f32_16x16x32_bf16 v[84:87], v[184:187], v[216:219], v[84:87]
	v_mfma_f32_16x16x32_bf16 v[84:87], v[188:191], v[220:223], v[84:87]
	v_mfma_f32_16x16x32_bf16 v[80:83], v[192:195], v[216:219], v[80:83]
	v_mfma_f32_16x16x32_bf16 v[80:83], v[196:199], v[220:223], v[80:83]
	v_mfma_f32_16x16x32_bf16 v[68:71], v[184:187], v[224:227], v[68:71]
	v_mfma_f32_16x16x32_bf16 v[68:71], v[188:191], v[230:233], v[68:71]
	v_mfma_f32_16x16x32_bf16 v[64:67], v[192:195], v[224:227], v[64:67]
	v_mfma_f32_16x16x32_bf16 v[64:67], v[196:199], v[230:233], v[64:67]
	s_barrier
	s_setprio 0
	s_add_i32 s38, s68, s42
	v_lshl_add_u64 v[150:151], v[150:151], 0, s[14:15]
	s_mov_b32 m0, s38
	ds_read_b128 v[200:203], v174 offset:49152
	ds_read_b128 v[204:207], v174 offset:50176
	ds_read_b128 v[208:211], v174 offset:51200
	ds_read_b128 v[212:215], v174 offset:52224
	ds_read_b128 v[216:219], v174 offset:53248
	ds_read_b128 v[220:223], v174 offset:54272
	ds_read_b128 v[224:227], v174 offset:55296
	ds_read_b128 v[230:233], v174 offset:56320
	global_load_lds_dwordx4 v[150:151], off
	s_add_i32 m0, s38, 0x2000
	s_add_u32 s36, s36, 0x40080
	v_lshl_add_u64 v[150:151], v[154:155], 0, s[14:15]
	s_addc_u32 s37, s37, 0
	s_add_i32 s38, s69, s42
	global_load_lds_dwordx4 v[150:151], off
	v_lshl_add_u64 v[150:151], s[36:37], 0, v[132:133]
	s_mov_b32 m0, s38
	s_nop 0
	global_load_lds_dwordx4 v[150:151], off
	v_lshl_add_u64 v[150:151], s[36:37], 0, v[128:129]
	s_add_i32 m0, s38, 0x2000
	s_nop 0
	global_load_lds_dwordx4 v[150:151], off
	v_lshl_add_u64 v[150:151], v[158:159], 0, s[14:15]
	s_mov_b32 m0, s49
	s_nop 0
	global_load_lds_dwordx4 v[150:151], off
	v_lshl_add_u64 v[150:151], v[162:163], 0, s[14:15]
	s_mov_b32 m0, s50
	s_nop 0
	global_load_lds_dwordx4 v[150:151], off
	s_waitcnt vmcnt(8)
	s_waitcnt lgkmcnt(0)
	s_setprio 1
	s_barrier
	v_mfma_f32_16x16x32_bf16 v[60:63], v[146:149], v[200:203], v[60:63]
	v_mfma_f32_16x16x32_bf16 v[60:63], v[166:169], v[204:207], v[60:63]
	v_mfma_f32_16x16x32_bf16 v[56:59], v[176:179], v[200:203], v[56:59]
	v_mfma_f32_16x16x32_bf16 v[56:59], v[180:183], v[204:207], v[56:59]
	v_mfma_f32_16x16x32_bf16 v[44:47], v[146:149], v[208:211], v[44:47]
	v_mfma_f32_16x16x32_bf16 v[44:47], v[166:169], v[212:215], v[44:47]
	v_mfma_f32_16x16x32_bf16 v[40:43], v[176:179], v[208:211], v[40:43]
	v_mfma_f32_16x16x32_bf16 v[40:43], v[180:183], v[212:215], v[40:43]
	v_mfma_f32_16x16x32_bf16 v[28:31], v[146:149], v[216:219], v[28:31]
	v_mfma_f32_16x16x32_bf16 v[28:31], v[166:169], v[220:223], v[28:31]
	v_mfma_f32_16x16x32_bf16 v[24:27], v[176:179], v[216:219], v[24:27]
	v_mfma_f32_16x16x32_bf16 v[24:27], v[180:183], v[220:223], v[24:27]
	v_mfma_f32_16x16x32_bf16 v[12:15], v[146:149], v[224:227], v[12:15]
	v_mfma_f32_16x16x32_bf16 v[12:15], v[166:169], v[230:233], v[12:15]
	v_mfma_f32_16x16x32_bf16 v[8:11], v[176:179], v[224:227], v[8:11]
	v_mfma_f32_16x16x32_bf16 v[8:11], v[180:183], v[230:233], v[8:11]
	v_mfma_f32_16x16x32_bf16 v[52:55], v[184:187], v[200:203], v[52:55]
	v_mfma_f32_16x16x32_bf16 v[52:55], v[188:191], v[204:207], v[52:55]
	v_mfma_f32_16x16x32_bf16 v[48:51], v[192:195], v[200:203], v[48:51]
	v_mfma_f32_16x16x32_bf16 v[48:51], v[196:199], v[204:207], v[48:51]
	v_mfma_f32_16x16x32_bf16 v[36:39], v[184:187], v[208:211], v[36:39]
	v_mfma_f32_16x16x32_bf16 v[36:39], v[188:191], v[212:215], v[36:39]
	v_mfma_f32_16x16x32_bf16 v[32:35], v[192:195], v[208:211], v[32:35]
	v_mfma_f32_16x16x32_bf16 v[32:35], v[196:199], v[212:215], v[32:35]
	v_mfma_f32_16x16x32_bf16 v[20:23], v[184:187], v[216:219], v[20:23]
	v_mfma_f32_16x16x32_bf16 v[20:23], v[188:191], v[220:223], v[20:23]
	v_mfma_f32_16x16x32_bf16 v[16:19], v[192:195], v[216:219], v[16:19]
	v_mfma_f32_16x16x32_bf16 v[16:19], v[196:199], v[220:223], v[16:19]
	v_mfma_f32_16x16x32_bf16 v[4:7], v[184:187], v[224:227], v[4:7]
	v_mfma_f32_16x16x32_bf16 v[4:7], v[188:191], v[230:233], v[4:7]
	v_mfma_f32_16x16x32_bf16 v[0:3], v[192:195], v[224:227], v[0:3]
	v_mfma_f32_16x16x32_bf16 v[0:3], v[196:199], v[230:233], v[0:3]
	s_barrier
	s_setprio 0
	s_add_i32 s67, s67, 2
	s_add_u32 s4, s4, 0x100
	s_addc_u32 s5, s5, 0
	s_add_u32 s59, s59, 0x100
	s_addc_u32 s66, s66, 0
	s_cmp_gt_u32 s67, 13
.LBB0_759:
	ds_read_b128 v[146:149], v172
	ds_read_b128 v[166:169], v172 offset:1024
	ds_read_b128 v[176:179], v172 offset:2048
	ds_read_b128 v[180:183], v172 offset:3072
	ds_read_b128 v[184:187], v173
	ds_read_b128 v[188:191], v173 offset:1024
	ds_read_b128 v[192:195], v173 offset:2048
	ds_read_b128 v[196:199], v173 offset:3072
	s_add_u32 s36, s4, 0xfffc0080
	s_addc_u32 s37, s5, -1
	s_cmp_eq_u32 s67, 12
	s_cselect_b32 s39, s19, s37
	s_cselect_b32 s38, s57, s36
	s_cselect_b32 s37, s11, s66
	s_cselect_b32 s36, s58, s59
	v_lshl_add_u64 v[150:151], s[4:5], 0, v[138:139]
	s_add_i32 m0, s27, 0xc000
	ds_read_b128 v[200:203], v174
	ds_read_b128 v[204:207], v174 offset:1024
	ds_read_b128 v[208:211], v174 offset:2048
	ds_read_b128 v[212:215], v174 offset:3072
	ds_read_b128 v[216:219], v174 offset:4096
	ds_read_b128 v[220:223], v174 offset:5120
	ds_read_b128 v[224:227], v174 offset:6144
	ds_read_b128 v[230:233], v174 offset:7168
	global_load_lds_dwordx4 v[150:151], off
	v_lshl_add_u64 v[150:151], s[4:5], 0, v[140:141]
	s_add_i32 m0, s27, 0xe000
	s_nop 0
	global_load_lds_dwordx4 v[150:151], off
	s_waitcnt vmcnt(8)
	s_waitcnt lgkmcnt(0)
	s_setprio 1
	s_barrier
	v_mfma_f32_16x16x32_bf16 v[124:127], v[146:149], v[200:203], v[124:127]
	v_mfma_f32_16x16x32_bf16 v[124:127], v[166:169], v[204:207], v[124:127]
	v_mfma_f32_16x16x32_bf16 v[120:123], v[176:179], v[200:203], v[120:123]
	v_mfma_f32_16x16x32_bf16 v[120:123], v[180:183], v[204:207], v[120:123]
	v_mfma_f32_16x16x32_bf16 v[108:111], v[146:149], v[208:211], v[108:111]
	v_mfma_f32_16x16x32_bf16 v[108:111], v[166:169], v[212:215], v[108:111]
	v_mfma_f32_16x16x32_bf16 v[104:107], v[176:179], v[208:211], v[104:107]
	v_mfma_f32_16x16x32_bf16 v[104:107], v[180:183], v[212:215], v[104:107]
	v_mfma_f32_16x16x32_bf16 v[92:95], v[146:149], v[216:219], v[92:95]
	v_mfma_f32_16x16x32_bf16 v[92:95], v[166:169], v[220:223], v[92:95]
	v_mfma_f32_16x16x32_bf16 v[88:91], v[176:179], v[216:219], v[88:91]
	v_mfma_f32_16x16x32_bf16 v[88:91], v[180:183], v[220:223], v[88:91]
	v_mfma_f32_16x16x32_bf16 v[76:79], v[146:149], v[224:227], v[76:79]
	v_mfma_f32_16x16x32_bf16 v[76:79], v[166:169], v[230:233], v[76:79]
	v_mfma_f32_16x16x32_bf16 v[72:75], v[176:179], v[224:227], v[72:75]
	v_mfma_f32_16x16x32_bf16 v[72:75], v[180:183], v[230:233], v[72:75]
	v_mfma_f32_16x16x32_bf16 v[116:119], v[184:187], v[200:203], v[116:119]
	v_mfma_f32_16x16x32_bf16 v[116:119], v[188:191], v[204:207], v[116:119]
	v_mfma_f32_16x16x32_bf16 v[112:115], v[192:195], v[200:203], v[112:115]
	v_mfma_f32_16x16x32_bf16 v[112:115], v[196:199], v[204:207], v[112:115]
	v_mfma_f32_16x16x32_bf16 v[100:103], v[184:187], v[208:211], v[100:103]
	v_mfma_f32_16x16x32_bf16 v[100:103], v[188:191], v[212:215], v[100:103]
	v_mfma_f32_16x16x32_bf16 v[96:99], v[192:195], v[208:211], v[96:99]
	v_mfma_f32_16x16x32_bf16 v[96:99], v[196:199], v[212:215], v[96:99]
	v_mfma_f32_16x16x32_bf16 v[84:87], v[184:187], v[216:219], v[84:87]
	v_mfma_f32_16x16x32_bf16 v[84:87], v[188:191], v[220:223], v[84:87]
	v_mfma_f32_16x16x32_bf16 v[80:83], v[192:195], v[216:219], v[80:83]
	v_mfma_f32_16x16x32_bf16 v[80:83], v[196:199], v[220:223], v[80:83]
	v_mfma_f32_16x16x32_bf16 v[68:71], v[184:187], v[224:227], v[68:71]
	v_mfma_f32_16x16x32_bf16 v[68:71], v[188:191], v[230:233], v[68:71]
	v_mfma_f32_16x16x32_bf16 v[64:67], v[192:195], v[224:227], v[64:67]
	v_mfma_f32_16x16x32_bf16 v[64:67], v[196:199], v[230:233], v[64:67]
	s_barrier
	s_setprio 0
	s_add_i32 s68, s53, s42
	v_lshl_add_u64 v[150:151], s[36:37], 0, v[132:133]
	s_mov_b32 m0, s68
	ds_read_b128 v[200:203], v174 offset:16384
	ds_read_b128 v[204:207], v174 offset:17408
	ds_read_b128 v[208:211], v174 offset:18432
	ds_read_b128 v[212:215], v174 offset:19456
	ds_read_b128 v[216:219], v174 offset:20480
	ds_read_b128 v[220:223], v174 offset:21504
	ds_read_b128 v[224:227], v174 offset:22528
	ds_read_b128 v[230:233], v174 offset:23552
	global_load_lds_dwordx4 v[150:151], off
	s_add_i32 m0, s68, 0x2000
	s_add_u32 s68, s36, 0x40000
	v_lshl_add_u64 v[154:155], s[36:37], 0, v[128:129]
	s_addc_u32 s69, s37, 0
	s_add_i32 s70, s54, s42
	global_load_lds_dwordx4 v[154:155], off
	v_lshl_add_u64 v[158:159], s[68:69], 0, v[132:133]
	s_mov_b32 m0, s70
	v_lshl_add_u64 v[162:163], s[38:39], 0, v[130:131]
	global_load_lds_dwordx4 v[158:159], off
	v_lshl_add_u64 v[158:159], s[68:69], 0, v[128:129]
	s_add_i32 m0, s70, 0x2000
	s_nop 0
	global_load_lds_dwordx4 v[158:159], off
	v_lshl_add_u64 v[158:159], s[38:39], 0, v[134:135]
	s_mov_b32 m0, s27
	s_nop 0
	global_load_lds_dwordx4 v[158:159], off
	s_mov_b32 m0, s45
	s_nop 0
	global_load_lds_dwordx4 v[162:163], off
	s_waitcnt vmcnt(8)
	s_waitcnt lgkmcnt(0)
	s_setprio 1
	s_barrier
	v_mfma_f32_16x16x32_bf16 v[60:63], v[146:149], v[200:203], v[60:63]
	v_mfma_f32_16x16x32_bf16 v[60:63], v[166:169], v[204:207], v[60:63]
	v_mfma_f32_16x16x32_bf16 v[56:59], v[176:179], v[200:203], v[56:59]
	v_mfma_f32_16x16x32_bf16 v[56:59], v[180:183], v[204:207], v[56:59]
	v_mfma_f32_16x16x32_bf16 v[44:47], v[146:149], v[208:211], v[44:47]
	v_mfma_f32_16x16x32_bf16 v[44:47], v[166:169], v[212:215], v[44:47]
	v_mfma_f32_16x16x32_bf16 v[40:43], v[176:179], v[208:211], v[40:43]
	v_mfma_f32_16x16x32_bf16 v[40:43], v[180:183], v[212:215], v[40:43]
	v_mfma_f32_16x16x32_bf16 v[28:31], v[146:149], v[216:219], v[28:31]
	v_mfma_f32_16x16x32_bf16 v[28:31], v[166:169], v[220:223], v[28:31]
	v_mfma_f32_16x16x32_bf16 v[24:27], v[176:179], v[216:219], v[24:27]
	v_mfma_f32_16x16x32_bf16 v[24:27], v[180:183], v[220:223], v[24:27]
	v_mfma_f32_16x16x32_bf16 v[12:15], v[146:149], v[224:227], v[12:15]
	v_mfma_f32_16x16x32_bf16 v[12:15], v[166:169], v[230:233], v[12:15]
	v_mfma_f32_16x16x32_bf16 v[8:11], v[176:179], v[224:227], v[8:11]
	v_mfma_f32_16x16x32_bf16 v[8:11], v[180:183], v[230:233], v[8:11]
	v_mfma_f32_16x16x32_bf16 v[52:55], v[184:187], v[200:203], v[52:55]
	v_mfma_f32_16x16x32_bf16 v[52:55], v[188:191], v[204:207], v[52:55]
	v_mfma_f32_16x16x32_bf16 v[48:51], v[192:195], v[200:203], v[48:51]
	v_mfma_f32_16x16x32_bf16 v[48:51], v[196:199], v[204:207], v[48:51]
	v_mfma_f32_16x16x32_bf16 v[36:39], v[184:187], v[208:211], v[36:39]
	v_mfma_f32_16x16x32_bf16 v[36:39], v[188:191], v[212:215], v[36:39]
	v_mfma_f32_16x16x32_bf16 v[32:35], v[192:195], v[208:211], v[32:35]
	v_mfma_f32_16x16x32_bf16 v[32:35], v[196:199], v[212:215], v[32:35]
	v_mfma_f32_16x16x32_bf16 v[20:23], v[184:187], v[216:219], v[20:23]
	v_mfma_f32_16x16x32_bf16 v[20:23], v[188:191], v[220:223], v[20:23]
	v_mfma_f32_16x16x32_bf16 v[16:19], v[192:195], v[216:219], v[16:19]
	v_mfma_f32_16x16x32_bf16 v[16:19], v[196:199], v[220:223], v[16:19]
	v_mfma_f32_16x16x32_bf16 v[4:7], v[184:187], v[224:227], v[4:7]
	v_mfma_f32_16x16x32_bf16 v[4:7], v[188:191], v[230:233], v[4:7]
	v_mfma_f32_16x16x32_bf16 v[0:3], v[192:195], v[224:227], v[0:3]
	v_mfma_f32_16x16x32_bf16 v[0:3], v[196:199], v[230:233], v[0:3]
	s_barrier
	s_setprio 0
	s_add_i32 s68, 0, 0x18000
	v_add_u32_e32 v152, s68, v157
	s_add_i32 s69, 0, 0x1c000
	ds_read_b128 v[146:149], v152
	ds_read_b128 v[166:169], v152 offset:1024
	ds_read_b128 v[176:179], v152 offset:2048
	ds_read_b128 v[180:183], v152 offset:3072
	v_add_u32_e32 v152, s69, v157
	ds_read_b128 v[184:187], v152
	ds_read_b128 v[188:191], v152 offset:1024
	ds_read_b128 v[192:195], v152 offset:2048
	ds_read_b128 v[196:199], v152 offset:3072
	s_add_u32 s38, s38, 0x40000
	s_addc_u32 s39, s39, 0
	s_mov_b32 m0, s46
	v_lshl_add_u64 v[234:235], s[38:39], 0, v[134:135]
	ds_read_b128 v[200:203], v174 offset:32768
	ds_read_b128 v[204:207], v174 offset:33792
	ds_read_b128 v[208:211], v174 offset:34816
	ds_read_b128 v[212:215], v174 offset:35840
	ds_read_b128 v[216:219], v174 offset:36864
	ds_read_b128 v[220:223], v174 offset:37888
	ds_read_b128 v[224:227], v174 offset:38912
	ds_read_b128 v[230:233], v174 offset:39936
	global_load_lds_dwordx4 v[234:235], off
	v_lshl_add_u64 v[234:235], s[38:39], 0, v[130:131]
	s_mov_b32 m0, s47
	s_nop 0
	global_load_lds_dwordx4 v[234:235], off
	s_waitcnt vmcnt(8)
	s_waitcnt lgkmcnt(0)
	s_setprio 1
	s_barrier
	v_mfma_f32_16x16x32_bf16 v[124:127], v[146:149], v[200:203], v[124:127]
	v_mfma_f32_16x16x32_bf16 v[124:127], v[166:169], v[204:207], v[124:127]
	v_mfma_f32_16x16x32_bf16 v[120:123], v[176:179], v[200:203], v[120:123]
	v_mfma_f32_16x16x32_bf16 v[120:123], v[180:183], v[204:207], v[120:123]
	v_mfma_f32_16x16x32_bf16 v[108:111], v[146:149], v[208:211], v[108:111]
	v_mfma_f32_16x16x32_bf16 v[108:111], v[166:169], v[212:215], v[108:111]
	v_mfma_f32_16x16x32_bf16 v[104:107], v[176:179], v[208:211], v[104:107]
	v_mfma_f32_16x16x32_bf16 v[104:107], v[180:183], v[212:215], v[104:107]
	v_mfma_f32_16x16x32_bf16 v[92:95], v[146:149], v[216:219], v[92:95]
	v_mfma_f32_16x16x32_bf16 v[92:95], v[166:169], v[220:223], v[92:95]
	v_mfma_f32_16x16x32_bf16 v[88:91], v[176:179], v[216:219], v[88:91]
	v_mfma_f32_16x16x32_bf16 v[88:91], v[180:183], v[220:223], v[88:91]
	v_mfma_f32_16x16x32_bf16 v[76:79], v[146:149], v[224:227], v[76:79]
	v_mfma_f32_16x16x32_bf16 v[76:79], v[166:169], v[230:233], v[76:79]
	v_mfma_f32_16x16x32_bf16 v[72:75], v[176:179], v[224:227], v[72:75]
	v_mfma_f32_16x16x32_bf16 v[72:75], v[180:183], v[230:233], v[72:75]
	v_mfma_f32_16x16x32_bf16 v[116:119], v[184:187], v[200:203], v[116:119]
	v_mfma_f32_16x16x32_bf16 v[116:119], v[188:191], v[204:207], v[116:119]
	v_mfma_f32_16x16x32_bf16 v[112:115], v[192:195], v[200:203], v[112:115]
	v_mfma_f32_16x16x32_bf16 v[112:115], v[196:199], v[204:207], v[112:115]
	v_mfma_f32_16x16x32_bf16 v[100:103], v[184:187], v[208:211], v[100:103]
	v_mfma_f32_16x16x32_bf16 v[100:103], v[188:191], v[212:215], v[100:103]
	v_mfma_f32_16x16x32_bf16 v[96:99], v[192:195], v[208:211], v[96:99]
	v_mfma_f32_16x16x32_bf16 v[96:99], v[196:199], v[212:215], v[96:99]
	v_mfma_f32_16x16x32_bf16 v[84:87], v[184:187], v[216:219], v[84:87]
	v_mfma_f32_16x16x32_bf16 v[84:87], v[188:191], v[220:223], v[84:87]
	v_mfma_f32_16x16x32_bf16 v[80:83], v[192:195], v[216:219], v[80:83]
	v_mfma_f32_16x16x32_bf16 v[80:83], v[196:199], v[220:223], v[80:83]
	v_mfma_f32_16x16x32_bf16 v[68:71], v[184:187], v[224:227], v[68:71]
	v_mfma_f32_16x16x32_bf16 v[68:71], v[188:191], v[230:233], v[68:71]
	v_mfma_f32_16x16x32_bf16 v[64:67], v[192:195], v[224:227], v[64:67]
	v_mfma_f32_16x16x32_bf16 v[64:67], v[196:199], v[230:233], v[64:67]
	s_barrier
	s_setprio 0
	s_add_i32 s38, s68, s42
	v_lshl_add_u64 v[150:151], v[150:151], 0, s[14:15]
	s_mov_b32 m0, s38
	ds_read_b128 v[200:203], v174 offset:49152
	ds_read_b128 v[204:207], v174 offset:50176
	ds_read_b128 v[208:211], v174 offset:51200
	ds_read_b128 v[212:215], v174 offset:52224
	ds_read_b128 v[216:219], v174 offset:53248
	ds_read_b128 v[220:223], v174 offset:54272
	ds_read_b128 v[224:227], v174 offset:55296
	ds_read_b128 v[230:233], v174 offset:56320
	global_load_lds_dwordx4 v[150:151], off
	s_add_i32 m0, s38, 0x2000
	s_add_u32 s36, s36, 0x40080
	v_lshl_add_u64 v[150:151], v[154:155], 0, s[14:15]
	s_addc_u32 s37, s37, 0
	s_add_i32 s38, s69, s42
	global_load_lds_dwordx4 v[150:151], off
	v_lshl_add_u64 v[150:151], s[36:37], 0, v[132:133]
	s_mov_b32 m0, s38
	s_nop 0
	global_load_lds_dwordx4 v[150:151], off
	v_lshl_add_u64 v[150:151], s[36:37], 0, v[128:129]
	s_add_i32 m0, s38, 0x2000
	s_nop 0
	global_load_lds_dwordx4 v[150:151], off
	v_lshl_add_u64 v[150:151], v[158:159], 0, s[14:15]
	s_mov_b32 m0, s49
	s_nop 0
	global_load_lds_dwordx4 v[150:151], off
	v_lshl_add_u64 v[150:151], v[162:163], 0, s[14:15]
	s_mov_b32 m0, s50
	s_nop 0
	global_load_lds_dwordx4 v[150:151], off
	s_waitcnt vmcnt(8)
	s_waitcnt lgkmcnt(0)
	s_setprio 1
	s_barrier
	v_mfma_f32_16x16x32_bf16 v[60:63], v[146:149], v[200:203], v[60:63]
	v_mfma_f32_16x16x32_bf16 v[60:63], v[166:169], v[204:207], v[60:63]
	v_mfma_f32_16x16x32_bf16 v[56:59], v[176:179], v[200:203], v[56:59]
	v_mfma_f32_16x16x32_bf16 v[56:59], v[180:183], v[204:207], v[56:59]
	v_mfma_f32_16x16x32_bf16 v[44:47], v[146:149], v[208:211], v[44:47]
	v_mfma_f32_16x16x32_bf16 v[44:47], v[166:169], v[212:215], v[44:47]
	v_mfma_f32_16x16x32_bf16 v[40:43], v[176:179], v[208:211], v[40:43]
	v_mfma_f32_16x16x32_bf16 v[40:43], v[180:183], v[212:215], v[40:43]
	v_mfma_f32_16x16x32_bf16 v[28:31], v[146:149], v[216:219], v[28:31]
	v_mfma_f32_16x16x32_bf16 v[28:31], v[166:169], v[220:223], v[28:31]
	v_mfma_f32_16x16x32_bf16 v[24:27], v[176:179], v[216:219], v[24:27]
	v_mfma_f32_16x16x32_bf16 v[24:27], v[180:183], v[220:223], v[24:27]
	v_mfma_f32_16x16x32_bf16 v[12:15], v[146:149], v[224:227], v[12:15]
	v_mfma_f32_16x16x32_bf16 v[12:15], v[166:169], v[230:233], v[12:15]
	v_mfma_f32_16x16x32_bf16 v[8:11], v[176:179], v[224:227], v[8:11]
	v_mfma_f32_16x16x32_bf16 v[8:11], v[180:183], v[230:233], v[8:11]
	v_mfma_f32_16x16x32_bf16 v[52:55], v[184:187], v[200:203], v[52:55]
	v_mfma_f32_16x16x32_bf16 v[52:55], v[188:191], v[204:207], v[52:55]
	v_mfma_f32_16x16x32_bf16 v[48:51], v[192:195], v[200:203], v[48:51]
	v_mfma_f32_16x16x32_bf16 v[48:51], v[196:199], v[204:207], v[48:51]
	v_mfma_f32_16x16x32_bf16 v[36:39], v[184:187], v[208:211], v[36:39]
	v_mfma_f32_16x16x32_bf16 v[36:39], v[188:191], v[212:215], v[36:39]
	v_mfma_f32_16x16x32_bf16 v[32:35], v[192:195], v[208:211], v[32:35]
	v_mfma_f32_16x16x32_bf16 v[32:35], v[196:199], v[212:215], v[32:35]
	v_mfma_f32_16x16x32_bf16 v[20:23], v[184:187], v[216:219], v[20:23]
	v_mfma_f32_16x16x32_bf16 v[20:23], v[188:191], v[220:223], v[20:23]
	v_mfma_f32_16x16x32_bf16 v[16:19], v[192:195], v[216:219], v[16:19]
	v_mfma_f32_16x16x32_bf16 v[16:19], v[196:199], v[220:223], v[16:19]
	v_mfma_f32_16x16x32_bf16 v[4:7], v[184:187], v[224:227], v[4:7]
	v_mfma_f32_16x16x32_bf16 v[4:7], v[188:191], v[230:233], v[4:7]
	v_mfma_f32_16x16x32_bf16 v[0:3], v[192:195], v[224:227], v[0:3]
	v_mfma_f32_16x16x32_bf16 v[0:3], v[196:199], v[230:233], v[0:3]
	s_barrier
	s_setprio 0
	s_add_i32 s67, s67, 2
	s_add_u32 s4, s4, 0x100
	s_addc_u32 s5, s5, 0
	s_add_u32 s59, s59, 0x100
	s_addc_u32 s66, s66, 0
	s_cmp_gt_u32 s67, 13
	s_cbranch_scc0 .LBB0_759
	s_and_b64 vcc, exec, s[16:17]
	s_cbranch_vccz .LBB0_762
	s_barrier

.LBB0_835:
	s_add_u32 s80, s22, 0x100
	s_addc_u32 s81, s23, 0
	s_mov_b32 s82, -2
	ds_read_b128 v[112:115], v203
	ds_read_b128 v[116:119], v203 offset:1024
	ds_read_b128 v[136:139], v203 offset:2048
	ds_read_b128 v[140:143], v203 offset:3072
	ds_read_b128 v[144:147], v204
	ds_read_b128 v[148:151], v204 offset:1024
	ds_read_b128 v[152:155], v204 offset:2048
	ds_read_b128 v[156:159], v204 offset:3072
	s_add_u32 s22, s20, 0x100
	s_addc_u32 s23, s21, 0
	s_cmp_eq_u32 s82, 40
	s_cselect_b32 s37, s7, s23
	s_cselect_b32 s36, s6, s22
	s_cselect_b32 s27, s19, s81
	s_cselect_b32 s26, s18, s80
	v_lshl_add_u64 v[200:201], s[20:21], 0, v[186:187]
	s_add_i32 m0, s43, 0xc000
	ds_read_b128 v[160:163], v205
	ds_read_b128 v[164:167], v205 offset:1024
	ds_read_b128 v[168:171], v205 offset:2048
	ds_read_b128 v[172:175], v205 offset:3072
	ds_read_b128 v[206:209], v205 offset:4096
	ds_read_b128 v[210:213], v205 offset:5120
	ds_read_b128 v[214:217], v205 offset:6144
	ds_read_b128 v[218:221], v205 offset:7168
	global_load_lds_dwordx4 v[200:201], off
	v_lshl_add_u64 v[200:201], s[20:21], 0, v[188:189]
	s_add_i32 m0, s43, 0xe000
	s_nop 0
	global_load_lds_dwordx4 v[200:201], off
	s_waitcnt vmcnt(8)
	s_waitcnt lgkmcnt(0)
	s_setprio 1
	s_barrier
	v_mfma_f32_16x16x32_bf16 v[132:135], v[112:115], v[160:163], 0
	v_mfma_f32_16x16x32_bf16 v[132:135], v[116:119], v[164:167], v[132:135]
	v_mfma_f32_16x16x32_bf16 v[128:131], v[136:139], v[160:163], 0
	v_mfma_f32_16x16x32_bf16 v[128:131], v[140:143], v[164:167], v[128:131]
	v_mfma_f32_16x16x32_bf16 v[108:111], v[112:115], v[168:171], 0
	v_mfma_f32_16x16x32_bf16 v[108:111], v[116:119], v[172:175], v[108:111]
	v_mfma_f32_16x16x32_bf16 v[104:107], v[136:139], v[168:171], 0
	v_mfma_f32_16x16x32_bf16 v[104:107], v[140:143], v[172:175], v[104:107]
	v_mfma_f32_16x16x32_bf16 v[92:95], v[112:115], v[206:209], 0
	v_mfma_f32_16x16x32_bf16 v[92:95], v[116:119], v[210:213], v[92:95]
	v_mfma_f32_16x16x32_bf16 v[88:91], v[136:139], v[206:209], 0
	v_mfma_f32_16x16x32_bf16 v[88:91], v[140:143], v[210:213], v[88:91]
	v_mfma_f32_16x16x32_bf16 v[76:79], v[112:115], v[214:217], 0
	v_mfma_f32_16x16x32_bf16 v[76:79], v[116:119], v[218:221], v[76:79]
	v_mfma_f32_16x16x32_bf16 v[72:75], v[136:139], v[214:217], 0
	v_mfma_f32_16x16x32_bf16 v[72:75], v[140:143], v[218:221], v[72:75]
	v_mfma_f32_16x16x32_bf16 v[124:127], v[144:147], v[160:163], 0
	v_mfma_f32_16x16x32_bf16 v[124:127], v[148:151], v[164:167], v[124:127]
	v_mfma_f32_16x16x32_bf16 v[120:123], v[152:155], v[160:163], 0
	v_mfma_f32_16x16x32_bf16 v[120:123], v[156:159], v[164:167], v[120:123]
	v_mfma_f32_16x16x32_bf16 v[100:103], v[144:147], v[168:171], 0
	v_mfma_f32_16x16x32_bf16 v[100:103], v[148:151], v[172:175], v[100:103]
	v_mfma_f32_16x16x32_bf16 v[96:99], v[152:155], v[168:171], 0
	v_mfma_f32_16x16x32_bf16 v[96:99], v[156:159], v[172:175], v[96:99]
	v_mfma_f32_16x16x32_bf16 v[84:87], v[144:147], v[206:209], 0
	v_mfma_f32_16x16x32_bf16 v[84:87], v[148:151], v[210:213], v[84:87]
	v_mfma_f32_16x16x32_bf16 v[80:83], v[152:155], v[206:209], 0
	v_mfma_f32_16x16x32_bf16 v[80:83], v[156:159], v[210:213], v[80:83]
	v_mfma_f32_16x16x32_bf16 v[68:71], v[144:147], v[214:217], 0
	v_mfma_f32_16x16x32_bf16 v[68:71], v[148:151], v[218:221], v[68:71]
	v_mfma_f32_16x16x32_bf16 v[64:67], v[152:155], v[214:217], 0
	v_mfma_f32_16x16x32_bf16 v[64:67], v[156:159], v[218:221], v[64:67]
	s_barrier
	s_setprio 0
	s_add_i32 s20, s59, s40
	v_lshl_add_u64 v[200:201], s[26:27], 0, v[180:181]
	s_mov_b32 m0, s20
	ds_read_b128 v[160:163], v205 offset:16384
	ds_read_b128 v[164:167], v205 offset:17408
	ds_read_b128 v[168:171], v205 offset:18432
	ds_read_b128 v[172:175], v205 offset:19456
	ds_read_b128 v[206:209], v205 offset:20480
	ds_read_b128 v[210:213], v205 offset:21504
	ds_read_b128 v[214:217], v205 offset:22528
	ds_read_b128 v[218:221], v205 offset:23552
	global_load_lds_dwordx4 v[200:201], off
	s_add_i32 m0, s20, 0x2000
	s_add_u32 s20, s26, 0xb0000
	v_lshl_add_u64 v[222:223], s[26:27], 0, v[176:177]
	s_addc_u32 s21, s27, 0
	s_add_i32 s83, s66, s40
	global_load_lds_dwordx4 v[222:223], off
	v_lshl_add_u64 v[224:225], s[20:21], 0, v[180:181]
	s_mov_b32 m0, s83
	v_lshl_add_u64 v[226:227], s[36:37], 0, v[178:179]
	global_load_lds_dwordx4 v[224:225], off
	v_lshl_add_u64 v[224:225], s[20:21], 0, v[176:177]
	s_add_i32 m0, s83, 0x2000
	s_nop 0
	global_load_lds_dwordx4 v[224:225], off
	v_lshl_add_u64 v[224:225], s[36:37], 0, v[182:183]
	s_mov_b32 m0, s43
	s_nop 0
	global_load_lds_dwordx4 v[224:225], off
	s_mov_b32 m0, s44
	s_nop 0
	global_load_lds_dwordx4 v[226:227], off
	s_waitcnt vmcnt(8)
	s_waitcnt lgkmcnt(0)
	s_setprio 1
	s_barrier
	v_mfma_f32_16x16x32_bf16 v[60:63], v[112:115], v[160:163], 0
	v_mfma_f32_16x16x32_bf16 v[60:63], v[116:119], v[164:167], v[60:63]
	v_mfma_f32_16x16x32_bf16 v[56:59], v[136:139], v[160:163], 0
	v_mfma_f32_16x16x32_bf16 v[56:59], v[140:143], v[164:167], v[56:59]
	v_mfma_f32_16x16x32_bf16 v[44:47], v[112:115], v[168:171], 0
	v_mfma_f32_16x16x32_bf16 v[44:47], v[116:119], v[172:175], v[44:47]
	v_mfma_f32_16x16x32_bf16 v[40:43], v[136:139], v[168:171], 0
	v_mfma_f32_16x16x32_bf16 v[40:43], v[140:143], v[172:175], v[40:43]
	v_mfma_f32_16x16x32_bf16 v[28:31], v[112:115], v[206:209], 0
	v_mfma_f32_16x16x32_bf16 v[28:31], v[116:119], v[210:213], v[28:31]
	v_mfma_f32_16x16x32_bf16 v[24:27], v[136:139], v[206:209], 0
	v_mfma_f32_16x16x32_bf16 v[24:27], v[140:143], v[210:213], v[24:27]
	v_mfma_f32_16x16x32_bf16 v[12:15], v[112:115], v[214:217], 0
	v_mfma_f32_16x16x32_bf16 v[12:15], v[116:119], v[218:221], v[12:15]
	v_mfma_f32_16x16x32_bf16 v[8:11], v[136:139], v[214:217], 0
	v_mfma_f32_16x16x32_bf16 v[8:11], v[140:143], v[218:221], v[8:11]
	v_mfma_f32_16x16x32_bf16 v[52:55], v[144:147], v[160:163], 0
	v_mfma_f32_16x16x32_bf16 v[52:55], v[148:151], v[164:167], v[52:55]
	v_mfma_f32_16x16x32_bf16 v[48:51], v[152:155], v[160:163], 0
	v_mfma_f32_16x16x32_bf16 v[48:51], v[156:159], v[164:167], v[48:51]
	v_mfma_f32_16x16x32_bf16 v[36:39], v[144:147], v[168:171], 0
	v_mfma_f32_16x16x32_bf16 v[36:39], v[148:151], v[172:175], v[36:39]
	v_mfma_f32_16x16x32_bf16 v[32:35], v[152:155], v[168:171], 0
	v_mfma_f32_16x16x32_bf16 v[32:35], v[156:159], v[172:175], v[32:35]
	v_mfma_f32_16x16x32_bf16 v[20:23], v[144:147], v[206:209], 0
	v_mfma_f32_16x16x32_bf16 v[20:23], v[148:151], v[210:213], v[20:23]
	v_mfma_f32_16x16x32_bf16 v[16:19], v[152:155], v[206:209], 0
	v_mfma_f32_16x16x32_bf16 v[16:19], v[156:159], v[210:213], v[16:19]
	v_mfma_f32_16x16x32_bf16 v[4:7], v[144:147], v[214:217], 0
	v_mfma_f32_16x16x32_bf16 v[4:7], v[148:151], v[218:221], v[4:7]
	v_mfma_f32_16x16x32_bf16 v[0:3], v[152:155], v[214:217], 0
	v_mfma_f32_16x16x32_bf16 v[0:3], v[156:159], v[218:221], v[0:3]
	s_barrier
	s_setprio 0
	s_add_i32 s83, 0, 0x18000
	s_add_i32 s85, 0, 0x1c000
	v_add_u32_e32 v140, s83, v202
	v_add_u32_e32 v156, s85, v202
	ds_read_b128 v[112:115], v140
	ds_read_b128 v[116:119], v140 offset:1024
	ds_read_b128 v[136:139], v140 offset:2048
	ds_read_b128 v[140:143], v140 offset:3072
	ds_read_b128 v[144:147], v156
	ds_read_b128 v[148:151], v156 offset:1024
	ds_read_b128 v[152:155], v156 offset:2048
	ds_read_b128 v[156:159], v156 offset:3072
	s_add_u32 s20, s36, 0xb0000
	s_addc_u32 s21, s37, 0
	s_mov_b32 m0, s45
	v_lshl_add_u64 v[230:231], s[20:21], 0, v[182:183]
	ds_read_b128 v[160:163], v205 offset:32768
	ds_read_b128 v[164:167], v205 offset:33792
	ds_read_b128 v[168:171], v205 offset:34816
	ds_read_b128 v[172:175], v205 offset:35840
	ds_read_b128 v[206:209], v205 offset:36864
	ds_read_b128 v[210:213], v205 offset:37888
	ds_read_b128 v[214:217], v205 offset:38912
	ds_read_b128 v[218:221], v205 offset:39936
	global_load_lds_dwordx4 v[230:231], off
	v_lshl_add_u64 v[230:231], s[20:21], 0, v[178:179]
	s_mov_b32 m0, s46
	s_nop 0
	global_load_lds_dwordx4 v[230:231], off
	s_waitcnt vmcnt(8)
	s_waitcnt lgkmcnt(0)
	s_setprio 1
	s_barrier
	v_mfma_f32_16x16x32_bf16 v[132:135], v[112:115], v[160:163], v[132:135]
	v_mfma_f32_16x16x32_bf16 v[132:135], v[116:119], v[164:167], v[132:135]
	v_mfma_f32_16x16x32_bf16 v[128:131], v[136:139], v[160:163], v[128:131]
	v_mfma_f32_16x16x32_bf16 v[128:131], v[140:143], v[164:167], v[128:131]
	v_mfma_f32_16x16x32_bf16 v[108:111], v[112:115], v[168:171], v[108:111]
	v_mfma_f32_16x16x32_bf16 v[108:111], v[116:119], v[172:175], v[108:111]
	v_mfma_f32_16x16x32_bf16 v[104:107], v[136:139], v[168:171], v[104:107]
	v_mfma_f32_16x16x32_bf16 v[104:107], v[140:143], v[172:175], v[104:107]
	v_mfma_f32_16x16x32_bf16 v[92:95], v[112:115], v[206:209], v[92:95]
	v_mfma_f32_16x16x32_bf16 v[92:95], v[116:119], v[210:213], v[92:95]
	v_mfma_f32_16x16x32_bf16 v[88:91], v[136:139], v[206:209], v[88:91]
	v_mfma_f32_16x16x32_bf16 v[88:91], v[140:143], v[210:213], v[88:91]
	v_mfma_f32_16x16x32_bf16 v[76:79], v[112:115], v[214:217], v[76:79]
	v_mfma_f32_16x16x32_bf16 v[76:79], v[116:119], v[218:221], v[76:79]
	v_mfma_f32_16x16x32_bf16 v[72:75], v[136:139], v[214:217], v[72:75]
	v_mfma_f32_16x16x32_bf16 v[72:75], v[140:143], v[218:221], v[72:75]
	v_mfma_f32_16x16x32_bf16 v[124:127], v[144:147], v[160:163], v[124:127]
	v_mfma_f32_16x16x32_bf16 v[124:127], v[148:151], v[164:167], v[124:127]
	v_mfma_f32_16x16x32_bf16 v[120:123], v[152:155], v[160:163], v[120:123]
	v_mfma_f32_16x16x32_bf16 v[120:123], v[156:159], v[164:167], v[120:123]
	v_mfma_f32_16x16x32_bf16 v[100:103], v[144:147], v[168:171], v[100:103]
	v_mfma_f32_16x16x32_bf16 v[100:103], v[148:151], v[172:175], v[100:103]
	v_mfma_f32_16x16x32_bf16 v[96:99], v[152:155], v[168:171], v[96:99]
	v_mfma_f32_16x16x32_bf16 v[96:99], v[156:159], v[172:175], v[96:99]
	v_mfma_f32_16x16x32_bf16 v[84:87], v[144:147], v[206:209], v[84:87]
	v_mfma_f32_16x16x32_bf16 v[84:87], v[148:151], v[210:213], v[84:87]
	v_mfma_f32_16x16x32_bf16 v[80:83], v[152:155], v[206:209], v[80:83]
	v_mfma_f32_16x16x32_bf16 v[80:83], v[156:159], v[210:213], v[80:83]
	v_mfma_f32_16x16x32_bf16 v[68:71], v[144:147], v[214:217], v[68:71]
	v_mfma_f32_16x16x32_bf16 v[68:71], v[148:151], v[218:221], v[68:71]
	v_mfma_f32_16x16x32_bf16 v[64:67], v[152:155], v[214:217], v[64:67]
	v_mfma_f32_16x16x32_bf16 v[64:67], v[156:159], v[218:221], v[64:67]
	s_barrier
	s_setprio 0
	s_add_i32 s20, s83, s40
	v_lshl_add_u64 v[200:201], v[200:201], 0, s[14:15]
	s_mov_b32 m0, s20
	ds_read_b128 v[160:163], v205 offset:49152
	ds_read_b128 v[164:167], v205 offset:50176
	ds_read_b128 v[168:171], v205 offset:51200
	ds_read_b128 v[172:175], v205 offset:52224
	ds_read_b128 v[206:209], v205 offset:53248
	ds_read_b128 v[210:213], v205 offset:54272
	ds_read_b128 v[214:217], v205 offset:55296
	ds_read_b128 v[218:221], v205 offset:56320
	global_load_lds_dwordx4 v[200:201], off
	s_add_i32 m0, s20, 0x2000
	s_add_u32 s20, s26, 0xb0080
	v_lshl_add_u64 v[200:201], v[222:223], 0, s[14:15]
	s_addc_u32 s21, s27, 0
	s_add_i32 s26, s85, s40
	global_load_lds_dwordx4 v[200:201], off
	v_lshl_add_u64 v[200:201], s[20:21], 0, v[180:181]
	s_mov_b32 m0, s26
	s_nop 0
	global_load_lds_dwordx4 v[200:201], off
	v_lshl_add_u64 v[200:201], s[20:21], 0, v[176:177]
	s_add_i32 m0, s26, 0x2000
	s_nop 0
	global_load_lds_dwordx4 v[200:201], off
	v_lshl_add_u64 v[200:201], v[224:225], 0, s[14:15]
	s_mov_b32 m0, s52
	s_nop 0
	global_load_lds_dwordx4 v[200:201], off
	v_lshl_add_u64 v[200:201], v[226:227], 0, s[14:15]
	s_mov_b32 m0, s53
	s_nop 0
	global_load_lds_dwordx4 v[200:201], off
	s_waitcnt vmcnt(8)
	s_waitcnt lgkmcnt(0)
	s_setprio 1
	s_barrier
	v_mfma_f32_16x16x32_bf16 v[60:63], v[112:115], v[160:163], v[60:63]
	v_mfma_f32_16x16x32_bf16 v[60:63], v[116:119], v[164:167], v[60:63]
	v_mfma_f32_16x16x32_bf16 v[56:59], v[136:139], v[160:163], v[56:59]
	v_mfma_f32_16x16x32_bf16 v[56:59], v[140:143], v[164:167], v[56:59]
	v_mfma_f32_16x16x32_bf16 v[44:47], v[112:115], v[168:171], v[44:47]
	v_mfma_f32_16x16x32_bf16 v[44:47], v[116:119], v[172:175], v[44:47]
	v_mfma_f32_16x16x32_bf16 v[40:43], v[136:139], v[168:171], v[40:43]
	v_mfma_f32_16x16x32_bf16 v[40:43], v[140:143], v[172:175], v[40:43]
	v_mfma_f32_16x16x32_bf16 v[28:31], v[112:115], v[206:209], v[28:31]
	v_mfma_f32_16x16x32_bf16 v[28:31], v[116:119], v[210:213], v[28:31]
	v_mfma_f32_16x16x32_bf16 v[24:27], v[136:139], v[206:209], v[24:27]
	v_mfma_f32_16x16x32_bf16 v[24:27], v[140:143], v[210:213], v[24:27]
	v_mfma_f32_16x16x32_bf16 v[12:15], v[112:115], v[214:217], v[12:15]
	v_mfma_f32_16x16x32_bf16 v[12:15], v[116:119], v[218:221], v[12:15]
	v_mfma_f32_16x16x32_bf16 v[8:11], v[136:139], v[214:217], v[8:11]
	v_mfma_f32_16x16x32_bf16 v[8:11], v[140:143], v[218:221], v[8:11]
	v_mfma_f32_16x16x32_bf16 v[52:55], v[144:147], v[160:163], v[52:55]
	v_mfma_f32_16x16x32_bf16 v[52:55], v[148:151], v[164:167], v[52:55]
	v_mfma_f32_16x16x32_bf16 v[48:51], v[152:155], v[160:163], v[48:51]
	v_mfma_f32_16x16x32_bf16 v[48:51], v[156:159], v[164:167], v[48:51]
	v_mfma_f32_16x16x32_bf16 v[36:39], v[144:147], v[168:171], v[36:39]
	v_mfma_f32_16x16x32_bf16 v[36:39], v[148:151], v[172:175], v[36:39]
	v_mfma_f32_16x16x32_bf16 v[32:35], v[152:155], v[168:171], v[32:35]
	v_mfma_f32_16x16x32_bf16 v[32:35], v[156:159], v[172:175], v[32:35]
	v_mfma_f32_16x16x32_bf16 v[20:23], v[144:147], v[206:209], v[20:23]
	v_mfma_f32_16x16x32_bf16 v[20:23], v[148:151], v[210:213], v[20:23]
	v_mfma_f32_16x16x32_bf16 v[16:19], v[152:155], v[206:209], v[16:19]
	v_mfma_f32_16x16x32_bf16 v[16:19], v[156:159], v[210:213], v[16:19]
	v_mfma_f32_16x16x32_bf16 v[4:7], v[144:147], v[214:217], v[4:7]
	v_mfma_f32_16x16x32_bf16 v[4:7], v[148:151], v[218:221], v[4:7]
	v_mfma_f32_16x16x32_bf16 v[0:3], v[152:155], v[214:217], v[0:3]
	v_mfma_f32_16x16x32_bf16 v[0:3], v[156:159], v[218:221], v[0:3]
	s_barrier
	s_setprio 0
	s_add_i32 s82, s82, 2
	s_add_u32 s80, s80, 0x100
	s_addc_u32 s81, s81, 0
	s_cmp_gt_u32 s82, 41
	s_mov_b64 s[20:21], s[22:23]
.LBB0_836:
	ds_read_b128 v[112:115], v203
	ds_read_b128 v[116:119], v203 offset:1024
	ds_read_b128 v[136:139], v203 offset:2048
	ds_read_b128 v[140:143], v203 offset:3072
	ds_read_b128 v[144:147], v204
	ds_read_b128 v[148:151], v204 offset:1024
	ds_read_b128 v[152:155], v204 offset:2048
	ds_read_b128 v[156:159], v204 offset:3072
	s_add_u32 s22, s20, 0x100
	s_addc_u32 s23, s21, 0
	s_cmp_eq_u32 s82, 40
	s_cselect_b32 s37, s7, s23
	s_cselect_b32 s36, s6, s22
	s_cselect_b32 s27, s19, s81
	s_cselect_b32 s26, s18, s80
	v_lshl_add_u64 v[200:201], s[20:21], 0, v[186:187]
	s_add_i32 m0, s43, 0xc000
	ds_read_b128 v[160:163], v205
	ds_read_b128 v[164:167], v205 offset:1024
	ds_read_b128 v[168:171], v205 offset:2048
	ds_read_b128 v[172:175], v205 offset:3072
	ds_read_b128 v[206:209], v205 offset:4096
	ds_read_b128 v[210:213], v205 offset:5120
	ds_read_b128 v[214:217], v205 offset:6144
	ds_read_b128 v[218:221], v205 offset:7168
	global_load_lds_dwordx4 v[200:201], off
	v_lshl_add_u64 v[200:201], s[20:21], 0, v[188:189]
	s_add_i32 m0, s43, 0xe000
	s_nop 0
	global_load_lds_dwordx4 v[200:201], off
	s_waitcnt vmcnt(8)
	s_waitcnt lgkmcnt(0)
	s_setprio 1
	s_barrier
	v_mfma_f32_16x16x32_bf16 v[132:135], v[112:115], v[160:163], v[132:135]
	v_mfma_f32_16x16x32_bf16 v[132:135], v[116:119], v[164:167], v[132:135]
	v_mfma_f32_16x16x32_bf16 v[128:131], v[136:139], v[160:163], v[128:131]
	v_mfma_f32_16x16x32_bf16 v[128:131], v[140:143], v[164:167], v[128:131]
	v_mfma_f32_16x16x32_bf16 v[108:111], v[112:115], v[168:171], v[108:111]
	v_mfma_f32_16x16x32_bf16 v[108:111], v[116:119], v[172:175], v[108:111]
	v_mfma_f32_16x16x32_bf16 v[104:107], v[136:139], v[168:171], v[104:107]
	v_mfma_f32_16x16x32_bf16 v[104:107], v[140:143], v[172:175], v[104:107]
	v_mfma_f32_16x16x32_bf16 v[92:95], v[112:115], v[206:209], v[92:95]
	v_mfma_f32_16x16x32_bf16 v[92:95], v[116:119], v[210:213], v[92:95]
	v_mfma_f32_16x16x32_bf16 v[88:91], v[136:139], v[206:209], v[88:91]
	v_mfma_f32_16x16x32_bf16 v[88:91], v[140:143], v[210:213], v[88:91]
	v_mfma_f32_16x16x32_bf16 v[76:79], v[112:115], v[214:217], v[76:79]
	v_mfma_f32_16x16x32_bf16 v[76:79], v[116:119], v[218:221], v[76:79]
	v_mfma_f32_16x16x32_bf16 v[72:75], v[136:139], v[214:217], v[72:75]
	v_mfma_f32_16x16x32_bf16 v[72:75], v[140:143], v[218:221], v[72:75]
	v_mfma_f32_16x16x32_bf16 v[124:127], v[144:147], v[160:163], v[124:127]
	v_mfma_f32_16x16x32_bf16 v[124:127], v[148:151], v[164:167], v[124:127]
	v_mfma_f32_16x16x32_bf16 v[120:123], v[152:155], v[160:163], v[120:123]
	v_mfma_f32_16x16x32_bf16 v[120:123], v[156:159], v[164:167], v[120:123]
	v_mfma_f32_16x16x32_bf16 v[100:103], v[144:147], v[168:171], v[100:103]
	v_mfma_f32_16x16x32_bf16 v[100:103], v[148:151], v[172:175], v[100:103]
	v_mfma_f32_16x16x32_bf16 v[96:99], v[152:155], v[168:171], v[96:99]
	v_mfma_f32_16x16x32_bf16 v[96:99], v[156:159], v[172:175], v[96:99]
	v_mfma_f32_16x16x32_bf16 v[84:87], v[144:147], v[206:209], v[84:87]
	v_mfma_f32_16x16x32_bf16 v[84:87], v[148:151], v[210:213], v[84:87]
	v_mfma_f32_16x16x32_bf16 v[80:83], v[152:155], v[206:209], v[80:83]
	v_mfma_f32_16x16x32_bf16 v[80:83], v[156:159], v[210:213], v[80:83]
	v_mfma_f32_16x16x32_bf16 v[68:71], v[144:147], v[214:217], v[68:71]
	v_mfma_f32_16x16x32_bf16 v[68:71], v[148:151], v[218:221], v[68:71]
	v_mfma_f32_16x16x32_bf16 v[64:67], v[152:155], v[214:217], v[64:67]
	v_mfma_f32_16x16x32_bf16 v[64:67], v[156:159], v[218:221], v[64:67]
	s_barrier
	s_setprio 0
	s_add_i32 s20, s59, s40
	v_lshl_add_u64 v[200:201], s[26:27], 0, v[180:181]
	s_mov_b32 m0, s20
	ds_read_b128 v[160:163], v205 offset:16384
	ds_read_b128 v[164:167], v205 offset:17408
	ds_read_b128 v[168:171], v205 offset:18432
	ds_read_b128 v[172:175], v205 offset:19456
	ds_read_b128 v[206:209], v205 offset:20480
	ds_read_b128 v[210:213], v205 offset:21504
	ds_read_b128 v[214:217], v205 offset:22528
	ds_read_b128 v[218:221], v205 offset:23552
	global_load_lds_dwordx4 v[200:201], off
	s_add_i32 m0, s20, 0x2000
	s_add_u32 s20, s26, 0xb0000
	v_lshl_add_u64 v[222:223], s[26:27], 0, v[176:177]
	s_addc_u32 s21, s27, 0
	s_add_i32 s83, s66, s40
	global_load_lds_dwordx4 v[222:223], off
	v_lshl_add_u64 v[224:225], s[20:21], 0, v[180:181]
	s_mov_b32 m0, s83
	v_lshl_add_u64 v[226:227], s[36:37], 0, v[178:179]
	global_load_lds_dwordx4 v[224:225], off
	v_lshl_add_u64 v[224:225], s[20:21], 0, v[176:177]
	s_add_i32 m0, s83, 0x2000
	s_nop 0
	global_load_lds_dwordx4 v[224:225], off
	v_lshl_add_u64 v[224:225], s[36:37], 0, v[182:183]
	s_mov_b32 m0, s43
	s_nop 0
	global_load_lds_dwordx4 v[224:225], off
	s_mov_b32 m0, s44
	s_nop 0
	global_load_lds_dwordx4 v[226:227], off
	s_waitcnt vmcnt(8)
	s_waitcnt lgkmcnt(0)
	s_setprio 1
	s_barrier
	v_mfma_f32_16x16x32_bf16 v[60:63], v[112:115], v[160:163], v[60:63]
	v_mfma_f32_16x16x32_bf16 v[60:63], v[116:119], v[164:167], v[60:63]
	v_mfma_f32_16x16x32_bf16 v[56:59], v[136:139], v[160:163], v[56:59]
	v_mfma_f32_16x16x32_bf16 v[56:59], v[140:143], v[164:167], v[56:59]
	v_mfma_f32_16x16x32_bf16 v[44:47], v[112:115], v[168:171], v[44:47]
	v_mfma_f32_16x16x32_bf16 v[44:47], v[116:119], v[172:175], v[44:47]
	v_mfma_f32_16x16x32_bf16 v[40:43], v[136:139], v[168:171], v[40:43]
	v_mfma_f32_16x16x32_bf16 v[40:43], v[140:143], v[172:175], v[40:43]
	v_mfma_f32_16x16x32_bf16 v[28:31], v[112:115], v[206:209], v[28:31]
	v_mfma_f32_16x16x32_bf16 v[28:31], v[116:119], v[210:213], v[28:31]
	v_mfma_f32_16x16x32_bf16 v[24:27], v[136:139], v[206:209], v[24:27]
	v_mfma_f32_16x16x32_bf16 v[24:27], v[140:143], v[210:213], v[24:27]
	v_mfma_f32_16x16x32_bf16 v[12:15], v[112:115], v[214:217], v[12:15]
	v_mfma_f32_16x16x32_bf16 v[12:15], v[116:119], v[218:221], v[12:15]
	v_mfma_f32_16x16x32_bf16 v[8:11], v[136:139], v[214:217], v[8:11]
	v_mfma_f32_16x16x32_bf16 v[8:11], v[140:143], v[218:221], v[8:11]
	v_mfma_f32_16x16x32_bf16 v[52:55], v[144:147], v[160:163], v[52:55]
	v_mfma_f32_16x16x32_bf16 v[52:55], v[148:151], v[164:167], v[52:55]
	v_mfma_f32_16x16x32_bf16 v[48:51], v[152:155], v[160:163], v[48:51]
	v_mfma_f32_16x16x32_bf16 v[48:51], v[156:159], v[164:167], v[48:51]
	v_mfma_f32_16x16x32_bf16 v[36:39], v[144:147], v[168:171], v[36:39]
	v_mfma_f32_16x16x32_bf16 v[36:39], v[148:151], v[172:175], v[36:39]
	v_mfma_f32_16x16x32_bf16 v[32:35], v[152:155], v[168:171], v[32:35]
	v_mfma_f32_16x16x32_bf16 v[32:35], v[156:159], v[172:175], v[32:35]
	v_mfma_f32_16x16x32_bf16 v[20:23], v[144:147], v[206:209], v[20:23]
	v_mfma_f32_16x16x32_bf16 v[20:23], v[148:151], v[210:213], v[20:23]
	v_mfma_f32_16x16x32_bf16 v[16:19], v[152:155], v[206:209], v[16:19]
	v_mfma_f32_16x16x32_bf16 v[16:19], v[156:159], v[210:213], v[16:19]
	v_mfma_f32_16x16x32_bf16 v[4:7], v[144:147], v[214:217], v[4:7]
	v_mfma_f32_16x16x32_bf16 v[4:7], v[148:151], v[218:221], v[4:7]
	v_mfma_f32_16x16x32_bf16 v[0:3], v[152:155], v[214:217], v[0:3]
	v_mfma_f32_16x16x32_bf16 v[0:3], v[156:159], v[218:221], v[0:3]
	s_barrier
	s_setprio 0
	s_add_i32 s83, 0, 0x18000
	s_add_i32 s85, 0, 0x1c000
	v_add_u32_e32 v140, s83, v202
	v_add_u32_e32 v156, s85, v202
	ds_read_b128 v[112:115], v140
	ds_read_b128 v[116:119], v140 offset:1024
	ds_read_b128 v[136:139], v140 offset:2048
	ds_read_b128 v[140:143], v140 offset:3072
	ds_read_b128 v[144:147], v156
	ds_read_b128 v[148:151], v156 offset:1024
	ds_read_b128 v[152:155], v156 offset:2048
	ds_read_b128 v[156:159], v156 offset:3072
	s_add_u32 s20, s36, 0xb0000
	s_addc_u32 s21, s37, 0
	s_mov_b32 m0, s45
	v_lshl_add_u64 v[230:231], s[20:21], 0, v[182:183]
	ds_read_b128 v[160:163], v205 offset:32768
	ds_read_b128 v[164:167], v205 offset:33792
	ds_read_b128 v[168:171], v205 offset:34816
	ds_read_b128 v[172:175], v205 offset:35840
	ds_read_b128 v[206:209], v205 offset:36864
	ds_read_b128 v[210:213], v205 offset:37888
	ds_read_b128 v[214:217], v205 offset:38912
	ds_read_b128 v[218:221], v205 offset:39936
	global_load_lds_dwordx4 v[230:231], off
	v_lshl_add_u64 v[230:231], s[20:21], 0, v[178:179]
	s_mov_b32 m0, s46
	s_nop 0
	global_load_lds_dwordx4 v[230:231], off
	s_waitcnt vmcnt(8)
	s_waitcnt lgkmcnt(0)
	s_setprio 1
	s_barrier
	v_mfma_f32_16x16x32_bf16 v[132:135], v[112:115], v[160:163], v[132:135]
	v_mfma_f32_16x16x32_bf16 v[132:135], v[116:119], v[164:167], v[132:135]
	v_mfma_f32_16x16x32_bf16 v[128:131], v[136:139], v[160:163], v[128:131]
	v_mfma_f32_16x16x32_bf16 v[128:131], v[140:143], v[164:167], v[128:131]
	v_mfma_f32_16x16x32_bf16 v[108:111], v[112:115], v[168:171], v[108:111]
	v_mfma_f32_16x16x32_bf16 v[108:111], v[116:119], v[172:175], v[108:111]
	v_mfma_f32_16x16x32_bf16 v[104:107], v[136:139], v[168:171], v[104:107]
	v_mfma_f32_16x16x32_bf16 v[104:107], v[140:143], v[172:175], v[104:107]
	v_mfma_f32_16x16x32_bf16 v[92:95], v[112:115], v[206:209], v[92:95]
	v_mfma_f32_16x16x32_bf16 v[92:95], v[116:119], v[210:213], v[92:95]
	v_mfma_f32_16x16x32_bf16 v[88:91], v[136:139], v[206:209], v[88:91]
	v_mfma_f32_16x16x32_bf16 v[88:91], v[140:143], v[210:213], v[88:91]
	v_mfma_f32_16x16x32_bf16 v[76:79], v[112:115], v[214:217], v[76:79]
	v_mfma_f32_16x16x32_bf16 v[76:79], v[116:119], v[218:221], v[76:79]
	v_mfma_f32_16x16x32_bf16 v[72:75], v[136:139], v[214:217], v[72:75]
	v_mfma_f32_16x16x32_bf16 v[72:75], v[140:143], v[218:221], v[72:75]
	v_mfma_f32_16x16x32_bf16 v[124:127], v[144:147], v[160:163], v[124:127]
	v_mfma_f32_16x16x32_bf16 v[124:127], v[148:151], v[164:167], v[124:127]
	v_mfma_f32_16x16x32_bf16 v[120:123], v[152:155], v[160:163], v[120:123]
	v_mfma_f32_16x16x32_bf16 v[120:123], v[156:159], v[164:167], v[120:123]
	v_mfma_f32_16x16x32_bf16 v[100:103], v[144:147], v[168:171], v[100:103]
	v_mfma_f32_16x16x32_bf16 v[100:103], v[148:151], v[172:175], v[100:103]
	v_mfma_f32_16x16x32_bf16 v[96:99], v[152:155], v[168:171], v[96:99]
	v_mfma_f32_16x16x32_bf16 v[96:99], v[156:159], v[172:175], v[96:99]
	v_mfma_f32_16x16x32_bf16 v[84:87], v[144:147], v[206:209], v[84:87]
	v_mfma_f32_16x16x32_bf16 v[84:87], v[148:151], v[210:213], v[84:87]
	v_mfma_f32_16x16x32_bf16 v[80:83], v[152:155], v[206:209], v[80:83]
	v_mfma_f32_16x16x32_bf16 v[80:83], v[156:159], v[210:213], v[80:83]
	v_mfma_f32_16x16x32_bf16 v[68:71], v[144:147], v[214:217], v[68:71]
	v_mfma_f32_16x16x32_bf16 v[68:71], v[148:151], v[218:221], v[68:71]
	v_mfma_f32_16x16x32_bf16 v[64:67], v[152:155], v[214:217], v[64:67]
	v_mfma_f32_16x16x32_bf16 v[64:67], v[156:159], v[218:221], v[64:67]
	s_barrier
	s_setprio 0
	s_add_i32 s20, s83, s40
	v_lshl_add_u64 v[200:201], v[200:201], 0, s[14:15]
	s_mov_b32 m0, s20
	ds_read_b128 v[160:163], v205 offset:49152
	ds_read_b128 v[164:167], v205 offset:50176
	ds_read_b128 v[168:171], v205 offset:51200
	ds_read_b128 v[172:175], v205 offset:52224
	ds_read_b128 v[206:209], v205 offset:53248
	ds_read_b128 v[210:213], v205 offset:54272
	ds_read_b128 v[214:217], v205 offset:55296
	ds_read_b128 v[218:221], v205 offset:56320
	global_load_lds_dwordx4 v[200:201], off
	s_add_i32 m0, s20, 0x2000
	s_add_u32 s20, s26, 0xb0080
	v_lshl_add_u64 v[200:201], v[222:223], 0, s[14:15]
	s_addc_u32 s21, s27, 0
	s_add_i32 s26, s85, s40
	global_load_lds_dwordx4 v[200:201], off
	v_lshl_add_u64 v[200:201], s[20:21], 0, v[180:181]
	s_mov_b32 m0, s26
	s_nop 0
	global_load_lds_dwordx4 v[200:201], off
	v_lshl_add_u64 v[200:201], s[20:21], 0, v[176:177]
	s_add_i32 m0, s26, 0x2000
	s_nop 0
	global_load_lds_dwordx4 v[200:201], off
	v_lshl_add_u64 v[200:201], v[224:225], 0, s[14:15]
	s_mov_b32 m0, s52
	s_nop 0
	global_load_lds_dwordx4 v[200:201], off
	v_lshl_add_u64 v[200:201], v[226:227], 0, s[14:15]
	s_mov_b32 m0, s53
	s_nop 0
	global_load_lds_dwordx4 v[200:201], off
	s_waitcnt vmcnt(8)
	s_waitcnt lgkmcnt(0)
	s_setprio 1
	s_barrier
	v_mfma_f32_16x16x32_bf16 v[60:63], v[112:115], v[160:163], v[60:63]
	v_mfma_f32_16x16x32_bf16 v[60:63], v[116:119], v[164:167], v[60:63]
	v_mfma_f32_16x16x32_bf16 v[56:59], v[136:139], v[160:163], v[56:59]
	v_mfma_f32_16x16x32_bf16 v[56:59], v[140:143], v[164:167], v[56:59]
	v_mfma_f32_16x16x32_bf16 v[44:47], v[112:115], v[168:171], v[44:47]
	v_mfma_f32_16x16x32_bf16 v[44:47], v[116:119], v[172:175], v[44:47]
	v_mfma_f32_16x16x32_bf16 v[40:43], v[136:139], v[168:171], v[40:43]
	v_mfma_f32_16x16x32_bf16 v[40:43], v[140:143], v[172:175], v[40:43]
	v_mfma_f32_16x16x32_bf16 v[28:31], v[112:115], v[206:209], v[28:31]
	v_mfma_f32_16x16x32_bf16 v[28:31], v[116:119], v[210:213], v[28:31]
	v_mfma_f32_16x16x32_bf16 v[24:27], v[136:139], v[206:209], v[24:27]
	v_mfma_f32_16x16x32_bf16 v[24:27], v[140:143], v[210:213], v[24:27]
	v_mfma_f32_16x16x32_bf16 v[12:15], v[112:115], v[214:217], v[12:15]
	v_mfma_f32_16x16x32_bf16 v[12:15], v[116:119], v[218:221], v[12:15]
	v_mfma_f32_16x16x32_bf16 v[8:11], v[136:139], v[214:217], v[8:11]
	v_mfma_f32_16x16x32_bf16 v[8:11], v[140:143], v[218:221], v[8:11]
	v_mfma_f32_16x16x32_bf16 v[52:55], v[144:147], v[160:163], v[52:55]
	v_mfma_f32_16x16x32_bf16 v[52:55], v[148:151], v[164:167], v[52:55]
	v_mfma_f32_16x16x32_bf16 v[48:51], v[152:155], v[160:163], v[48:51]
	v_mfma_f32_16x16x32_bf16 v[48:51], v[156:159], v[164:167], v[48:51]
	v_mfma_f32_16x16x32_bf16 v[36:39], v[144:147], v[168:171], v[36:39]
	v_mfma_f32_16x16x32_bf16 v[36:39], v[148:151], v[172:175], v[36:39]
	v_mfma_f32_16x16x32_bf16 v[32:35], v[152:155], v[168:171], v[32:35]
	v_mfma_f32_16x16x32_bf16 v[32:35], v[156:159], v[172:175], v[32:35]
	v_mfma_f32_16x16x32_bf16 v[20:23], v[144:147], v[206:209], v[20:23]
	v_mfma_f32_16x16x32_bf16 v[20:23], v[148:151], v[210:213], v[20:23]
	v_mfma_f32_16x16x32_bf16 v[16:19], v[152:155], v[206:209], v[16:19]
	v_mfma_f32_16x16x32_bf16 v[16:19], v[156:159], v[210:213], v[16:19]
	v_mfma_f32_16x16x32_bf16 v[4:7], v[144:147], v[214:217], v[4:7]
	v_mfma_f32_16x16x32_bf16 v[4:7], v[148:151], v[218:221], v[4:7]
	v_mfma_f32_16x16x32_bf16 v[0:3], v[152:155], v[214:217], v[0:3]
	v_mfma_f32_16x16x32_bf16 v[0:3], v[156:159], v[218:221], v[0:3]
	s_barrier
	s_setprio 0
	s_add_i32 s82, s82, 2
	s_add_u32 s80, s80, 0x100
	s_addc_u32 s81, s81, 0
	s_cmp_gt_u32 s82, 41
	s_mov_b64 s[20:21], s[22:23]
	s_cbranch_scc0 .LBB0_836
	s_and_b64 vcc, exec, s[16:17]
	s_cbranch_vccz .LBB0_839
	s_barrier
